# strategy 4: one static s_setprio 1 for waves 4-7 at kernel entry, all per-segment flips deleted
# speedup vs baseline: 1.0021x; 1.0021x over previous
; #define LAS __attribute__((address_space(3)))
; #define WSP() ((unsigned char*)karg(168))
; #define OUTP() ((float*)karg(160))
; __device__ __forceinline__ unsigned xb_add(unsigned* p, unsigned v) { return __hip_atomic_fetch_add(p, v, __ATOMIC_RELAXED, __HIP_MEMORY_SCOPE_AGENT); }
; __device__ __forceinline__ unsigned xb_xcc_id() { return (unsigned)__builtin_amdgcn_s_getreg((3 << 11) | 20) & 0xFu; }
; __global__ void __launch_bounds__(NWAVES * 64, 2) fwd_megakernel(Args A) {
;     extern __shared__ __attribute__((aligned(16))) unsigned char lds[];
;     cg::grid_group grid = cg::this_grid();
;     const int G = gridDim.x, bx = blockIdx.x;
;     LAS unsigned char* ldsg = (LAS unsigned char*)lds;
;     unsigned char* ws = WSP(); unsigned char* R = ws + WS_R;
;     bf16* XB = (bf16*)(ws + WS_XB); float* SSQ = (float*)(ws + WS_SSQ); float* X = OUTP();
;     bf16* H = (bf16*)(R + R_H); bf16* MIX = (bf16*)(R + R_MIX);
;     if (threadIdx.x < 16) ((volatile LAS unsigned*)(ldsg + (LDS_BYTES - 128)))[threadIdx.x] = 0u;
;     __syncthreads();
;     volatile LAS unsigned* ldsw = (volatile LAS unsigned*)(ldsg + (LDS_BYTES - 128));
;     XcdBarrier xbar; xbar.bar = (unsigned*)ws; xbar.x = xb_xcc_id(); xbar.st = ldsw;
;     if (threadIdx.x == 0) ldsw[4] = xb_add(&xbar.bar[XB_XCNT(xbar.x)], 1u);
_Z14fwd_megakernel4Args:
	v_readfirstlane_b32 s99, v0
	s_nop 3
	s_and_b32 s99, s99, 0x3ff
	s_lshr_b32 s99, s99, 6
	s_cmp_ge_u32 s99, 4
	s_cbranch_scc0 .Lprio_done
	s_setprio 1
.Lprio_done:
	s_add_u32 s6, s0, 0xb0
	s_movk_i32 s3, 0xa8
	s_addc_u32 s7, s1, 0
	s_load_dwordx2 s[80:81], s[0:1], 0xb0
	s_load_dword s28, s[0:1], 0xb8
	s_ashr_i32 s5, s3, 31
	s_add_u32 s4, s0, s3
	s_addc_u32 s5, s1, s5
	s_movk_i32 s3, 0xa0
	s_load_dwordx2 s[76:77], s[4:5], 0x0
	s_ashr_i32 s5, s3, 31
	s_add_u32 s4, s0, s3
	s_addc_u32 s5, s1, s5
	s_load_dwordx2 s[4:5], s[4:5], 0x0
	v_and_b32_e32 v165, 0x3ff, v0
	v_cmp_gt_u32_e32 vcc, 16, v165
	s_waitcnt lgkmcnt(0)
	v_writelane_b32 v246, s4, 0
	s_nop 1
	v_writelane_b32 v246, s5, 1
	s_and_saveexec_b64 s[4:5], vcc
	v_lshl_add_u32 v1, v165, 2, 0
	v_add_u32_e32 v1, 0x23f80, v1
	v_mov_b32_e32 v2, 0
	ds_write_b32 v1, v2
	s_or_b64 exec, exec, s[4:5]
	s_waitcnt lgkmcnt(0)
	s_barrier
	s_getreg_b32 s3, hwreg(HW_REG_XCC_ID, 0, 4)
	s_and_b32 s3, s3, 15
	v_cmp_eq_u32_e64 s[72:73], 0, v165
	s_and_saveexec_b64 s[4:5], s[72:73]
	s_cbranch_execz .LBB0_6
	s_mov_b64 s[10:11], exec
	v_mbcnt_lo_u32_b32 v1, s10, 0
	v_mbcnt_hi_u32_b32 v1, s11, v1
	v_cmp_eq_u32_e32 vcc, 0, v1
	s_and_saveexec_b64 s[8:9], vcc
	s_cbranch_execz .LBB0_5
	s_lshl_b32 s12, s3, 8
	s_bcnt1_i32_b64 s10, s[10:11]
	v_mov_b32_e32 v2, s12
	v_mov_b32_e32 v3, s10
	global_atomic_add v2, v2, v3, s[76:77] offset:1024 sc0

; #define PG8_STAGE(bufoff, gbase, voff) do { _Pragma("unroll") for (int _i = 0; _i < 2; ++_i) \
;         __builtin_amdgcn_global_load_lds((const unsigned*)((const char*)(gbase) + (voff)[_i]), (PG8_LAS unsigned*)(lds + (bufoff) + ldsw + _i * 8192), 16, 0, 0); } while (0)
; #define PG8_WAIT_V(n) asm volatile("s_waitcnt vmcnt(" #n ")" ::: "memory")
; #define PG8_WAIT_L(n) asm volatile("s_waitcnt lgkmcnt(" #n ")" ::: "memory")
; template <class Epi, class Sched, bool ALIGN_EPI = false, bool SP2 = false>
; __device__ __forceinline__ void gemm_phase(PG8_LAS unsigned char* lds, const Gemm g, const Sched& S, const Epi& E) {
;     ...
;         for (int t = 0; t < nt; t += 2) {
;             const bool last = (t == nt - 2);
;             const char* a1 = cA + (size_t)(t + 1) * kstep;
;             const char* a2 = last ? nA : cA + (size_t)(t + 2) * kstep; const char* b2 = last ? nB : cB + (size_t)(t + 2) * kstep;
;             const char* a3 = a2 + kstep; const char* b3 = b2 + kstep;
;             if (last && has_next) S.a_ready(nxt);
;             if constexpr (SP2) {
;             PG8_LDB(B0, 0, 0); PG8_LDB(B1, 0, 1); PG8_SCHED; PG8_LDA(At, 0, 0); PG8_STAGE(PG8_SA(1, 1), a1 + hstep, voffA);
;             PG8_WAIT_V(8); PG8_WAIT_L(0); PG8_BAR; __builtin_amdgcn_s_setprio(1); PG8_MMA_NP(0, 0, At, B0); PG8_MMA_NP(0, 1, At, B1); __builtin_amdgcn_s_setprio(0); PG8_BAR; PG8_SCHED;
;             PG8_LDA(At, 0, 1); PG8_STAGE(PG8_SB(0, 0), b2, voffB); PG8_STAGE(PG8_SB(0, 1), b2 + hstep, voffB); PG8_STAGE(PG8_SA(0, 0), a2, voffA);
;             PG8_WAIT_V(8); PG8_WAIT_L(0); PG8_BAR; __builtin_amdgcn_s_setprio(1); PG8_MMA_NP(1, 0, At, B0); PG8_MMA_NP(1, 1, At, B1); __builtin_amdgcn_s_setprio(0); PG8_BAR; PG8_SCHED;
;             PG8_LDB(B0, 1, 0); PG8_LDB(B1, 1, 1); PG8_SCHED; PG8_LDA(At, 1, 0); PG8_STAGE(PG8_SA(0, 1), a2 + hstep, voffA);
;             PG8_WAIT_V(8); PG8_WAIT_L(0); PG8_BAR; __builtin_amdgcn_s_setprio(1); PG8_MMA_NP(0, 0, At, B0); PG8_MMA_NP(0, 1, At, B1); __builtin_amdgcn_s_setprio(0); PG8_BAR; PG8_SCHED;
;             PG8_LDA(At, 1, 1); PG8_STAGE(PG8_SB(1, 0), b3, voffB); PG8_STAGE(PG8_SB(1, 1), b3 + hstep, voffB); PG8_STAGE(PG8_SA(1, 0), a3, voffA);
;             PG8_WAIT_V(8); PG8_WAIT_L(0); PG8_BAR; __builtin_amdgcn_s_setprio(1); PG8_MMA_NP(1, 0, At, B0); PG8_MMA_NP(1, 1, At, B1); __builtin_amdgcn_s_setprio(0); PG8_BAR; PG8_SCHED;
.LBB0_165:
	s_ashr_i32 s47, s46, 31
	s_lshl_b64 s[14:15], s[46:47], 19
	s_add_u32 s50, s86, s14
	s_addc_u32 s51, s87, s15
	s_and_b64 s[14:15], s[40:41], exec
	s_cselect_b32 s47, s51, s3
	s_cselect_b32 s59, s50, s2
	s_ashr_i32 s45, s44, 31
	s_lshl_b64 s[14:15], s[44:45], 19
	v_readlane_b32 s22, v244, 18
	s_add_u32 s52, s22, s14
	v_readlane_b32 s14, v244, 19
	s_addc_u32 s53, s14, s15
	s_and_b64 s[14:15], s[40:41], exec
	s_cselect_b32 s45, s53, s13
	s_cselect_b32 s60, s52, s12
	s_add_u32 s2, s2, 0x40080
	s_addc_u32 s3, s3, 0
	s_add_u32 s61, s12, 0x100
	s_addc_u32 s62, s13, 0
	s_mov_b32 s63, -2
	s_add_u32 s12, s2, 0xfffc0080
	s_addc_u32 s13, s3, -1
	s_add_i32 s22, 0, 0x10000
	s_cmp_eq_u32 s63, 12
	s_cselect_b32 s15, s47, s13
	s_cselect_b32 s14, s59, s12
	s_cselect_b32 s13, s45, s62
	s_cselect_b32 s12, s60, s61
	s_add_i32 s23, 0, 0x14000
	v_add_u32_e32 v154, s22, v183
	v_add_u32_e32 v162, s23, v183
	ds_read_b128 v[130:133], v154
	ds_read_b128 v[146:149], v154 offset:1024
	ds_read_b128 v[150:153], v154 offset:2048
	ds_read_b128 v[154:157], v154 offset:3072
	ds_read_b128 v[158:161], v162
	ds_read_b128 v[178:181], v162 offset:1024
	ds_read_b128 v[186:189], v162 offset:2048
	ds_read_b128 v[202:205], v162 offset:3072
	v_lshl_add_u64 v[162:163], s[2:3], 0, v[142:143]
	s_add_i32 m0, s10, 0xc000
	ds_read_b128 v[206:209], v185
	ds_read_b128 v[210:213], v185 offset:1024
	ds_read_b128 v[214:217], v185 offset:2048
	ds_read_b128 v[218:221], v185 offset:3072
	ds_read_b128 v[222:225], v185 offset:4096
	ds_read_b128 v[226:229], v185 offset:5120
	ds_read_b128 v[230:233], v185 offset:6144
	ds_read_b128 v[234:237], v185 offset:7168
	global_load_lds_dwordx4 v[162:163], off
	v_lshl_add_u64 v[162:163], s[2:3], 0, v[144:145]
	s_add_i32 m0, s10, 0xe000
	s_nop 0
	global_load_lds_dwordx4 v[162:163], off
	s_waitcnt vmcnt(8)
	s_waitcnt lgkmcnt(0)
	s_barrier
	s_waitcnt lgkmcnt(0)
	v_mfma_f32_16x16x32_bf16 v[126:129], v[130:133], v[206:209], 0
	v_mfma_f32_16x16x32_bf16 v[118:121], v[150:153], v[206:209], 0
	v_mfma_f32_16x16x32_bf16 v[110:113], v[130:133], v[214:217], 0
	v_mfma_f32_16x16x32_bf16 v[102:105], v[150:153], v[214:217], 0
	v_mfma_f32_16x16x32_bf16 v[94:97], v[130:133], v[222:225], 0
	v_mfma_f32_16x16x32_bf16 v[86:89], v[150:153], v[222:225], 0
	v_mfma_f32_16x16x32_bf16 v[78:81], v[130:133], v[230:233], 0
	v_mfma_f32_16x16x32_bf16 v[70:73], v[150:153], v[230:233], 0
	v_mfma_f32_16x16x32_bf16 v[122:125], v[158:161], v[206:209], 0
	v_mfma_f32_16x16x32_bf16 v[114:117], v[186:189], v[206:209], 0
	v_mfma_f32_16x16x32_bf16 v[106:109], v[158:161], v[214:217], 0
	v_mfma_f32_16x16x32_bf16 v[98:101], v[186:189], v[214:217], 0
	v_mfma_f32_16x16x32_bf16 v[90:93], v[158:161], v[222:225], 0
	v_mfma_f32_16x16x32_bf16 v[82:85], v[186:189], v[222:225], 0
	v_mfma_f32_16x16x32_bf16 v[74:77], v[158:161], v[230:233], 0
	v_mfma_f32_16x16x32_bf16 v[66:69], v[186:189], v[230:233], 0
	v_mfma_f32_16x16x32_bf16 v[126:129], v[146:149], v[210:213], v[126:129]
	v_mfma_f32_16x16x32_bf16 v[118:121], v[154:157], v[210:213], v[118:121]
	v_mfma_f32_16x16x32_bf16 v[110:113], v[146:149], v[218:221], v[110:113]
	v_mfma_f32_16x16x32_bf16 v[102:105], v[154:157], v[218:221], v[102:105]
	v_mfma_f32_16x16x32_bf16 v[94:97], v[146:149], v[226:229], v[94:97]
	v_mfma_f32_16x16x32_bf16 v[86:89], v[154:157], v[226:229], v[86:89]
	v_mfma_f32_16x16x32_bf16 v[78:81], v[146:149], v[234:237], v[78:81]
	v_mfma_f32_16x16x32_bf16 v[70:73], v[154:157], v[234:237], v[70:73]
	v_mfma_f32_16x16x32_bf16 v[122:125], v[178:181], v[210:213], v[122:125]
	v_mfma_f32_16x16x32_bf16 v[114:117], v[202:205], v[210:213], v[114:117]
	v_mfma_f32_16x16x32_bf16 v[106:109], v[178:181], v[218:221], v[106:109]
	v_mfma_f32_16x16x32_bf16 v[98:101], v[202:205], v[218:221], v[98:101]
	v_mfma_f32_16x16x32_bf16 v[90:93], v[178:181], v[226:229], v[90:93]
	v_mfma_f32_16x16x32_bf16 v[82:85], v[202:205], v[226:229], v[82:85]
	v_mfma_f32_16x16x32_bf16 v[74:77], v[178:181], v[234:237], v[74:77]
	v_mfma_f32_16x16x32_bf16 v[66:69], v[202:205], v[234:237], v[66:69]
	s_barrier
	s_add_i32 s22, s22, s8
	v_lshl_add_u64 v[162:163], s[12:13], 0, v[0:1]
	s_mov_b32 m0, s22
	ds_read_b128 v[206:209], v185 offset:16384
	ds_read_b128 v[210:213], v185 offset:17408
	ds_read_b128 v[214:217], v185 offset:18432
	ds_read_b128 v[218:221], v185 offset:19456
	ds_read_b128 v[222:225], v185 offset:20480
	ds_read_b128 v[226:229], v185 offset:21504
	ds_read_b128 v[230:233], v185 offset:22528
	ds_read_b128 v[234:237], v185 offset:23552
	global_load_lds_dwordx4 v[162:163], off
	s_add_i32 m0, s22, 0x2000
	s_add_u32 s64, s12, 0x40000
	v_lshl_add_u64 v[190:191], s[12:13], 0, v[134:135]
	s_addc_u32 s65, s13, 0
	s_add_i32 s22, s23, s8
	global_load_lds_dwordx4 v[190:191], off
	v_lshl_add_u64 v[238:239], s[64:65], 0, v[0:1]
	s_mov_b32 m0, s22
	v_lshl_add_u64 v[240:241], s[14:15], 0, v[136:137]
	global_load_lds_dwordx4 v[238:239], off
	v_lshl_add_u64 v[238:239], s[64:65], 0, v[134:135]
	s_add_i32 m0, s22, 0x2000
	s_nop 0
	global_load_lds_dwordx4 v[238:239], off
	v_lshl_add_u64 v[238:239], s[14:15], 0, v[138:139]
	s_mov_b32 m0, s10
	s_nop 0
	global_load_lds_dwordx4 v[238:239], off
	s_mov_b32 m0, s29
	s_nop 0
	global_load_lds_dwordx4 v[240:241], off
	s_waitcnt vmcnt(8)
	s_waitcnt lgkmcnt(0)
	s_barrier
; #define PG8_STAGE(bufoff, gbase, voff) do { _Pragma("unroll") for (int _i = 0; _i < 2; ++_i) \
;         __builtin_amdgcn_global_load_lds((const unsigned*)((const char*)(gbase) + (voff)[_i]), (PG8_LAS unsigned*)(lds + (bufoff) + ldsw + _i * 8192), 16, 0, 0); } while (0)
; #define PG8_LDA(dst, b, h) do { _Pragma("unroll") for (int m = 0; m < 4; ++m) _Pragma("unroll") for (int k = 0; k < 2; ++k) dst[m][k] = *(const PG8_LAS bf16x8*)(lds + PG8_SA(b, h) + aoff + m * 2048 + k * 1024); } while (0)
; #define PG8_LDB(dst, b, h) do { _Pragma("unroll") for (int n = 0; n < 2; ++n) _Pragma("unroll") for (int k = 0; k < 2; ++k) dst[n][k] = *(const PG8_LAS bf16x8*)(lds + PG8_SB(b, h) + boff + n * 2048 + k * 1024); } while (0)
; #define PG8_MMA_NP(ai, bj, At, Bt) do { _Pragma("unroll") for (int m = 0; m < 4; ++m) _Pragma("unroll") for (int n = 0; n < 2; ++n) _Pragma("unroll") for (int k = 0; k < 2; ++k) \
;         acc[ai][bj][m][n] = __builtin_amdgcn_mfma_f32_16x16x32_bf16(Bt[n][k], At[m][k], acc[ai][bj][m][n], 0, 0, 0); } while (0)
; #define PG8_WAIT_V(n) asm volatile("s_waitcnt vmcnt(" #n ")" ::: "memory")
; #define PG8_WAIT_L(n) asm volatile("s_waitcnt lgkmcnt(" #n ")" ::: "memory")
; template <class Epi, class Sched, bool ALIGN_EPI = false, bool SP2 = false>
; __device__ __forceinline__ void gemm_phase(PG8_LAS unsigned char* lds, const Gemm g, const Sched& S, const Epi& E) {
;     ...
;             PG8_LDA(At, 0, 1); PG8_STAGE(PG8_SB(0, 0), b2, voffB); PG8_STAGE(PG8_SB(0, 1), b2 + hstep, voffB); PG8_STAGE(PG8_SA(0, 0), a2, voffA);
;             PG8_WAIT_V(8); PG8_WAIT_L(0); PG8_BAR; __builtin_amdgcn_s_setprio(1); PG8_MMA_NP(1, 0, At, B0); PG8_MMA_NP(1, 1, At, B1); __builtin_amdgcn_s_setprio(0); PG8_BAR; PG8_SCHED;
;             PG8_LDB(B0, 1, 0); PG8_LDB(B1, 1, 1); PG8_SCHED; PG8_LDA(At, 1, 0); PG8_STAGE(PG8_SA(0, 1), a2 + hstep, voffA);
;             PG8_WAIT_V(8); PG8_WAIT_L(0); PG8_BAR; __builtin_amdgcn_s_setprio(1); PG8_MMA_NP(0, 0, At, B0); PG8_MMA_NP(0, 1, At, B1); __builtin_amdgcn_s_setprio(0); PG8_BAR; PG8_SCHED;
;             PG8_LDA(At, 1, 1); PG8_STAGE(PG8_SB(1, 0), b3, voffB); PG8_STAGE(PG8_SB(1, 1), b3 + hstep, voffB); PG8_STAGE(PG8_SA(1, 0), a3, voffA);
;             PG8_WAIT_V(8); PG8_WAIT_L(0); PG8_BAR; __builtin_amdgcn_s_setprio(1); PG8_MMA_NP(1, 0, At, B0); PG8_MMA_NP(1, 1, At, B1); __builtin_amdgcn_s_setprio(0); PG8_BAR; PG8_SCHED;
	s_waitcnt lgkmcnt(0)
	v_mfma_f32_16x16x32_bf16 v[62:65], v[130:133], v[206:209], 0
	v_mfma_f32_16x16x32_bf16 v[54:57], v[150:153], v[206:209], 0
	v_mfma_f32_16x16x32_bf16 v[46:49], v[130:133], v[214:217], 0
	v_mfma_f32_16x16x32_bf16 v[38:41], v[150:153], v[214:217], 0
	v_mfma_f32_16x16x32_bf16 v[30:33], v[130:133], v[222:225], 0
	v_mfma_f32_16x16x32_bf16 v[22:25], v[150:153], v[222:225], 0
	v_mfma_f32_16x16x32_bf16 v[14:17], v[130:133], v[230:233], 0
	v_mfma_f32_16x16x32_bf16 v[6:9], v[150:153], v[230:233], 0
	v_mfma_f32_16x16x32_bf16 v[58:61], v[158:161], v[206:209], 0
	v_mfma_f32_16x16x32_bf16 v[50:53], v[186:189], v[206:209], 0
	v_mfma_f32_16x16x32_bf16 v[42:45], v[158:161], v[214:217], 0
	v_mfma_f32_16x16x32_bf16 v[34:37], v[186:189], v[214:217], 0
	v_mfma_f32_16x16x32_bf16 v[26:29], v[158:161], v[222:225], 0
	v_mfma_f32_16x16x32_bf16 v[18:21], v[186:189], v[222:225], 0
	v_mfma_f32_16x16x32_bf16 v[10:13], v[158:161], v[230:233], 0
	v_mfma_f32_16x16x32_bf16 v[2:5], v[186:189], v[230:233], 0
	v_mfma_f32_16x16x32_bf16 v[62:65], v[146:149], v[210:213], v[62:65]
	v_mfma_f32_16x16x32_bf16 v[54:57], v[154:157], v[210:213], v[54:57]
	v_mfma_f32_16x16x32_bf16 v[46:49], v[146:149], v[218:221], v[46:49]
	v_mfma_f32_16x16x32_bf16 v[38:41], v[154:157], v[218:221], v[38:41]
	v_mfma_f32_16x16x32_bf16 v[30:33], v[146:149], v[226:229], v[30:33]
	v_mfma_f32_16x16x32_bf16 v[22:25], v[154:157], v[226:229], v[22:25]
	v_mfma_f32_16x16x32_bf16 v[14:17], v[146:149], v[234:237], v[14:17]
	v_mfma_f32_16x16x32_bf16 v[6:9], v[154:157], v[234:237], v[6:9]
	v_mfma_f32_16x16x32_bf16 v[58:61], v[178:181], v[210:213], v[58:61]
	v_mfma_f32_16x16x32_bf16 v[50:53], v[202:205], v[210:213], v[50:53]
	v_mfma_f32_16x16x32_bf16 v[42:45], v[178:181], v[218:221], v[42:45]
	v_mfma_f32_16x16x32_bf16 v[34:37], v[202:205], v[218:221], v[34:37]
	v_mfma_f32_16x16x32_bf16 v[26:29], v[178:181], v[226:229], v[26:29]
	v_mfma_f32_16x16x32_bf16 v[18:21], v[202:205], v[226:229], v[18:21]
	v_mfma_f32_16x16x32_bf16 v[10:13], v[178:181], v[234:237], v[10:13]
	v_mfma_f32_16x16x32_bf16 v[2:5], v[202:205], v[234:237], v[2:5]
	s_barrier
	s_add_i32 s22, 0, 0x18000
	s_add_i32 s23, 0, 0x1c000
	v_add_u32_e32 v154, s22, v183
	v_add_u32_e32 v202, s23, v183
	ds_read_b128 v[130:133], v154
	ds_read_b128 v[146:149], v154 offset:1024
	ds_read_b128 v[150:153], v154 offset:2048
	ds_read_b128 v[154:157], v154 offset:3072
	ds_read_b128 v[158:161], v202
	ds_read_b128 v[178:181], v202 offset:1024
	ds_read_b128 v[186:189], v202 offset:2048
	ds_read_b128 v[202:205], v202 offset:3072
	s_add_u32 s14, s14, 0x40000
	s_addc_u32 s15, s15, 0
	s_mov_b32 m0, s30
	v_lshl_add_u64 v[242:243], s[14:15], 0, v[138:139]
	ds_read_b128 v[206:209], v185 offset:32768
	ds_read_b128 v[210:213], v185 offset:33792
	ds_read_b128 v[214:217], v185 offset:34816
	ds_read_b128 v[218:221], v185 offset:35840
	ds_read_b128 v[222:225], v185 offset:36864
	ds_read_b128 v[226:229], v185 offset:37888
	ds_read_b128 v[230:233], v185 offset:38912
	ds_read_b128 v[234:237], v185 offset:39936
	global_load_lds_dwordx4 v[242:243], off
	v_lshl_add_u64 v[242:243], s[14:15], 0, v[136:137]
	s_mov_b32 m0, s31
	s_nop 0
	global_load_lds_dwordx4 v[242:243], off
	s_waitcnt vmcnt(8)
	s_waitcnt lgkmcnt(0)
	s_barrier
	s_waitcnt lgkmcnt(0)
	v_mfma_f32_16x16x32_bf16 v[126:129], v[130:133], v[206:209], v[126:129]
	v_mfma_f32_16x16x32_bf16 v[118:121], v[150:153], v[206:209], v[118:121]
	v_mfma_f32_16x16x32_bf16 v[110:113], v[130:133], v[214:217], v[110:113]
	v_mfma_f32_16x16x32_bf16 v[102:105], v[150:153], v[214:217], v[102:105]
	v_mfma_f32_16x16x32_bf16 v[94:97], v[130:133], v[222:225], v[94:97]
	v_mfma_f32_16x16x32_bf16 v[86:89], v[150:153], v[222:225], v[86:89]
	v_mfma_f32_16x16x32_bf16 v[78:81], v[130:133], v[230:233], v[78:81]
	v_mfma_f32_16x16x32_bf16 v[70:73], v[150:153], v[230:233], v[70:73]
	v_mfma_f32_16x16x32_bf16 v[122:125], v[158:161], v[206:209], v[122:125]
	v_mfma_f32_16x16x32_bf16 v[114:117], v[186:189], v[206:209], v[114:117]
	v_mfma_f32_16x16x32_bf16 v[106:109], v[158:161], v[214:217], v[106:109]
	v_mfma_f32_16x16x32_bf16 v[98:101], v[186:189], v[214:217], v[98:101]
	v_mfma_f32_16x16x32_bf16 v[90:93], v[158:161], v[222:225], v[90:93]
	v_mfma_f32_16x16x32_bf16 v[82:85], v[186:189], v[222:225], v[82:85]
	v_mfma_f32_16x16x32_bf16 v[74:77], v[158:161], v[230:233], v[74:77]
	v_mfma_f32_16x16x32_bf16 v[66:69], v[186:189], v[230:233], v[66:69]
	v_mfma_f32_16x16x32_bf16 v[126:129], v[146:149], v[210:213], v[126:129]
	v_mfma_f32_16x16x32_bf16 v[118:121], v[154:157], v[210:213], v[118:121]
	v_mfma_f32_16x16x32_bf16 v[110:113], v[146:149], v[218:221], v[110:113]
	v_mfma_f32_16x16x32_bf16 v[102:105], v[154:157], v[218:221], v[102:105]
	v_mfma_f32_16x16x32_bf16 v[94:97], v[146:149], v[226:229], v[94:97]
	v_mfma_f32_16x16x32_bf16 v[86:89], v[154:157], v[226:229], v[86:89]
	v_mfma_f32_16x16x32_bf16 v[78:81], v[146:149], v[234:237], v[78:81]
	v_mfma_f32_16x16x32_bf16 v[70:73], v[154:157], v[234:237], v[70:73]
	v_mfma_f32_16x16x32_bf16 v[122:125], v[178:181], v[210:213], v[122:125]
	v_mfma_f32_16x16x32_bf16 v[114:117], v[202:205], v[210:213], v[114:117]
	v_mfma_f32_16x16x32_bf16 v[106:109], v[178:181], v[218:221], v[106:109]
	v_mfma_f32_16x16x32_bf16 v[98:101], v[202:205], v[218:221], v[98:101]
	v_mfma_f32_16x16x32_bf16 v[90:93], v[178:181], v[226:229], v[90:93]
	v_mfma_f32_16x16x32_bf16 v[82:85], v[202:205], v[226:229], v[82:85]
	v_mfma_f32_16x16x32_bf16 v[74:77], v[178:181], v[234:237], v[74:77]
	v_mfma_f32_16x16x32_bf16 v[66:69], v[202:205], v[234:237], v[66:69]
	s_barrier
; #define PG8_STAGE(bufoff, gbase, voff) do { _Pragma("unroll") for (int _i = 0; _i < 2; ++_i) \
;         __builtin_amdgcn_global_load_lds((const unsigned*)((const char*)(gbase) + (voff)[_i]), (PG8_LAS unsigned*)(lds + (bufoff) + ldsw + _i * 8192), 16, 0, 0); } while (0)
; #define PG8_LDA(dst, b, h) do { _Pragma("unroll") for (int m = 0; m < 4; ++m) _Pragma("unroll") for (int k = 0; k < 2; ++k) dst[m][k] = *(const PG8_LAS bf16x8*)(lds + PG8_SA(b, h) + aoff + m * 2048 + k * 1024); } while (0)
; #define PG8_LDB(dst, b, h) do { _Pragma("unroll") for (int n = 0; n < 2; ++n) _Pragma("unroll") for (int k = 0; k < 2; ++k) dst[n][k] = *(const PG8_LAS bf16x8*)(lds + PG8_SB(b, h) + boff + n * 2048 + k * 1024); } while (0)
; #define PG8_WAIT_V(n) asm volatile("s_waitcnt vmcnt(" #n ")" ::: "memory")
; #define PG8_WAIT_L(n) asm volatile("s_waitcnt lgkmcnt(" #n ")" ::: "memory")
; #define PG8_BAR __builtin_amdgcn_s_barrier()
; #define PG8_SCHED __builtin_amdgcn_sched_barrier(0)
; template <class Epi, class Sched, bool ALIGN_EPI = false, bool SP2 = false>
; __device__ __forceinline__ void gemm_phase(PG8_LAS unsigned char* lds, const Gemm g, const Sched& S, const Epi& E) {
;     ...
;         for (int t = 0; t < nt; t += 2) {
;             const bool last = (t == nt - 2);
;             const char* a1 = cA + (size_t)(t + 1) * kstep;
;             const char* a2 = last ? nA : cA + (size_t)(t + 2) * kstep; const char* b2 = last ? nB : cB + (size_t)(t + 2) * kstep;
;             const char* a3 = a2 + kstep; const char* b3 = b2 + kstep;
;             if (last && has_next) S.a_ready(nxt);
;             if constexpr (SP2) {
;             PG8_LDB(B0, 0, 0); PG8_LDB(B1, 0, 1); PG8_SCHED; PG8_LDA(At, 0, 0); PG8_STAGE(PG8_SA(1, 1), a1 + hstep, voffA);
;     ...
;             PG8_LDB(B0, 1, 0); PG8_LDB(B1, 1, 1); PG8_SCHED; PG8_LDA(At, 1, 0); PG8_STAGE(PG8_SA(0, 1), a2 + hstep, voffA);
;             PG8_WAIT_V(8); PG8_WAIT_L(0); PG8_BAR; __builtin_amdgcn_s_setprio(1); PG8_MMA_NP(0, 0, At, B0); PG8_MMA_NP(0, 1, At, B1); __builtin_amdgcn_s_setprio(0); PG8_BAR; PG8_SCHED;
;             PG8_LDA(At, 1, 1); PG8_STAGE(PG8_SB(1, 0), b3, voffB); PG8_STAGE(PG8_SB(1, 1), b3 + hstep, voffB); PG8_STAGE(PG8_SA(1, 0), a3, voffA);
;             PG8_WAIT_V(8); PG8_WAIT_L(0); PG8_BAR; __builtin_amdgcn_s_setprio(1); PG8_MMA_NP(1, 0, At, B0); PG8_MMA_NP(1, 1, At, B1); __builtin_amdgcn_s_setprio(0); PG8_BAR; PG8_SCHED;
	s_add_i32 s14, s22, s8
	v_lshl_add_u64 v[162:163], v[162:163], 0, s[20:21]
	s_mov_b32 m0, s14
	ds_read_b128 v[206:209], v185 offset:49152
	ds_read_b128 v[210:213], v185 offset:50176
	ds_read_b128 v[214:217], v185 offset:51200
	ds_read_b128 v[218:221], v185 offset:52224
	ds_read_b128 v[222:225], v185 offset:53248
	ds_read_b128 v[226:229], v185 offset:54272
	ds_read_b128 v[230:233], v185 offset:55296
	ds_read_b128 v[234:237], v185 offset:56320
	global_load_lds_dwordx4 v[162:163], off
	s_add_i32 m0, s14, 0x2000
	s_add_u32 s12, s12, 0x40080
	v_lshl_add_u64 v[162:163], v[190:191], 0, s[20:21]
	s_addc_u32 s13, s13, 0
	s_add_i32 s14, s23, s8
	global_load_lds_dwordx4 v[162:163], off
	v_lshl_add_u64 v[162:163], s[12:13], 0, v[0:1]
	s_mov_b32 m0, s14
	s_nop 0
	global_load_lds_dwordx4 v[162:163], off
	v_lshl_add_u64 v[162:163], s[12:13], 0, v[134:135]
	s_add_i32 m0, s14, 0x2000
	s_nop 0
	global_load_lds_dwordx4 v[162:163], off
	v_lshl_add_u64 v[162:163], v[238:239], 0, s[20:21]
	s_mov_b32 m0, s54
	s_nop 0
	global_load_lds_dwordx4 v[162:163], off
	v_lshl_add_u64 v[162:163], v[240:241], 0, s[20:21]
	s_mov_b32 m0, s55
	s_nop 0
	global_load_lds_dwordx4 v[162:163], off
	s_waitcnt vmcnt(8)
	s_waitcnt lgkmcnt(0)
	s_barrier
	s_waitcnt lgkmcnt(0)
	v_mfma_f32_16x16x32_bf16 v[62:65], v[130:133], v[206:209], v[62:65]
	v_mfma_f32_16x16x32_bf16 v[54:57], v[150:153], v[206:209], v[54:57]
	v_mfma_f32_16x16x32_bf16 v[46:49], v[130:133], v[214:217], v[46:49]
	v_mfma_f32_16x16x32_bf16 v[38:41], v[150:153], v[214:217], v[38:41]
	v_mfma_f32_16x16x32_bf16 v[30:33], v[130:133], v[222:225], v[30:33]
	v_mfma_f32_16x16x32_bf16 v[22:25], v[150:153], v[222:225], v[22:25]
	v_mfma_f32_16x16x32_bf16 v[14:17], v[130:133], v[230:233], v[14:17]
	v_mfma_f32_16x16x32_bf16 v[6:9], v[150:153], v[230:233], v[6:9]
	v_mfma_f32_16x16x32_bf16 v[58:61], v[158:161], v[206:209], v[58:61]
	v_mfma_f32_16x16x32_bf16 v[50:53], v[186:189], v[206:209], v[50:53]
	v_mfma_f32_16x16x32_bf16 v[42:45], v[158:161], v[214:217], v[42:45]
	v_mfma_f32_16x16x32_bf16 v[34:37], v[186:189], v[214:217], v[34:37]
	v_mfma_f32_16x16x32_bf16 v[26:29], v[158:161], v[222:225], v[26:29]
	v_mfma_f32_16x16x32_bf16 v[18:21], v[186:189], v[222:225], v[18:21]
	v_mfma_f32_16x16x32_bf16 v[10:13], v[158:161], v[230:233], v[10:13]
	v_mfma_f32_16x16x32_bf16 v[2:5], v[186:189], v[230:233], v[2:5]
	v_mfma_f32_16x16x32_bf16 v[62:65], v[146:149], v[210:213], v[62:65]
	v_mfma_f32_16x16x32_bf16 v[54:57], v[154:157], v[210:213], v[54:57]
	v_mfma_f32_16x16x32_bf16 v[46:49], v[146:149], v[218:221], v[46:49]
	v_mfma_f32_16x16x32_bf16 v[38:41], v[154:157], v[218:221], v[38:41]
	v_mfma_f32_16x16x32_bf16 v[30:33], v[146:149], v[226:229], v[30:33]
	v_mfma_f32_16x16x32_bf16 v[22:25], v[154:157], v[226:229], v[22:25]
	v_mfma_f32_16x16x32_bf16 v[14:17], v[146:149], v[234:237], v[14:17]
	v_mfma_f32_16x16x32_bf16 v[6:9], v[154:157], v[234:237], v[6:9]
	v_mfma_f32_16x16x32_bf16 v[58:61], v[178:181], v[210:213], v[58:61]
	v_mfma_f32_16x16x32_bf16 v[50:53], v[202:205], v[210:213], v[50:53]
	v_mfma_f32_16x16x32_bf16 v[42:45], v[178:181], v[218:221], v[42:45]
	v_mfma_f32_16x16x32_bf16 v[34:37], v[202:205], v[218:221], v[34:37]
	v_mfma_f32_16x16x32_bf16 v[26:29], v[178:181], v[226:229], v[26:29]
	v_mfma_f32_16x16x32_bf16 v[18:21], v[202:205], v[226:229], v[18:21]
	v_mfma_f32_16x16x32_bf16 v[10:13], v[178:181], v[234:237], v[10:13]
	v_mfma_f32_16x16x32_bf16 v[2:5], v[202:205], v[234:237], v[2:5]
	s_barrier
	s_add_i32 s63, s63, 2
	s_add_u32 s2, s2, 0x100
	s_addc_u32 s3, s3, 0
	s_add_u32 s61, s61, 0x100
	s_addc_u32 s62, s62, 0
	s_cmp_gt_u32 s63, 13
	s_cbranch_scc0 .LBB0_166
	s_branch .Lkexit_0
.LBB0_166:
	s_add_u32 s12, s2, 0xfffc0080
	s_addc_u32 s13, s3, -1
	s_add_i32 s22, 0, 0x10000
	s_cmp_eq_u32 s63, 12
	s_cselect_b32 s15, s47, s13
	s_cselect_b32 s14, s59, s12
	s_cselect_b32 s13, s45, s62
	s_cselect_b32 s12, s60, s61
	s_add_i32 s23, 0, 0x14000
	v_add_u32_e32 v154, s22, v183
	v_add_u32_e32 v162, s23, v183
	ds_read_b128 v[130:133], v154
	ds_read_b128 v[146:149], v154 offset:1024
	ds_read_b128 v[150:153], v154 offset:2048
	ds_read_b128 v[154:157], v154 offset:3072
	ds_read_b128 v[158:161], v162
	ds_read_b128 v[178:181], v162 offset:1024
	ds_read_b128 v[186:189], v162 offset:2048
	ds_read_b128 v[202:205], v162 offset:3072
	v_lshl_add_u64 v[162:163], s[2:3], 0, v[142:143]
	s_add_i32 m0, s10, 0xc000
	ds_read_b128 v[206:209], v185
	ds_read_b128 v[210:213], v185 offset:1024
	ds_read_b128 v[214:217], v185 offset:2048
	ds_read_b128 v[218:221], v185 offset:3072
	ds_read_b128 v[222:225], v185 offset:4096
	ds_read_b128 v[226:229], v185 offset:5120
	ds_read_b128 v[230:233], v185 offset:6144
	ds_read_b128 v[234:237], v185 offset:7168
	global_load_lds_dwordx4 v[162:163], off
	v_lshl_add_u64 v[162:163], s[2:3], 0, v[144:145]
	s_add_i32 m0, s10, 0xe000
	s_nop 0
	global_load_lds_dwordx4 v[162:163], off
	s_waitcnt vmcnt(8)
	s_waitcnt lgkmcnt(0)
	s_barrier
; #define PG8_STAGE(bufoff, gbase, voff) do { _Pragma("unroll") for (int _i = 0; _i < 2; ++_i) \
;         __builtin_amdgcn_global_load_lds((const unsigned*)((const char*)(gbase) + (voff)[_i]), (PG8_LAS unsigned*)(lds + (bufoff) + ldsw + _i * 8192), 16, 0, 0); } while (0)
; #define PG8_LDA(dst, b, h) do { _Pragma("unroll") for (int m = 0; m < 4; ++m) _Pragma("unroll") for (int k = 0; k < 2; ++k) dst[m][k] = *(const PG8_LAS bf16x8*)(lds + PG8_SA(b, h) + aoff + m * 2048 + k * 1024); } while (0)
; #define PG8_LDB(dst, b, h) do { _Pragma("unroll") for (int n = 0; n < 2; ++n) _Pragma("unroll") for (int k = 0; k < 2; ++k) dst[n][k] = *(const PG8_LAS bf16x8*)(lds + PG8_SB(b, h) + boff + n * 2048 + k * 1024); } while (0)
; #define PG8_MMA_NP(ai, bj, At, Bt) do { _Pragma("unroll") for (int m = 0; m < 4; ++m) _Pragma("unroll") for (int n = 0; n < 2; ++n) _Pragma("unroll") for (int k = 0; k < 2; ++k) \
;         acc[ai][bj][m][n] = __builtin_amdgcn_mfma_f32_16x16x32_bf16(Bt[n][k], At[m][k], acc[ai][bj][m][n], 0, 0, 0); } while (0)
; #define PG8_WAIT_V(n) asm volatile("s_waitcnt vmcnt(" #n ")" ::: "memory")
; #define PG8_WAIT_L(n) asm volatile("s_waitcnt lgkmcnt(" #n ")" ::: "memory")
; #define PG8_BAR __builtin_amdgcn_s_barrier()
; #define PG8_SCHED __builtin_amdgcn_sched_barrier(0)
; template <class Epi, class Sched, bool ALIGN_EPI = false, bool SP2 = false>
; __device__ __forceinline__ void gemm_phase(PG8_LAS unsigned char* lds, const Gemm g, const Sched& S, const Epi& E) {
;     ...
;             PG8_LDB(B0, 0, 0); PG8_LDB(B1, 0, 1); PG8_SCHED; PG8_LDA(At, 0, 0); PG8_STAGE(PG8_SA(1, 1), a1 + hstep, voffA);
;             PG8_WAIT_V(8); PG8_WAIT_L(0); PG8_BAR; __builtin_amdgcn_s_setprio(1); PG8_MMA_NP(0, 0, At, B0); PG8_MMA_NP(0, 1, At, B1); __builtin_amdgcn_s_setprio(0); PG8_BAR; PG8_SCHED;
;             PG8_LDA(At, 0, 1); PG8_STAGE(PG8_SB(0, 0), b2, voffB); PG8_STAGE(PG8_SB(0, 1), b2 + hstep, voffB); PG8_STAGE(PG8_SA(0, 0), a2, voffA);
;             PG8_WAIT_V(8); PG8_WAIT_L(0); PG8_BAR; __builtin_amdgcn_s_setprio(1); PG8_MMA_NP(1, 0, At, B0); PG8_MMA_NP(1, 1, At, B1); __builtin_amdgcn_s_setprio(0); PG8_BAR; PG8_SCHED;
	s_waitcnt lgkmcnt(0)
	v_mfma_f32_16x16x32_bf16 v[126:129], v[130:133], v[206:209], v[126:129]
	v_mfma_f32_16x16x32_bf16 v[118:121], v[150:153], v[206:209], v[118:121]
	v_mfma_f32_16x16x32_bf16 v[110:113], v[130:133], v[214:217], v[110:113]
	v_mfma_f32_16x16x32_bf16 v[102:105], v[150:153], v[214:217], v[102:105]
	v_mfma_f32_16x16x32_bf16 v[94:97], v[130:133], v[222:225], v[94:97]
	v_mfma_f32_16x16x32_bf16 v[86:89], v[150:153], v[222:225], v[86:89]
	v_mfma_f32_16x16x32_bf16 v[78:81], v[130:133], v[230:233], v[78:81]
	v_mfma_f32_16x16x32_bf16 v[70:73], v[150:153], v[230:233], v[70:73]
	v_mfma_f32_16x16x32_bf16 v[122:125], v[158:161], v[206:209], v[122:125]
	v_mfma_f32_16x16x32_bf16 v[114:117], v[186:189], v[206:209], v[114:117]
	v_mfma_f32_16x16x32_bf16 v[106:109], v[158:161], v[214:217], v[106:109]
	v_mfma_f32_16x16x32_bf16 v[98:101], v[186:189], v[214:217], v[98:101]
	v_mfma_f32_16x16x32_bf16 v[90:93], v[158:161], v[222:225], v[90:93]
	v_mfma_f32_16x16x32_bf16 v[82:85], v[186:189], v[222:225], v[82:85]
	v_mfma_f32_16x16x32_bf16 v[74:77], v[158:161], v[230:233], v[74:77]
	v_mfma_f32_16x16x32_bf16 v[66:69], v[186:189], v[230:233], v[66:69]
	v_mfma_f32_16x16x32_bf16 v[126:129], v[146:149], v[210:213], v[126:129]
	v_mfma_f32_16x16x32_bf16 v[118:121], v[154:157], v[210:213], v[118:121]
	v_mfma_f32_16x16x32_bf16 v[110:113], v[146:149], v[218:221], v[110:113]
	v_mfma_f32_16x16x32_bf16 v[102:105], v[154:157], v[218:221], v[102:105]
	v_mfma_f32_16x16x32_bf16 v[94:97], v[146:149], v[226:229], v[94:97]
	v_mfma_f32_16x16x32_bf16 v[86:89], v[154:157], v[226:229], v[86:89]
	v_mfma_f32_16x16x32_bf16 v[78:81], v[146:149], v[234:237], v[78:81]
	v_mfma_f32_16x16x32_bf16 v[70:73], v[154:157], v[234:237], v[70:73]
	v_mfma_f32_16x16x32_bf16 v[122:125], v[178:181], v[210:213], v[122:125]
	v_mfma_f32_16x16x32_bf16 v[114:117], v[202:205], v[210:213], v[114:117]
	v_mfma_f32_16x16x32_bf16 v[106:109], v[178:181], v[218:221], v[106:109]
	v_mfma_f32_16x16x32_bf16 v[98:101], v[202:205], v[218:221], v[98:101]
	v_mfma_f32_16x16x32_bf16 v[90:93], v[178:181], v[226:229], v[90:93]
	v_mfma_f32_16x16x32_bf16 v[82:85], v[202:205], v[226:229], v[82:85]
	v_mfma_f32_16x16x32_bf16 v[74:77], v[178:181], v[234:237], v[74:77]
	v_mfma_f32_16x16x32_bf16 v[66:69], v[202:205], v[234:237], v[66:69]
	s_barrier
	s_add_i32 s22, s22, s8
	v_lshl_add_u64 v[162:163], s[12:13], 0, v[0:1]
	s_mov_b32 m0, s22
	ds_read_b128 v[206:209], v185 offset:16384
	ds_read_b128 v[210:213], v185 offset:17408
	ds_read_b128 v[214:217], v185 offset:18432
	ds_read_b128 v[218:221], v185 offset:19456
	ds_read_b128 v[222:225], v185 offset:20480
	ds_read_b128 v[226:229], v185 offset:21504
	ds_read_b128 v[230:233], v185 offset:22528
	ds_read_b128 v[234:237], v185 offset:23552
	global_load_lds_dwordx4 v[162:163], off
	s_add_i32 m0, s22, 0x2000
	s_add_u32 s64, s12, 0x40000
	v_lshl_add_u64 v[190:191], s[12:13], 0, v[134:135]
	s_addc_u32 s65, s13, 0
	s_add_i32 s22, s23, s8
	global_load_lds_dwordx4 v[190:191], off
	v_lshl_add_u64 v[238:239], s[64:65], 0, v[0:1]
	s_mov_b32 m0, s22
	v_lshl_add_u64 v[240:241], s[14:15], 0, v[136:137]
	global_load_lds_dwordx4 v[238:239], off
	v_lshl_add_u64 v[238:239], s[64:65], 0, v[134:135]
	s_add_i32 m0, s22, 0x2000
	s_nop 0
	global_load_lds_dwordx4 v[238:239], off
	v_lshl_add_u64 v[238:239], s[14:15], 0, v[138:139]
	s_mov_b32 m0, s10
	s_nop 0
	global_load_lds_dwordx4 v[238:239], off
	s_mov_b32 m0, s29
	s_nop 0
	global_load_lds_dwordx4 v[240:241], off
	s_waitcnt vmcnt(8)
	s_waitcnt lgkmcnt(0)
	s_barrier
	s_waitcnt lgkmcnt(0)
	v_mfma_f32_16x16x32_bf16 v[62:65], v[130:133], v[206:209], v[62:65]
	v_mfma_f32_16x16x32_bf16 v[54:57], v[150:153], v[206:209], v[54:57]
	v_mfma_f32_16x16x32_bf16 v[46:49], v[130:133], v[214:217], v[46:49]
	v_mfma_f32_16x16x32_bf16 v[38:41], v[150:153], v[214:217], v[38:41]
	v_mfma_f32_16x16x32_bf16 v[30:33], v[130:133], v[222:225], v[30:33]
	v_mfma_f32_16x16x32_bf16 v[22:25], v[150:153], v[222:225], v[22:25]
	v_mfma_f32_16x16x32_bf16 v[14:17], v[130:133], v[230:233], v[14:17]
	v_mfma_f32_16x16x32_bf16 v[6:9], v[150:153], v[230:233], v[6:9]
	v_mfma_f32_16x16x32_bf16 v[58:61], v[158:161], v[206:209], v[58:61]
	v_mfma_f32_16x16x32_bf16 v[50:53], v[186:189], v[206:209], v[50:53]
	v_mfma_f32_16x16x32_bf16 v[42:45], v[158:161], v[214:217], v[42:45]
	v_mfma_f32_16x16x32_bf16 v[34:37], v[186:189], v[214:217], v[34:37]
	v_mfma_f32_16x16x32_bf16 v[26:29], v[158:161], v[222:225], v[26:29]
	v_mfma_f32_16x16x32_bf16 v[18:21], v[186:189], v[222:225], v[18:21]
	v_mfma_f32_16x16x32_bf16 v[10:13], v[158:161], v[230:233], v[10:13]
	v_mfma_f32_16x16x32_bf16 v[2:5], v[186:189], v[230:233], v[2:5]
	v_mfma_f32_16x16x32_bf16 v[62:65], v[146:149], v[210:213], v[62:65]
	v_mfma_f32_16x16x32_bf16 v[54:57], v[154:157], v[210:213], v[54:57]
	v_mfma_f32_16x16x32_bf16 v[46:49], v[146:149], v[218:221], v[46:49]
	v_mfma_f32_16x16x32_bf16 v[38:41], v[154:157], v[218:221], v[38:41]
	v_mfma_f32_16x16x32_bf16 v[30:33], v[146:149], v[226:229], v[30:33]
	v_mfma_f32_16x16x32_bf16 v[22:25], v[154:157], v[226:229], v[22:25]
	v_mfma_f32_16x16x32_bf16 v[14:17], v[146:149], v[234:237], v[14:17]
	v_mfma_f32_16x16x32_bf16 v[6:9], v[154:157], v[234:237], v[6:9]
	v_mfma_f32_16x16x32_bf16 v[58:61], v[178:181], v[210:213], v[58:61]
	v_mfma_f32_16x16x32_bf16 v[50:53], v[202:205], v[210:213], v[50:53]
	v_mfma_f32_16x16x32_bf16 v[42:45], v[178:181], v[218:221], v[42:45]
	v_mfma_f32_16x16x32_bf16 v[34:37], v[202:205], v[218:221], v[34:37]
	v_mfma_f32_16x16x32_bf16 v[26:29], v[178:181], v[226:229], v[26:29]
	v_mfma_f32_16x16x32_bf16 v[18:21], v[202:205], v[226:229], v[18:21]
	v_mfma_f32_16x16x32_bf16 v[10:13], v[178:181], v[234:237], v[10:13]
	v_mfma_f32_16x16x32_bf16 v[2:5], v[202:205], v[234:237], v[2:5]
	s_barrier
; #define PG8_STAGE(bufoff, gbase, voff) do { _Pragma("unroll") for (int _i = 0; _i < 2; ++_i) \
;         __builtin_amdgcn_global_load_lds((const unsigned*)((const char*)(gbase) + (voff)[_i]), (PG8_LAS unsigned*)(lds + (bufoff) + ldsw + _i * 8192), 16, 0, 0); } while (0)
; #define PG8_LDA(dst, b, h) do { _Pragma("unroll") for (int m = 0; m < 4; ++m) _Pragma("unroll") for (int k = 0; k < 2; ++k) dst[m][k] = *(const PG8_LAS bf16x8*)(lds + PG8_SA(b, h) + aoff + m * 2048 + k * 1024); } while (0)
; #define PG8_LDB(dst, b, h) do { _Pragma("unroll") for (int n = 0; n < 2; ++n) _Pragma("unroll") for (int k = 0; k < 2; ++k) dst[n][k] = *(const PG8_LAS bf16x8*)(lds + PG8_SB(b, h) + boff + n * 2048 + k * 1024); } while (0)
; #define PG8_MMA_NP(ai, bj, At, Bt) do { _Pragma("unroll") for (int m = 0; m < 4; ++m) _Pragma("unroll") for (int n = 0; n < 2; ++n) _Pragma("unroll") for (int k = 0; k < 2; ++k) \
;         acc[ai][bj][m][n] = __builtin_amdgcn_mfma_f32_16x16x32_bf16(Bt[n][k], At[m][k], acc[ai][bj][m][n], 0, 0, 0); } while (0)
; #define PG8_WAIT_V(n) asm volatile("s_waitcnt vmcnt(" #n ")" ::: "memory")
; #define PG8_WAIT_L(n) asm volatile("s_waitcnt lgkmcnt(" #n ")" ::: "memory")
; #define PG8_BAR __builtin_amdgcn_s_barrier()
; #define PG8_SCHED __builtin_amdgcn_sched_barrier(0)
; template <class Epi, class Sched, bool ALIGN_EPI = false, bool SP2 = false>
; __device__ __forceinline__ void gemm_phase(PG8_LAS unsigned char* lds, const Gemm g, const Sched& S, const Epi& E) {
;     ...
;             PG8_LDB(B0, 1, 0); PG8_LDB(B1, 1, 1); PG8_SCHED; PG8_LDA(At, 1, 0); PG8_STAGE(PG8_SA(0, 1), a2 + hstep, voffA);
;             PG8_WAIT_V(8); PG8_WAIT_L(0); PG8_BAR; __builtin_amdgcn_s_setprio(1); PG8_MMA_NP(0, 0, At, B0); PG8_MMA_NP(0, 1, At, B1); __builtin_amdgcn_s_setprio(0); PG8_BAR; PG8_SCHED;
;             PG8_LDA(At, 1, 1); PG8_STAGE(PG8_SB(1, 0), b3, voffB); PG8_STAGE(PG8_SB(1, 1), b3 + hstep, voffB); PG8_STAGE(PG8_SA(1, 0), a3, voffA);
;             PG8_WAIT_V(8); PG8_WAIT_L(0); PG8_BAR; __builtin_amdgcn_s_setprio(1); PG8_MMA_NP(1, 0, At, B0); PG8_MMA_NP(1, 1, At, B1); __builtin_amdgcn_s_setprio(0); PG8_BAR; PG8_SCHED;
	s_add_i32 s22, 0, 0x18000
	s_add_i32 s23, 0, 0x1c000
	v_add_u32_e32 v154, s22, v183
	v_add_u32_e32 v202, s23, v183
	ds_read_b128 v[130:133], v154
	ds_read_b128 v[146:149], v154 offset:1024
	ds_read_b128 v[150:153], v154 offset:2048
	ds_read_b128 v[154:157], v154 offset:3072
	ds_read_b128 v[158:161], v202
	ds_read_b128 v[178:181], v202 offset:1024
	ds_read_b128 v[186:189], v202 offset:2048
	ds_read_b128 v[202:205], v202 offset:3072
	s_add_u32 s14, s14, 0x40000
	s_addc_u32 s15, s15, 0
	s_mov_b32 m0, s30
	v_lshl_add_u64 v[242:243], s[14:15], 0, v[138:139]
	ds_read_b128 v[206:209], v185 offset:32768
	ds_read_b128 v[210:213], v185 offset:33792
	ds_read_b128 v[214:217], v185 offset:34816
	ds_read_b128 v[218:221], v185 offset:35840
	ds_read_b128 v[222:225], v185 offset:36864
	ds_read_b128 v[226:229], v185 offset:37888
	ds_read_b128 v[230:233], v185 offset:38912
	ds_read_b128 v[234:237], v185 offset:39936
	global_load_lds_dwordx4 v[242:243], off
	v_lshl_add_u64 v[242:243], s[14:15], 0, v[136:137]
	s_mov_b32 m0, s31
	s_nop 0
	global_load_lds_dwordx4 v[242:243], off
	s_waitcnt vmcnt(8)
	s_waitcnt lgkmcnt(0)
	s_barrier
	s_waitcnt lgkmcnt(0)
	v_mfma_f32_16x16x32_bf16 v[126:129], v[130:133], v[206:209], v[126:129]
	v_mfma_f32_16x16x32_bf16 v[118:121], v[150:153], v[206:209], v[118:121]
	v_mfma_f32_16x16x32_bf16 v[110:113], v[130:133], v[214:217], v[110:113]
	v_mfma_f32_16x16x32_bf16 v[102:105], v[150:153], v[214:217], v[102:105]
	v_mfma_f32_16x16x32_bf16 v[94:97], v[130:133], v[222:225], v[94:97]
	v_mfma_f32_16x16x32_bf16 v[86:89], v[150:153], v[222:225], v[86:89]
	v_mfma_f32_16x16x32_bf16 v[78:81], v[130:133], v[230:233], v[78:81]
	v_mfma_f32_16x16x32_bf16 v[70:73], v[150:153], v[230:233], v[70:73]
	v_mfma_f32_16x16x32_bf16 v[122:125], v[158:161], v[206:209], v[122:125]
	v_mfma_f32_16x16x32_bf16 v[114:117], v[186:189], v[206:209], v[114:117]
	v_mfma_f32_16x16x32_bf16 v[106:109], v[158:161], v[214:217], v[106:109]
	v_mfma_f32_16x16x32_bf16 v[98:101], v[186:189], v[214:217], v[98:101]
	v_mfma_f32_16x16x32_bf16 v[90:93], v[158:161], v[222:225], v[90:93]
	v_mfma_f32_16x16x32_bf16 v[82:85], v[186:189], v[222:225], v[82:85]
	v_mfma_f32_16x16x32_bf16 v[74:77], v[158:161], v[230:233], v[74:77]
	v_mfma_f32_16x16x32_bf16 v[66:69], v[186:189], v[230:233], v[66:69]
	v_mfma_f32_16x16x32_bf16 v[126:129], v[146:149], v[210:213], v[126:129]
	v_mfma_f32_16x16x32_bf16 v[118:121], v[154:157], v[210:213], v[118:121]
	v_mfma_f32_16x16x32_bf16 v[110:113], v[146:149], v[218:221], v[110:113]
	v_mfma_f32_16x16x32_bf16 v[102:105], v[154:157], v[218:221], v[102:105]
	v_mfma_f32_16x16x32_bf16 v[94:97], v[146:149], v[226:229], v[94:97]
	v_mfma_f32_16x16x32_bf16 v[86:89], v[154:157], v[226:229], v[86:89]
	v_mfma_f32_16x16x32_bf16 v[78:81], v[146:149], v[234:237], v[78:81]
	v_mfma_f32_16x16x32_bf16 v[70:73], v[154:157], v[234:237], v[70:73]
	v_mfma_f32_16x16x32_bf16 v[122:125], v[178:181], v[210:213], v[122:125]
	v_mfma_f32_16x16x32_bf16 v[114:117], v[202:205], v[210:213], v[114:117]
	v_mfma_f32_16x16x32_bf16 v[106:109], v[178:181], v[218:221], v[106:109]
	v_mfma_f32_16x16x32_bf16 v[98:101], v[202:205], v[218:221], v[98:101]
	v_mfma_f32_16x16x32_bf16 v[90:93], v[178:181], v[226:229], v[90:93]
	v_mfma_f32_16x16x32_bf16 v[82:85], v[202:205], v[226:229], v[82:85]
	v_mfma_f32_16x16x32_bf16 v[74:77], v[178:181], v[234:237], v[74:77]
	v_mfma_f32_16x16x32_bf16 v[66:69], v[202:205], v[234:237], v[66:69]
	s_barrier
	s_add_i32 s14, s22, s8
	v_lshl_add_u64 v[162:163], v[162:163], 0, s[20:21]
	s_mov_b32 m0, s14
	ds_read_b128 v[206:209], v185 offset:49152
	ds_read_b128 v[210:213], v185 offset:50176
	ds_read_b128 v[214:217], v185 offset:51200
	ds_read_b128 v[218:221], v185 offset:52224
	ds_read_b128 v[222:225], v185 offset:53248
	ds_read_b128 v[226:229], v185 offset:54272
	ds_read_b128 v[230:233], v185 offset:55296
	ds_read_b128 v[234:237], v185 offset:56320
	global_load_lds_dwordx4 v[162:163], off
	s_add_i32 m0, s14, 0x2000
	s_add_u32 s12, s12, 0x40080
	v_lshl_add_u64 v[162:163], v[190:191], 0, s[20:21]
	s_addc_u32 s13, s13, 0
	s_add_i32 s14, s23, s8
	global_load_lds_dwordx4 v[162:163], off
	v_lshl_add_u64 v[162:163], s[12:13], 0, v[0:1]
	s_mov_b32 m0, s14
	s_nop 0
	global_load_lds_dwordx4 v[162:163], off
	v_lshl_add_u64 v[162:163], s[12:13], 0, v[134:135]
	s_add_i32 m0, s14, 0x2000
	s_nop 0
	global_load_lds_dwordx4 v[162:163], off
	v_lshl_add_u64 v[162:163], v[238:239], 0, s[20:21]
	s_mov_b32 m0, s54
	s_nop 0
	global_load_lds_dwordx4 v[162:163], off
	v_lshl_add_u64 v[162:163], v[240:241], 0, s[20:21]
	s_mov_b32 m0, s55
	s_nop 0
	global_load_lds_dwordx4 v[162:163], off
	s_waitcnt vmcnt(8)
	s_waitcnt lgkmcnt(0)
	s_barrier
	s_waitcnt lgkmcnt(0)
	v_mfma_f32_16x16x32_bf16 v[62:65], v[130:133], v[206:209], v[62:65]
	v_mfma_f32_16x16x32_bf16 v[54:57], v[150:153], v[206:209], v[54:57]
	v_mfma_f32_16x16x32_bf16 v[46:49], v[130:133], v[214:217], v[46:49]
	v_mfma_f32_16x16x32_bf16 v[38:41], v[150:153], v[214:217], v[38:41]
	v_mfma_f32_16x16x32_bf16 v[30:33], v[130:133], v[222:225], v[30:33]
	v_mfma_f32_16x16x32_bf16 v[22:25], v[150:153], v[222:225], v[22:25]
	v_mfma_f32_16x16x32_bf16 v[14:17], v[130:133], v[230:233], v[14:17]
	v_mfma_f32_16x16x32_bf16 v[6:9], v[150:153], v[230:233], v[6:9]
	v_mfma_f32_16x16x32_bf16 v[58:61], v[158:161], v[206:209], v[58:61]
	v_mfma_f32_16x16x32_bf16 v[50:53], v[186:189], v[206:209], v[50:53]
	v_mfma_f32_16x16x32_bf16 v[42:45], v[158:161], v[214:217], v[42:45]
	v_mfma_f32_16x16x32_bf16 v[34:37], v[186:189], v[214:217], v[34:37]
	v_mfma_f32_16x16x32_bf16 v[26:29], v[158:161], v[222:225], v[26:29]
	v_mfma_f32_16x16x32_bf16 v[18:21], v[186:189], v[222:225], v[18:21]
	v_mfma_f32_16x16x32_bf16 v[10:13], v[158:161], v[230:233], v[10:13]
	v_mfma_f32_16x16x32_bf16 v[2:5], v[186:189], v[230:233], v[2:5]
	v_mfma_f32_16x16x32_bf16 v[62:65], v[146:149], v[210:213], v[62:65]
	v_mfma_f32_16x16x32_bf16 v[54:57], v[154:157], v[210:213], v[54:57]
	v_mfma_f32_16x16x32_bf16 v[46:49], v[146:149], v[218:221], v[46:49]
	v_mfma_f32_16x16x32_bf16 v[38:41], v[154:157], v[218:221], v[38:41]
	v_mfma_f32_16x16x32_bf16 v[30:33], v[146:149], v[226:229], v[30:33]
	v_mfma_f32_16x16x32_bf16 v[22:25], v[154:157], v[226:229], v[22:25]
	v_mfma_f32_16x16x32_bf16 v[14:17], v[146:149], v[234:237], v[14:17]
	v_mfma_f32_16x16x32_bf16 v[6:9], v[154:157], v[234:237], v[6:9]
	v_mfma_f32_16x16x32_bf16 v[58:61], v[178:181], v[210:213], v[58:61]
	v_mfma_f32_16x16x32_bf16 v[50:53], v[202:205], v[210:213], v[50:53]
	v_mfma_f32_16x16x32_bf16 v[42:45], v[178:181], v[218:221], v[42:45]
	v_mfma_f32_16x16x32_bf16 v[34:37], v[202:205], v[218:221], v[34:37]
	v_mfma_f32_16x16x32_bf16 v[26:29], v[178:181], v[226:229], v[26:29]
	v_mfma_f32_16x16x32_bf16 v[18:21], v[202:205], v[226:229], v[18:21]
	v_mfma_f32_16x16x32_bf16 v[10:13], v[178:181], v[234:237], v[10:13]
	v_mfma_f32_16x16x32_bf16 v[2:5], v[202:205], v[234:237], v[2:5]
	s_barrier
	s_add_i32 s63, s63, 2
	s_add_u32 s2, s2, 0x100
	s_addc_u32 s3, s3, 0
	s_add_u32 s61, s61, 0x100
	s_addc_u32 s62, s62, 0
	s_cmp_gt_u32 s63, 13
	s_cbranch_scc0 .LBB0_166

; #define PG8_STAGE(bufoff, gbase, voff) do { _Pragma("unroll") for (int _i = 0; _i < 2; ++_i) \
;         __builtin_amdgcn_global_load_lds((const unsigned*)((const char*)(gbase) + (voff)[_i]), (PG8_LAS unsigned*)(lds + (bufoff) + ldsw + _i * 8192), 16, 0, 0); } while (0)
; #define PG8_LDA(dst, b, h) do { _Pragma("unroll") for (int m = 0; m < 4; ++m) _Pragma("unroll") for (int k = 0; k < 2; ++k) dst[m][k] = *(const PG8_LAS bf16x8*)(lds + PG8_SA(b, h) + aoff + m * 2048 + k * 1024); } while (0)
; #define PG8_LDB(dst, b, h) do { _Pragma("unroll") for (int n = 0; n < 2; ++n) _Pragma("unroll") for (int k = 0; k < 2; ++k) dst[n][k] = *(const PG8_LAS bf16x8*)(lds + PG8_SB(b, h) + boff + n * 2048 + k * 1024); } while (0)
; #define PG8_MMA_NP(ai, bj, At, Bt) do { _Pragma("unroll") for (int m = 0; m < 4; ++m) _Pragma("unroll") for (int n = 0; n < 2; ++n) _Pragma("unroll") for (int k = 0; k < 2; ++k) \
;         acc[ai][bj][m][n] = __builtin_amdgcn_mfma_f32_16x16x32_bf16(Bt[n][k], At[m][k], acc[ai][bj][m][n], 0, 0, 0); } while (0)
; #define PG8_WAIT_V(n) asm volatile("s_waitcnt vmcnt(" #n ")" ::: "memory")
; #define PG8_WAIT_L(n) asm volatile("s_waitcnt lgkmcnt(" #n ")" ::: "memory")
; #define PG8_BAR __builtin_amdgcn_s_barrier()
; #define PG8_SCHED __builtin_amdgcn_sched_barrier(0)
; template <class Epi, class Sched, bool ALIGN_EPI = false, bool SP2 = false>
; __device__ __forceinline__ void gemm_phase(PG8_LAS unsigned char* lds, const Gemm g, const Sched& S, const Epi& E) {
;     ...
;             PG8_LDB(B0, 0, 0); PG8_LDB(B1, 0, 1); PG8_SCHED; PG8_LDA(At, 0, 0); PG8_STAGE(PG8_SA(1, 1), a1 + hstep, voffA);
;             PG8_WAIT_V(8); PG8_WAIT_L(0); PG8_BAR; __builtin_amdgcn_s_setprio(1); PG8_MMA_NP(0, 0, At, B0); PG8_MMA_NP(0, 1, At, B1); __builtin_amdgcn_s_setprio(0); PG8_BAR; PG8_SCHED;
;             PG8_LDA(At, 0, 1); PG8_STAGE(PG8_SB(0, 0), b2, voffB); PG8_STAGE(PG8_SB(0, 1), b2 + hstep, voffB); PG8_STAGE(PG8_SA(0, 0), a2, voffA);
;             PG8_WAIT_V(8); PG8_WAIT_L(0); PG8_BAR; __builtin_amdgcn_s_setprio(1); PG8_MMA_NP(1, 0, At, B0); PG8_MMA_NP(1, 1, At, B1); __builtin_amdgcn_s_setprio(0); PG8_BAR; PG8_SCHED;
.LBB0_194:
	s_add_u32 s40, s12, 0x100
	s_addc_u32 s41, s13, 0
	s_add_i32 s22, 0, 0x10000
	s_cmp_eq_u32 s70, 40
	s_cselect_b32 s47, s55, s41
	s_cselect_b32 s46, s54, s40
	s_cselect_b32 s15, s57, s69
	s_cselect_b32 s14, s56, s59
	s_add_i32 s23, 0, 0x14000
	v_add_u32_e32 v152, s22, v161
	v_add_u32_e32 v186, s23, v161
	ds_read_b128 v[130:133], v152
	ds_read_b128 v[134:137], v152 offset:1024
	ds_read_b128 v[148:151], v152 offset:2048
	ds_read_b128 v[152:155], v152 offset:3072
	ds_read_b128 v[156:159], v186
	ds_read_b128 v[178:181], v186 offset:1024
	ds_read_b128 v[182:185], v186 offset:2048
	ds_read_b128 v[186:189], v186 offset:3072
	v_lshl_add_u64 v[190:191], s[12:13], 0, v[144:145]
	s_add_i32 m0, s31, 0xc000
	ds_read_b128 v[202:205], v163
	ds_read_b128 v[206:209], v163 offset:1024
	ds_read_b128 v[210:213], v163 offset:2048
	ds_read_b128 v[214:217], v163 offset:3072
	ds_read_b128 v[218:221], v163 offset:4096
	ds_read_b128 v[222:225], v163 offset:5120
	ds_read_b128 v[226:229], v163 offset:6144
	ds_read_b128 v[230:233], v163 offset:7168
	global_load_lds_dwordx4 v[190:191], off
	v_lshl_add_u64 v[190:191], s[12:13], 0, v[146:147]
	s_add_i32 m0, s31, 0xe000
	s_nop 0
	global_load_lds_dwordx4 v[190:191], off
	s_waitcnt vmcnt(8)
	s_waitcnt lgkmcnt(0)
	s_barrier
	s_waitcnt lgkmcnt(0)
	v_mfma_f32_16x16x32_bf16 v[126:129], v[130:133], v[202:205], v[126:129]
	v_mfma_f32_16x16x32_bf16 v[122:125], v[148:151], v[202:205], v[122:125]
	v_mfma_f32_16x16x32_bf16 v[110:113], v[130:133], v[210:213], v[110:113]
	v_mfma_f32_16x16x32_bf16 v[106:109], v[148:151], v[210:213], v[106:109]
	v_mfma_f32_16x16x32_bf16 v[94:97], v[130:133], v[218:221], v[94:97]
	v_mfma_f32_16x16x32_bf16 v[90:93], v[148:151], v[218:221], v[90:93]
	v_mfma_f32_16x16x32_bf16 v[78:81], v[130:133], v[226:229], v[78:81]
	v_mfma_f32_16x16x32_bf16 v[74:77], v[148:151], v[226:229], v[74:77]
	v_mfma_f32_16x16x32_bf16 v[118:121], v[156:159], v[202:205], v[118:121]
	v_mfma_f32_16x16x32_bf16 v[114:117], v[182:185], v[202:205], v[114:117]
	v_mfma_f32_16x16x32_bf16 v[102:105], v[156:159], v[210:213], v[102:105]
	v_mfma_f32_16x16x32_bf16 v[98:101], v[182:185], v[210:213], v[98:101]
	v_mfma_f32_16x16x32_bf16 v[86:89], v[156:159], v[218:221], v[86:89]
	v_mfma_f32_16x16x32_bf16 v[82:85], v[182:185], v[218:221], v[82:85]
	v_mfma_f32_16x16x32_bf16 v[70:73], v[156:159], v[226:229], v[70:73]
	v_mfma_f32_16x16x32_bf16 v[66:69], v[182:185], v[226:229], v[66:69]
	v_mfma_f32_16x16x32_bf16 v[126:129], v[134:137], v[206:209], v[126:129]
	v_mfma_f32_16x16x32_bf16 v[122:125], v[152:155], v[206:209], v[122:125]
	v_mfma_f32_16x16x32_bf16 v[110:113], v[134:137], v[214:217], v[110:113]
	v_mfma_f32_16x16x32_bf16 v[106:109], v[152:155], v[214:217], v[106:109]
	v_mfma_f32_16x16x32_bf16 v[94:97], v[134:137], v[222:225], v[94:97]
	v_mfma_f32_16x16x32_bf16 v[90:93], v[152:155], v[222:225], v[90:93]
	v_mfma_f32_16x16x32_bf16 v[78:81], v[134:137], v[230:233], v[78:81]
	v_mfma_f32_16x16x32_bf16 v[74:77], v[152:155], v[230:233], v[74:77]
	v_mfma_f32_16x16x32_bf16 v[118:121], v[178:181], v[206:209], v[118:121]
	v_mfma_f32_16x16x32_bf16 v[114:117], v[186:189], v[206:209], v[114:117]
	v_mfma_f32_16x16x32_bf16 v[102:105], v[178:181], v[214:217], v[102:105]
	v_mfma_f32_16x16x32_bf16 v[98:101], v[186:189], v[214:217], v[98:101]
	v_mfma_f32_16x16x32_bf16 v[86:89], v[178:181], v[222:225], v[86:89]
	v_mfma_f32_16x16x32_bf16 v[82:85], v[186:189], v[222:225], v[82:85]
	v_mfma_f32_16x16x32_bf16 v[70:73], v[178:181], v[230:233], v[70:73]
	v_mfma_f32_16x16x32_bf16 v[66:69], v[186:189], v[230:233], v[66:69]
	s_barrier
	s_add_i32 s12, s22, s10
	v_lshl_add_u64 v[190:191], s[14:15], 0, v[0:1]
	s_mov_b32 m0, s12
	ds_read_b128 v[202:205], v163 offset:16384
	ds_read_b128 v[206:209], v163 offset:17408
	ds_read_b128 v[210:213], v163 offset:18432
	ds_read_b128 v[214:217], v163 offset:19456
	ds_read_b128 v[218:221], v163 offset:20480
	ds_read_b128 v[222:225], v163 offset:21504
	ds_read_b128 v[226:229], v163 offset:22528
	ds_read_b128 v[230:233], v163 offset:23552
	global_load_lds_dwordx4 v[190:191], off
	s_add_i32 m0, s12, 0x2000
	s_add_u32 s12, s14, 0xb0000
	v_lshl_add_u64 v[234:235], s[14:15], 0, v[138:139]
	s_addc_u32 s13, s15, 0
	s_add_i32 s22, s23, s10
	global_load_lds_dwordx4 v[234:235], off
	v_lshl_add_u64 v[236:237], s[12:13], 0, v[0:1]
	s_mov_b32 m0, s22
	v_lshl_add_u64 v[238:239], s[46:47], 0, v[140:141]
	global_load_lds_dwordx4 v[236:237], off
	v_lshl_add_u64 v[236:237], s[12:13], 0, v[138:139]
	s_add_i32 m0, s22, 0x2000
	s_nop 0
	global_load_lds_dwordx4 v[236:237], off
	v_lshl_add_u64 v[236:237], s[46:47], 0, v[142:143]
	s_mov_b32 m0, s31
	s_nop 0
	global_load_lds_dwordx4 v[236:237], off
	s_mov_b32 m0, s60
	s_nop 0
	global_load_lds_dwordx4 v[238:239], off
	s_waitcnt vmcnt(8)
	s_waitcnt lgkmcnt(0)
	s_barrier
; #define PG8_STAGE(bufoff, gbase, voff) do { _Pragma("unroll") for (int _i = 0; _i < 2; ++_i) \
;         __builtin_amdgcn_global_load_lds((const unsigned*)((const char*)(gbase) + (voff)[_i]), (PG8_LAS unsigned*)(lds + (bufoff) + ldsw + _i * 8192), 16, 0, 0); } while (0)
; #define PG8_LDA(dst, b, h) do { _Pragma("unroll") for (int m = 0; m < 4; ++m) _Pragma("unroll") for (int k = 0; k < 2; ++k) dst[m][k] = *(const PG8_LAS bf16x8*)(lds + PG8_SA(b, h) + aoff + m * 2048 + k * 1024); } while (0)
; #define PG8_LDB(dst, b, h) do { _Pragma("unroll") for (int n = 0; n < 2; ++n) _Pragma("unroll") for (int k = 0; k < 2; ++k) dst[n][k] = *(const PG8_LAS bf16x8*)(lds + PG8_SB(b, h) + boff + n * 2048 + k * 1024); } while (0)
; #define PG8_MMA_NP(ai, bj, At, Bt) do { _Pragma("unroll") for (int m = 0; m < 4; ++m) _Pragma("unroll") for (int n = 0; n < 2; ++n) _Pragma("unroll") for (int k = 0; k < 2; ++k) \
;         acc[ai][bj][m][n] = __builtin_amdgcn_mfma_f32_16x16x32_bf16(Bt[n][k], At[m][k], acc[ai][bj][m][n], 0, 0, 0); } while (0)
; #define PG8_WAIT_V(n) asm volatile("s_waitcnt vmcnt(" #n ")" ::: "memory")
; #define PG8_WAIT_L(n) asm volatile("s_waitcnt lgkmcnt(" #n ")" ::: "memory")
; #define PG8_BAR __builtin_amdgcn_s_barrier()
; #define PG8_SCHED __builtin_amdgcn_sched_barrier(0)
; template <class Epi, class Sched, bool ALIGN_EPI = false, bool SP2 = false>
; __device__ __forceinline__ void gemm_phase(PG8_LAS unsigned char* lds, const Gemm g, const Sched& S, const Epi& E) {
;     ...
;             PG8_WAIT_V(8); PG8_WAIT_L(0); PG8_BAR; __builtin_amdgcn_s_setprio(1); PG8_MMA_NP(1, 0, At, B0); PG8_MMA_NP(1, 1, At, B1); __builtin_amdgcn_s_setprio(0); PG8_BAR; PG8_SCHED;
;             PG8_LDB(B0, 1, 0); PG8_LDB(B1, 1, 1); PG8_SCHED; PG8_LDA(At, 1, 0); PG8_STAGE(PG8_SA(0, 1), a2 + hstep, voffA);
;             PG8_WAIT_V(8); PG8_WAIT_L(0); PG8_BAR; __builtin_amdgcn_s_setprio(1); PG8_MMA_NP(0, 0, At, B0); PG8_MMA_NP(0, 1, At, B1); __builtin_amdgcn_s_setprio(0); PG8_BAR; PG8_SCHED;
	s_waitcnt lgkmcnt(0)
	v_mfma_f32_16x16x32_bf16 v[62:65], v[130:133], v[202:205], v[62:65]
	v_mfma_f32_16x16x32_bf16 v[58:61], v[148:151], v[202:205], v[58:61]
	v_mfma_f32_16x16x32_bf16 v[46:49], v[130:133], v[210:213], v[46:49]
	v_mfma_f32_16x16x32_bf16 v[42:45], v[148:151], v[210:213], v[42:45]
	v_mfma_f32_16x16x32_bf16 v[30:33], v[130:133], v[218:221], v[30:33]
	v_mfma_f32_16x16x32_bf16 v[26:29], v[148:151], v[218:221], v[26:29]
	v_mfma_f32_16x16x32_bf16 v[14:17], v[130:133], v[226:229], v[14:17]
	v_mfma_f32_16x16x32_bf16 v[10:13], v[148:151], v[226:229], v[10:13]
	v_mfma_f32_16x16x32_bf16 v[54:57], v[156:159], v[202:205], v[54:57]
	v_mfma_f32_16x16x32_bf16 v[50:53], v[182:185], v[202:205], v[50:53]
	v_mfma_f32_16x16x32_bf16 v[38:41], v[156:159], v[210:213], v[38:41]
	v_mfma_f32_16x16x32_bf16 v[34:37], v[182:185], v[210:213], v[34:37]
	v_mfma_f32_16x16x32_bf16 v[22:25], v[156:159], v[218:221], v[22:25]
	v_mfma_f32_16x16x32_bf16 v[18:21], v[182:185], v[218:221], v[18:21]
	v_mfma_f32_16x16x32_bf16 v[6:9], v[156:159], v[226:229], v[6:9]
	v_mfma_f32_16x16x32_bf16 v[2:5], v[182:185], v[226:229], v[2:5]
	v_mfma_f32_16x16x32_bf16 v[62:65], v[134:137], v[206:209], v[62:65]
	v_mfma_f32_16x16x32_bf16 v[58:61], v[152:155], v[206:209], v[58:61]
	v_mfma_f32_16x16x32_bf16 v[46:49], v[134:137], v[214:217], v[46:49]
	v_mfma_f32_16x16x32_bf16 v[42:45], v[152:155], v[214:217], v[42:45]
	v_mfma_f32_16x16x32_bf16 v[30:33], v[134:137], v[222:225], v[30:33]
	v_mfma_f32_16x16x32_bf16 v[26:29], v[152:155], v[222:225], v[26:29]
	v_mfma_f32_16x16x32_bf16 v[14:17], v[134:137], v[230:233], v[14:17]
	v_mfma_f32_16x16x32_bf16 v[10:13], v[152:155], v[230:233], v[10:13]
	v_mfma_f32_16x16x32_bf16 v[54:57], v[178:181], v[206:209], v[54:57]
	v_mfma_f32_16x16x32_bf16 v[50:53], v[186:189], v[206:209], v[50:53]
	v_mfma_f32_16x16x32_bf16 v[38:41], v[178:181], v[214:217], v[38:41]
	v_mfma_f32_16x16x32_bf16 v[34:37], v[186:189], v[214:217], v[34:37]
	v_mfma_f32_16x16x32_bf16 v[22:25], v[178:181], v[222:225], v[22:25]
	v_mfma_f32_16x16x32_bf16 v[18:21], v[186:189], v[222:225], v[18:21]
	v_mfma_f32_16x16x32_bf16 v[6:9], v[178:181], v[230:233], v[6:9]
	v_mfma_f32_16x16x32_bf16 v[2:5], v[186:189], v[230:233], v[2:5]
	s_barrier
	s_add_i32 s22, 0, 0x18000
	s_add_i32 s23, 0, 0x1c000
	v_add_u32_e32 v152, s22, v161
	v_add_u32_e32 v186, s23, v161
	ds_read_b128 v[130:133], v152
	ds_read_b128 v[134:137], v152 offset:1024
	ds_read_b128 v[148:151], v152 offset:2048
	ds_read_b128 v[152:155], v152 offset:3072
	ds_read_b128 v[156:159], v186
	ds_read_b128 v[178:181], v186 offset:1024
	ds_read_b128 v[182:185], v186 offset:2048
	ds_read_b128 v[186:189], v186 offset:3072
	s_add_u32 s12, s46, 0xb0000
	s_addc_u32 s13, s47, 0
	s_mov_b32 m0, s61
	v_lshl_add_u64 v[240:241], s[12:13], 0, v[142:143]
	ds_read_b128 v[202:205], v163 offset:32768
	ds_read_b128 v[206:209], v163 offset:33792
	ds_read_b128 v[210:213], v163 offset:34816
	ds_read_b128 v[214:217], v163 offset:35840
	ds_read_b128 v[218:221], v163 offset:36864
	ds_read_b128 v[222:225], v163 offset:37888
	ds_read_b128 v[226:229], v163 offset:38912
	ds_read_b128 v[230:233], v163 offset:39936
	global_load_lds_dwordx4 v[240:241], off
	v_lshl_add_u64 v[240:241], s[12:13], 0, v[140:141]
	s_mov_b32 m0, s62
	s_nop 0
	global_load_lds_dwordx4 v[240:241], off
	s_waitcnt vmcnt(8)
	s_waitcnt lgkmcnt(0)
	s_barrier
	s_waitcnt lgkmcnt(0)
	v_mfma_f32_16x16x32_bf16 v[126:129], v[130:133], v[202:205], v[126:129]
	v_mfma_f32_16x16x32_bf16 v[122:125], v[148:151], v[202:205], v[122:125]
	v_mfma_f32_16x16x32_bf16 v[110:113], v[130:133], v[210:213], v[110:113]
	v_mfma_f32_16x16x32_bf16 v[106:109], v[148:151], v[210:213], v[106:109]
	v_mfma_f32_16x16x32_bf16 v[94:97], v[130:133], v[218:221], v[94:97]
	v_mfma_f32_16x16x32_bf16 v[90:93], v[148:151], v[218:221], v[90:93]
	v_mfma_f32_16x16x32_bf16 v[78:81], v[130:133], v[226:229], v[78:81]
	v_mfma_f32_16x16x32_bf16 v[74:77], v[148:151], v[226:229], v[74:77]
	v_mfma_f32_16x16x32_bf16 v[118:121], v[156:159], v[202:205], v[118:121]
	v_mfma_f32_16x16x32_bf16 v[114:117], v[182:185], v[202:205], v[114:117]
	v_mfma_f32_16x16x32_bf16 v[102:105], v[156:159], v[210:213], v[102:105]
	v_mfma_f32_16x16x32_bf16 v[98:101], v[182:185], v[210:213], v[98:101]
	v_mfma_f32_16x16x32_bf16 v[86:89], v[156:159], v[218:221], v[86:89]
	v_mfma_f32_16x16x32_bf16 v[82:85], v[182:185], v[218:221], v[82:85]
	v_mfma_f32_16x16x32_bf16 v[70:73], v[156:159], v[226:229], v[70:73]
	v_mfma_f32_16x16x32_bf16 v[66:69], v[182:185], v[226:229], v[66:69]
	v_mfma_f32_16x16x32_bf16 v[126:129], v[134:137], v[206:209], v[126:129]
	v_mfma_f32_16x16x32_bf16 v[122:125], v[152:155], v[206:209], v[122:125]
	v_mfma_f32_16x16x32_bf16 v[110:113], v[134:137], v[214:217], v[110:113]
	v_mfma_f32_16x16x32_bf16 v[106:109], v[152:155], v[214:217], v[106:109]
	v_mfma_f32_16x16x32_bf16 v[94:97], v[134:137], v[222:225], v[94:97]
	v_mfma_f32_16x16x32_bf16 v[90:93], v[152:155], v[222:225], v[90:93]
	v_mfma_f32_16x16x32_bf16 v[78:81], v[134:137], v[230:233], v[78:81]
	v_mfma_f32_16x16x32_bf16 v[74:77], v[152:155], v[230:233], v[74:77]
	v_mfma_f32_16x16x32_bf16 v[118:121], v[178:181], v[206:209], v[118:121]
	v_mfma_f32_16x16x32_bf16 v[114:117], v[186:189], v[206:209], v[114:117]
	v_mfma_f32_16x16x32_bf16 v[102:105], v[178:181], v[214:217], v[102:105]
	v_mfma_f32_16x16x32_bf16 v[98:101], v[186:189], v[214:217], v[98:101]
	v_mfma_f32_16x16x32_bf16 v[86:89], v[178:181], v[222:225], v[86:89]
	v_mfma_f32_16x16x32_bf16 v[82:85], v[186:189], v[222:225], v[82:85]
	v_mfma_f32_16x16x32_bf16 v[70:73], v[178:181], v[230:233], v[70:73]
	v_mfma_f32_16x16x32_bf16 v[66:69], v[186:189], v[230:233], v[66:69]
	s_barrier
; #define PG8_STAGE(bufoff, gbase, voff) do { _Pragma("unroll") for (int _i = 0; _i < 2; ++_i) \
;         __builtin_amdgcn_global_load_lds((const unsigned*)((const char*)(gbase) + (voff)[_i]), (PG8_LAS unsigned*)(lds + (bufoff) + ldsw + _i * 8192), 16, 0, 0); } while (0)
; #define PG8_LDA(dst, b, h) do { _Pragma("unroll") for (int m = 0; m < 4; ++m) _Pragma("unroll") for (int k = 0; k < 2; ++k) dst[m][k] = *(const PG8_LAS bf16x8*)(lds + PG8_SA(b, h) + aoff + m * 2048 + k * 1024); } while (0)
; #define PG8_MMA_NP(ai, bj, At, Bt) do { _Pragma("unroll") for (int m = 0; m < 4; ++m) _Pragma("unroll") for (int n = 0; n < 2; ++n) _Pragma("unroll") for (int k = 0; k < 2; ++k) \
;         acc[ai][bj][m][n] = __builtin_amdgcn_mfma_f32_16x16x32_bf16(Bt[n][k], At[m][k], acc[ai][bj][m][n], 0, 0, 0); } while (0)
; #define PG8_WAIT_V(n) asm volatile("s_waitcnt vmcnt(" #n ")" ::: "memory")
; #define PG8_WAIT_L(n) asm volatile("s_waitcnt lgkmcnt(" #n ")" ::: "memory")
; #define PG8_BAR __builtin_amdgcn_s_barrier()
; #define PG8_SCHED __builtin_amdgcn_sched_barrier(0)
; template <class Epi, class Sched, bool ALIGN_EPI = false, bool SP2 = false>
; __device__ __forceinline__ void gemm_phase(PG8_LAS unsigned char* lds, const Gemm g, const Sched& S, const Epi& E) {
;     ...
;             PG8_LDA(At, 1, 1); PG8_STAGE(PG8_SB(1, 0), b3, voffB); PG8_STAGE(PG8_SB(1, 1), b3 + hstep, voffB); PG8_STAGE(PG8_SA(1, 0), a3, voffA);
;             PG8_WAIT_V(8); PG8_WAIT_L(0); PG8_BAR; __builtin_amdgcn_s_setprio(1); PG8_MMA_NP(1, 0, At, B0); PG8_MMA_NP(1, 1, At, B1); __builtin_amdgcn_s_setprio(0); PG8_BAR; PG8_SCHED;
	s_add_i32 s12, s22, s10
	v_lshl_add_u64 v[190:191], v[190:191], 0, s[20:21]
	s_mov_b32 m0, s12
	ds_read_b128 v[202:205], v163 offset:49152
	ds_read_b128 v[206:209], v163 offset:50176
	ds_read_b128 v[210:213], v163 offset:51200
	ds_read_b128 v[214:217], v163 offset:52224
	ds_read_b128 v[218:221], v163 offset:53248
	ds_read_b128 v[222:225], v163 offset:54272
	ds_read_b128 v[226:229], v163 offset:55296
	ds_read_b128 v[230:233], v163 offset:56320
	global_load_lds_dwordx4 v[190:191], off
	s_add_i32 m0, s12, 0x2000
	s_add_u32 s12, s14, 0xb0080
	v_lshl_add_u64 v[190:191], v[234:235], 0, s[20:21]
	s_addc_u32 s13, s15, 0
	s_add_i32 s14, s23, s10
	global_load_lds_dwordx4 v[190:191], off
	v_lshl_add_u64 v[190:191], s[12:13], 0, v[0:1]
	s_mov_b32 m0, s14
	s_nop 0
	global_load_lds_dwordx4 v[190:191], off
	v_lshl_add_u64 v[190:191], s[12:13], 0, v[138:139]
	s_add_i32 m0, s14, 0x2000
	s_nop 0
	global_load_lds_dwordx4 v[190:191], off
	v_lshl_add_u64 v[190:191], v[236:237], 0, s[20:21]
	s_mov_b32 m0, s64
	s_nop 0
	global_load_lds_dwordx4 v[190:191], off
	v_lshl_add_u64 v[190:191], v[238:239], 0, s[20:21]
	s_mov_b32 m0, s65
	s_nop 0
	global_load_lds_dwordx4 v[190:191], off
	s_waitcnt vmcnt(8)
	s_waitcnt lgkmcnt(0)
	s_barrier
	s_waitcnt lgkmcnt(0)
	v_mfma_f32_16x16x32_bf16 v[62:65], v[130:133], v[202:205], v[62:65]
	v_mfma_f32_16x16x32_bf16 v[58:61], v[148:151], v[202:205], v[58:61]
	v_mfma_f32_16x16x32_bf16 v[46:49], v[130:133], v[210:213], v[46:49]
	v_mfma_f32_16x16x32_bf16 v[42:45], v[148:151], v[210:213], v[42:45]
	v_mfma_f32_16x16x32_bf16 v[30:33], v[130:133], v[218:221], v[30:33]
	v_mfma_f32_16x16x32_bf16 v[26:29], v[148:151], v[218:221], v[26:29]
	v_mfma_f32_16x16x32_bf16 v[14:17], v[130:133], v[226:229], v[14:17]
	v_mfma_f32_16x16x32_bf16 v[10:13], v[148:151], v[226:229], v[10:13]
	v_mfma_f32_16x16x32_bf16 v[54:57], v[156:159], v[202:205], v[54:57]
	v_mfma_f32_16x16x32_bf16 v[50:53], v[182:185], v[202:205], v[50:53]
	v_mfma_f32_16x16x32_bf16 v[38:41], v[156:159], v[210:213], v[38:41]
	v_mfma_f32_16x16x32_bf16 v[34:37], v[182:185], v[210:213], v[34:37]
	v_mfma_f32_16x16x32_bf16 v[22:25], v[156:159], v[218:221], v[22:25]
	v_mfma_f32_16x16x32_bf16 v[18:21], v[182:185], v[218:221], v[18:21]
	v_mfma_f32_16x16x32_bf16 v[6:9], v[156:159], v[226:229], v[6:9]
	v_mfma_f32_16x16x32_bf16 v[2:5], v[182:185], v[226:229], v[2:5]
	v_mfma_f32_16x16x32_bf16 v[62:65], v[134:137], v[206:209], v[62:65]
	v_mfma_f32_16x16x32_bf16 v[58:61], v[152:155], v[206:209], v[58:61]
	v_mfma_f32_16x16x32_bf16 v[46:49], v[134:137], v[214:217], v[46:49]
	v_mfma_f32_16x16x32_bf16 v[42:45], v[152:155], v[214:217], v[42:45]
	v_mfma_f32_16x16x32_bf16 v[30:33], v[134:137], v[222:225], v[30:33]
	v_mfma_f32_16x16x32_bf16 v[26:29], v[152:155], v[222:225], v[26:29]
	v_mfma_f32_16x16x32_bf16 v[14:17], v[134:137], v[230:233], v[14:17]
	v_mfma_f32_16x16x32_bf16 v[10:13], v[152:155], v[230:233], v[10:13]
	v_mfma_f32_16x16x32_bf16 v[54:57], v[178:181], v[206:209], v[54:57]
	v_mfma_f32_16x16x32_bf16 v[50:53], v[186:189], v[206:209], v[50:53]
	v_mfma_f32_16x16x32_bf16 v[38:41], v[178:181], v[214:217], v[38:41]
	v_mfma_f32_16x16x32_bf16 v[34:37], v[186:189], v[214:217], v[34:37]
	v_mfma_f32_16x16x32_bf16 v[22:25], v[178:181], v[222:225], v[22:25]
	v_mfma_f32_16x16x32_bf16 v[18:21], v[186:189], v[222:225], v[18:21]
	v_mfma_f32_16x16x32_bf16 v[6:9], v[178:181], v[230:233], v[6:9]
	v_mfma_f32_16x16x32_bf16 v[2:5], v[186:189], v[230:233], v[2:5]
	s_barrier
	s_add_i32 s70, s70, 2
	s_add_u32 s59, s59, 0x100
	s_addc_u32 s69, s69, 0
	s_cmp_gt_u32 s70, 41
	s_mov_b64 s[12:13], s[40:41]
	s_cbranch_scc0 .LBB0_194
	s_and_b64 vcc, exec, s[50:51]
	s_cbranch_vccz .LBB0_197
	s_barrier

; #define PG8_STAGE(bufoff, gbase, voff) do { _Pragma("unroll") for (int _i = 0; _i < 2; ++_i) \
;         __builtin_amdgcn_global_load_lds((const unsigned*)((const char*)(gbase) + (voff)[_i]), (PG8_LAS unsigned*)(lds + (bufoff) + ldsw + _i * 8192), 16, 0, 0); } while (0)
; #define PG8_LDA(dst, b, h) do { _Pragma("unroll") for (int m = 0; m < 4; ++m) _Pragma("unroll") for (int k = 0; k < 2; ++k) dst[m][k] = *(const PG8_LAS bf16x8*)(lds + PG8_SA(b, h) + aoff + m * 2048 + k * 1024); } while (0)
; #define PG8_LDB(dst, b, h) do { _Pragma("unroll") for (int n = 0; n < 2; ++n) _Pragma("unroll") for (int k = 0; k < 2; ++k) dst[n][k] = *(const PG8_LAS bf16x8*)(lds + PG8_SB(b, h) + boff + n * 2048 + k * 1024); } while (0)
; #define PG8_MMA_NP(ai, bj, At, Bt) do { _Pragma("unroll") for (int m = 0; m < 4; ++m) _Pragma("unroll") for (int n = 0; n < 2; ++n) _Pragma("unroll") for (int k = 0; k < 2; ++k) \
;         acc[ai][bj][m][n] = __builtin_amdgcn_mfma_f32_16x16x32_bf16(Bt[n][k], At[m][k], acc[ai][bj][m][n], 0, 0, 0); } while (0)
; template <class Epi, class Sched, bool ALIGN_EPI = false, bool SP2 = false>
; __device__ __forceinline__ void gemm_phase(PG8_LAS unsigned char* lds, const Gemm g, const Sched& S, const Epi& E) {
;     ...
;         const bool has_next = S.next(ui + 1, nxt);
;         const char* nA = has_next ? (const char*)g.A + (size_t)nxt.pm * tstep : cA; const char* nB = has_next ? (const char*)g.Bt + (size_t)nxt.pn * tstep : cB;
;         for (int t = 0; t < nt; t += 2) {
;             const bool last = (t == nt - 2);
;             const char* a1 = cA + (size_t)(t + 1) * kstep;
;             const char* a2 = last ? nA : cA + (size_t)(t + 2) * kstep; const char* b2 = last ? nB : cB + (size_t)(t + 2) * kstep;
;             const char* a3 = a2 + kstep; const char* b3 = b2 + kstep;
;             if (last && has_next) S.a_ready(nxt);
;             if constexpr (SP2) {
;             PG8_LDB(B0, 0, 0); PG8_LDB(B1, 0, 1); PG8_SCHED; PG8_LDA(At, 0, 0); PG8_STAGE(PG8_SA(1, 1), a1 + hstep, voffA);
;             PG8_WAIT_V(8); PG8_WAIT_L(0); PG8_BAR; __builtin_amdgcn_s_setprio(1); PG8_MMA_NP(0, 0, At, B0); PG8_MMA_NP(0, 1, At, B1); __builtin_amdgcn_s_setprio(0); PG8_BAR; PG8_SCHED;
;             PG8_LDA(At, 0, 1); PG8_STAGE(PG8_SB(0, 0), b2, voffB); PG8_STAGE(PG8_SB(0, 1), b2 + hstep, voffB); PG8_STAGE(PG8_SA(0, 0), a2, voffA);
.LBB0_369:
	s_ashr_i32 s55, s54, 31
	s_lshl_b64 s[40:41], s[54:55], 19
	s_add_u32 s56, s86, s40
	s_addc_u32 s57, s87, s41
	s_and_b64 s[40:41], s[42:43], exec
	s_cselect_b32 s46, s57, s13
	s_cselect_b32 s47, s56, s12
	s_ashr_i32 s53, s52, 31
	s_lshl_b64 s[40:41], s[52:53], 19
	s_add_u32 s58, s8, s40
	s_addc_u32 s59, s10, s41
	s_and_b64 s[40:41], s[42:43], exec
	s_cselect_b32 s48, s59, s15
	s_cselect_b32 s49, s58, s14
	s_add_u32 s12, s12, 0x40080
	s_addc_u32 s13, s13, 0
	s_add_u32 s53, s14, 0x100
	s_addc_u32 s55, s15, 0
	s_mov_b32 s65, -2
	s_add_u32 s14, s12, 0xfffc0080
	s_addc_u32 s15, s13, -1
	s_add_i32 s22, 0, 0x10000
	s_cmp_eq_u32 s65, 12
	s_cselect_b32 s41, s46, s15
	s_cselect_b32 s40, s47, s14
	s_cselect_b32 s15, s48, s55
	s_cselect_b32 s14, s49, s53
	s_add_i32 s23, 0, 0x14000
	v_add_u32_e32 v154, s22, v191
	v_add_u32_e32 v162, s23, v191
	ds_read_b128 v[130:133], v154
	ds_read_b128 v[146:149], v154 offset:1024
	ds_read_b128 v[150:153], v154 offset:2048
	ds_read_b128 v[154:157], v154 offset:3072
	ds_read_b128 v[158:161], v162
	ds_read_b128 v[178:181], v162 offset:1024
	ds_read_b128 v[182:185], v162 offset:2048
	ds_read_b128 v[186:189], v162 offset:3072
	v_lshl_add_u64 v[162:163], s[12:13], 0, v[142:143]
	s_add_i32 m0, s30, 0xc000
	ds_read_b128 v[204:207], v203
	ds_read_b128 v[208:211], v203 offset:1024
	ds_read_b128 v[212:215], v203 offset:2048
	ds_read_b128 v[216:219], v203 offset:3072
	ds_read_b128 v[220:223], v203 offset:4096
	ds_read_b128 v[224:227], v203 offset:5120
	ds_read_b128 v[228:231], v203 offset:6144
	ds_read_b128 v[232:235], v203 offset:7168
	global_load_lds_dwordx4 v[162:163], off
	v_lshl_add_u64 v[162:163], s[12:13], 0, v[144:145]
	s_add_i32 m0, s30, 0xe000
	s_nop 0
	global_load_lds_dwordx4 v[162:163], off
	s_waitcnt vmcnt(8)
	s_waitcnt lgkmcnt(0)
	s_barrier
	s_waitcnt lgkmcnt(0)
	v_mfma_f32_16x16x32_bf16 v[126:129], v[130:133], v[204:207], 0
	v_mfma_f32_16x16x32_bf16 v[122:125], v[150:153], v[204:207], 0
	v_mfma_f32_16x16x32_bf16 v[110:113], v[130:133], v[212:215], 0
	v_mfma_f32_16x16x32_bf16 v[106:109], v[150:153], v[212:215], 0
	v_mfma_f32_16x16x32_bf16 v[94:97], v[130:133], v[220:223], 0
	v_mfma_f32_16x16x32_bf16 v[90:93], v[150:153], v[220:223], 0
	v_mfma_f32_16x16x32_bf16 v[78:81], v[130:133], v[228:231], 0
	v_mfma_f32_16x16x32_bf16 v[74:77], v[150:153], v[228:231], 0
	v_mfma_f32_16x16x32_bf16 v[118:121], v[158:161], v[204:207], 0
	v_mfma_f32_16x16x32_bf16 v[114:117], v[182:185], v[204:207], 0
	v_mfma_f32_16x16x32_bf16 v[102:105], v[158:161], v[212:215], 0
	v_mfma_f32_16x16x32_bf16 v[98:101], v[182:185], v[212:215], 0
	v_mfma_f32_16x16x32_bf16 v[86:89], v[158:161], v[220:223], 0
	v_mfma_f32_16x16x32_bf16 v[82:85], v[182:185], v[220:223], 0
	v_mfma_f32_16x16x32_bf16 v[70:73], v[158:161], v[228:231], 0
	v_mfma_f32_16x16x32_bf16 v[66:69], v[182:185], v[228:231], 0
	v_mfma_f32_16x16x32_bf16 v[126:129], v[146:149], v[208:211], v[126:129]
	v_mfma_f32_16x16x32_bf16 v[122:125], v[154:157], v[208:211], v[122:125]
	v_mfma_f32_16x16x32_bf16 v[110:113], v[146:149], v[216:219], v[110:113]
	v_mfma_f32_16x16x32_bf16 v[106:109], v[154:157], v[216:219], v[106:109]
	v_mfma_f32_16x16x32_bf16 v[94:97], v[146:149], v[224:227], v[94:97]
	v_mfma_f32_16x16x32_bf16 v[90:93], v[154:157], v[224:227], v[90:93]
	v_mfma_f32_16x16x32_bf16 v[78:81], v[146:149], v[232:235], v[78:81]
	v_mfma_f32_16x16x32_bf16 v[74:77], v[154:157], v[232:235], v[74:77]
	v_mfma_f32_16x16x32_bf16 v[118:121], v[178:181], v[208:211], v[118:121]
	v_mfma_f32_16x16x32_bf16 v[114:117], v[186:189], v[208:211], v[114:117]
	v_mfma_f32_16x16x32_bf16 v[102:105], v[178:181], v[216:219], v[102:105]
	v_mfma_f32_16x16x32_bf16 v[98:101], v[186:189], v[216:219], v[98:101]
	v_mfma_f32_16x16x32_bf16 v[86:89], v[178:181], v[224:227], v[86:89]
	v_mfma_f32_16x16x32_bf16 v[82:85], v[186:189], v[224:227], v[82:85]
	v_mfma_f32_16x16x32_bf16 v[70:73], v[178:181], v[232:235], v[70:73]
	v_mfma_f32_16x16x32_bf16 v[66:69], v[186:189], v[232:235], v[66:69]
	s_barrier
	s_add_i32 s22, s22, s29
	v_lshl_add_u64 v[162:163], s[14:15], 0, v[0:1]
	s_mov_b32 m0, s22
	ds_read_b128 v[204:207], v203 offset:16384
	ds_read_b128 v[208:211], v203 offset:17408
	ds_read_b128 v[212:215], v203 offset:18432
	ds_read_b128 v[216:219], v203 offset:19456
	ds_read_b128 v[220:223], v203 offset:20480
	ds_read_b128 v[224:227], v203 offset:21504
	ds_read_b128 v[228:231], v203 offset:22528
	ds_read_b128 v[232:235], v203 offset:23552
	global_load_lds_dwordx4 v[162:163], off
	s_add_i32 m0, s22, 0x2000
	s_add_u32 s66, s14, 0x40000
	v_lshl_add_u64 v[236:237], s[14:15], 0, v[134:135]
	s_addc_u32 s67, s15, 0
	s_add_i32 s22, s23, s29
	global_load_lds_dwordx4 v[236:237], off
	v_lshl_add_u64 v[238:239], s[66:67], 0, v[0:1]
	s_mov_b32 m0, s22
	v_lshl_add_u64 v[240:241], s[40:41], 0, v[136:137]
	global_load_lds_dwordx4 v[238:239], off
	v_lshl_add_u64 v[238:239], s[66:67], 0, v[134:135]
	s_add_i32 m0, s22, 0x2000
	s_nop 0
	global_load_lds_dwordx4 v[238:239], off
	v_lshl_add_u64 v[238:239], s[40:41], 0, v[138:139]
	s_mov_b32 m0, s30
	s_nop 0
	global_load_lds_dwordx4 v[238:239], off
	s_mov_b32 m0, s31
	s_nop 0
	global_load_lds_dwordx4 v[240:241], off
	s_waitcnt vmcnt(8)
	s_waitcnt lgkmcnt(0)
	s_barrier
; #define PG8_STAGE(bufoff, gbase, voff) do { _Pragma("unroll") for (int _i = 0; _i < 2; ++_i) \
;         __builtin_amdgcn_global_load_lds((const unsigned*)((const char*)(gbase) + (voff)[_i]), (PG8_LAS unsigned*)(lds + (bufoff) + ldsw + _i * 8192), 16, 0, 0); } while (0)
; #define PG8_LDA(dst, b, h) do { _Pragma("unroll") for (int m = 0; m < 4; ++m) _Pragma("unroll") for (int k = 0; k < 2; ++k) dst[m][k] = *(const PG8_LAS bf16x8*)(lds + PG8_SA(b, h) + aoff + m * 2048 + k * 1024); } while (0)
; #define PG8_LDB(dst, b, h) do { _Pragma("unroll") for (int n = 0; n < 2; ++n) _Pragma("unroll") for (int k = 0; k < 2; ++k) dst[n][k] = *(const PG8_LAS bf16x8*)(lds + PG8_SB(b, h) + boff + n * 2048 + k * 1024); } while (0)
; #define PG8_MMA_NP(ai, bj, At, Bt) do { _Pragma("unroll") for (int m = 0; m < 4; ++m) _Pragma("unroll") for (int n = 0; n < 2; ++n) _Pragma("unroll") for (int k = 0; k < 2; ++k) \
;         acc[ai][bj][m][n] = __builtin_amdgcn_mfma_f32_16x16x32_bf16(Bt[n][k], At[m][k], acc[ai][bj][m][n], 0, 0, 0); } while (0)
; #define PG8_WAIT_V(n) asm volatile("s_waitcnt vmcnt(" #n ")" ::: "memory")
; #define PG8_WAIT_L(n) asm volatile("s_waitcnt lgkmcnt(" #n ")" ::: "memory")
; #define PG8_BAR __builtin_amdgcn_s_barrier()
; #define PG8_SCHED __builtin_amdgcn_sched_barrier(0)
; template <class Epi, class Sched, bool ALIGN_EPI = false, bool SP2 = false>
; __device__ __forceinline__ void gemm_phase(PG8_LAS unsigned char* lds, const Gemm g, const Sched& S, const Epi& E) {
;     ...
;             PG8_WAIT_V(8); PG8_WAIT_L(0); PG8_BAR; __builtin_amdgcn_s_setprio(1); PG8_MMA_NP(1, 0, At, B0); PG8_MMA_NP(1, 1, At, B1); __builtin_amdgcn_s_setprio(0); PG8_BAR; PG8_SCHED;
;             PG8_LDB(B0, 1, 0); PG8_LDB(B1, 1, 1); PG8_SCHED; PG8_LDA(At, 1, 0); PG8_STAGE(PG8_SA(0, 1), a2 + hstep, voffA);
;             PG8_WAIT_V(8); PG8_WAIT_L(0); PG8_BAR; __builtin_amdgcn_s_setprio(1); PG8_MMA_NP(0, 0, At, B0); PG8_MMA_NP(0, 1, At, B1); __builtin_amdgcn_s_setprio(0); PG8_BAR; PG8_SCHED;
	s_waitcnt lgkmcnt(0)
	v_mfma_f32_16x16x32_bf16 v[62:65], v[130:133], v[204:207], 0
	v_mfma_f32_16x16x32_bf16 v[58:61], v[150:153], v[204:207], 0
	v_mfma_f32_16x16x32_bf16 v[46:49], v[130:133], v[212:215], 0
	v_mfma_f32_16x16x32_bf16 v[42:45], v[150:153], v[212:215], 0
	v_mfma_f32_16x16x32_bf16 v[30:33], v[130:133], v[220:223], 0
	v_mfma_f32_16x16x32_bf16 v[26:29], v[150:153], v[220:223], 0
	v_mfma_f32_16x16x32_bf16 v[14:17], v[130:133], v[228:231], 0
	v_mfma_f32_16x16x32_bf16 v[10:13], v[150:153], v[228:231], 0
	v_mfma_f32_16x16x32_bf16 v[54:57], v[158:161], v[204:207], 0
	v_mfma_f32_16x16x32_bf16 v[50:53], v[182:185], v[204:207], 0
	v_mfma_f32_16x16x32_bf16 v[38:41], v[158:161], v[212:215], 0
	v_mfma_f32_16x16x32_bf16 v[34:37], v[182:185], v[212:215], 0
	v_mfma_f32_16x16x32_bf16 v[22:25], v[158:161], v[220:223], 0
	v_mfma_f32_16x16x32_bf16 v[18:21], v[182:185], v[220:223], 0
	v_mfma_f32_16x16x32_bf16 v[6:9], v[158:161], v[228:231], 0
	v_mfma_f32_16x16x32_bf16 v[2:5], v[182:185], v[228:231], 0
	v_mfma_f32_16x16x32_bf16 v[62:65], v[146:149], v[208:211], v[62:65]
	v_mfma_f32_16x16x32_bf16 v[58:61], v[154:157], v[208:211], v[58:61]
	v_mfma_f32_16x16x32_bf16 v[46:49], v[146:149], v[216:219], v[46:49]
	v_mfma_f32_16x16x32_bf16 v[42:45], v[154:157], v[216:219], v[42:45]
	v_mfma_f32_16x16x32_bf16 v[30:33], v[146:149], v[224:227], v[30:33]
	v_mfma_f32_16x16x32_bf16 v[26:29], v[154:157], v[224:227], v[26:29]
	v_mfma_f32_16x16x32_bf16 v[14:17], v[146:149], v[232:235], v[14:17]
	v_mfma_f32_16x16x32_bf16 v[10:13], v[154:157], v[232:235], v[10:13]
	v_mfma_f32_16x16x32_bf16 v[54:57], v[178:181], v[208:211], v[54:57]
	v_mfma_f32_16x16x32_bf16 v[50:53], v[186:189], v[208:211], v[50:53]
	v_mfma_f32_16x16x32_bf16 v[38:41], v[178:181], v[216:219], v[38:41]
	v_mfma_f32_16x16x32_bf16 v[34:37], v[186:189], v[216:219], v[34:37]
	v_mfma_f32_16x16x32_bf16 v[22:25], v[178:181], v[224:227], v[22:25]
	v_mfma_f32_16x16x32_bf16 v[18:21], v[186:189], v[224:227], v[18:21]
	v_mfma_f32_16x16x32_bf16 v[6:9], v[178:181], v[232:235], v[6:9]
	v_mfma_f32_16x16x32_bf16 v[2:5], v[186:189], v[232:235], v[2:5]
	s_barrier
	s_add_i32 s22, 0, 0x18000
	s_add_i32 s23, 0, 0x1c000
	v_add_u32_e32 v154, s22, v191
	v_add_u32_e32 v186, s23, v191
	ds_read_b128 v[130:133], v154
	ds_read_b128 v[146:149], v154 offset:1024
	ds_read_b128 v[150:153], v154 offset:2048
	ds_read_b128 v[154:157], v154 offset:3072
	ds_read_b128 v[158:161], v186
	ds_read_b128 v[178:181], v186 offset:1024
	ds_read_b128 v[182:185], v186 offset:2048
	ds_read_b128 v[186:189], v186 offset:3072
	s_add_u32 s40, s40, 0x40000
	s_addc_u32 s41, s41, 0
	s_mov_b32 m0, s60
	v_lshl_add_u64 v[242:243], s[40:41], 0, v[138:139]
	ds_read_b128 v[204:207], v203 offset:32768
	ds_read_b128 v[208:211], v203 offset:33792
	ds_read_b128 v[212:215], v203 offset:34816
	ds_read_b128 v[216:219], v203 offset:35840
	ds_read_b128 v[220:223], v203 offset:36864
	ds_read_b128 v[224:227], v203 offset:37888
	ds_read_b128 v[228:231], v203 offset:38912
	ds_read_b128 v[232:235], v203 offset:39936
	global_load_lds_dwordx4 v[242:243], off
	v_lshl_add_u64 v[242:243], s[40:41], 0, v[136:137]
	s_mov_b32 m0, s61
	s_nop 0
	global_load_lds_dwordx4 v[242:243], off
	s_waitcnt vmcnt(8)
	s_waitcnt lgkmcnt(0)
	s_barrier
	s_waitcnt lgkmcnt(0)
	v_mfma_f32_16x16x32_bf16 v[126:129], v[130:133], v[204:207], v[126:129]
	v_mfma_f32_16x16x32_bf16 v[122:125], v[150:153], v[204:207], v[122:125]
	v_mfma_f32_16x16x32_bf16 v[110:113], v[130:133], v[212:215], v[110:113]
	v_mfma_f32_16x16x32_bf16 v[106:109], v[150:153], v[212:215], v[106:109]
	v_mfma_f32_16x16x32_bf16 v[94:97], v[130:133], v[220:223], v[94:97]
	v_mfma_f32_16x16x32_bf16 v[90:93], v[150:153], v[220:223], v[90:93]
	v_mfma_f32_16x16x32_bf16 v[78:81], v[130:133], v[228:231], v[78:81]
	v_mfma_f32_16x16x32_bf16 v[74:77], v[150:153], v[228:231], v[74:77]
	v_mfma_f32_16x16x32_bf16 v[118:121], v[158:161], v[204:207], v[118:121]
	v_mfma_f32_16x16x32_bf16 v[114:117], v[182:185], v[204:207], v[114:117]
	v_mfma_f32_16x16x32_bf16 v[102:105], v[158:161], v[212:215], v[102:105]
	v_mfma_f32_16x16x32_bf16 v[98:101], v[182:185], v[212:215], v[98:101]
	v_mfma_f32_16x16x32_bf16 v[86:89], v[158:161], v[220:223], v[86:89]
	v_mfma_f32_16x16x32_bf16 v[82:85], v[182:185], v[220:223], v[82:85]
	v_mfma_f32_16x16x32_bf16 v[70:73], v[158:161], v[228:231], v[70:73]
	v_mfma_f32_16x16x32_bf16 v[66:69], v[182:185], v[228:231], v[66:69]
	v_mfma_f32_16x16x32_bf16 v[126:129], v[146:149], v[208:211], v[126:129]
	v_mfma_f32_16x16x32_bf16 v[122:125], v[154:157], v[208:211], v[122:125]
	v_mfma_f32_16x16x32_bf16 v[110:113], v[146:149], v[216:219], v[110:113]
	v_mfma_f32_16x16x32_bf16 v[106:109], v[154:157], v[216:219], v[106:109]
	v_mfma_f32_16x16x32_bf16 v[94:97], v[146:149], v[224:227], v[94:97]
	v_mfma_f32_16x16x32_bf16 v[90:93], v[154:157], v[224:227], v[90:93]
	v_mfma_f32_16x16x32_bf16 v[78:81], v[146:149], v[232:235], v[78:81]
	v_mfma_f32_16x16x32_bf16 v[74:77], v[154:157], v[232:235], v[74:77]
	v_mfma_f32_16x16x32_bf16 v[118:121], v[178:181], v[208:211], v[118:121]
	v_mfma_f32_16x16x32_bf16 v[114:117], v[186:189], v[208:211], v[114:117]
	v_mfma_f32_16x16x32_bf16 v[102:105], v[178:181], v[216:219], v[102:105]
	v_mfma_f32_16x16x32_bf16 v[98:101], v[186:189], v[216:219], v[98:101]
	v_mfma_f32_16x16x32_bf16 v[86:89], v[178:181], v[224:227], v[86:89]
	v_mfma_f32_16x16x32_bf16 v[82:85], v[186:189], v[224:227], v[82:85]
	v_mfma_f32_16x16x32_bf16 v[70:73], v[178:181], v[232:235], v[70:73]
	v_mfma_f32_16x16x32_bf16 v[66:69], v[186:189], v[232:235], v[66:69]
	s_barrier
; #define PG8_STAGE(bufoff, gbase, voff) do { _Pragma("unroll") for (int _i = 0; _i < 2; ++_i) \
;         __builtin_amdgcn_global_load_lds((const unsigned*)((const char*)(gbase) + (voff)[_i]), (PG8_LAS unsigned*)(lds + (bufoff) + ldsw + _i * 8192), 16, 0, 0); } while (0)
; #define PG8_LDA(dst, b, h) do { _Pragma("unroll") for (int m = 0; m < 4; ++m) _Pragma("unroll") for (int k = 0; k < 2; ++k) dst[m][k] = *(const PG8_LAS bf16x8*)(lds + PG8_SA(b, h) + aoff + m * 2048 + k * 1024); } while (0)
; #define PG8_WAIT_V(n) asm volatile("s_waitcnt vmcnt(" #n ")" ::: "memory")
; template <class Epi, class Sched, bool ALIGN_EPI = false, bool SP2 = false>
; __device__ __forceinline__ void gemm_phase(PG8_LAS unsigned char* lds, const Gemm g, const Sched& S, const Epi& E) {
;     ...
;             const char* a2 = last ? nA : cA + (size_t)(t + 2) * kstep; const char* b2 = last ? nB : cB + (size_t)(t + 2) * kstep;
;             const char* a3 = a2 + kstep; const char* b3 = b2 + kstep;
;             if (last && has_next) S.a_ready(nxt);
;             if constexpr (SP2) {
;             PG8_LDB(B0, 0, 0); PG8_LDB(B1, 0, 1); PG8_SCHED; PG8_LDA(At, 0, 0); PG8_STAGE(PG8_SA(1, 1), a1 + hstep, voffA);
;             PG8_WAIT_V(8); PG8_WAIT_L(0); PG8_BAR; __builtin_amdgcn_s_setprio(1); PG8_MMA_NP(0, 0, At, B0); PG8_MMA_NP(0, 1, At, B1); __builtin_amdgcn_s_setprio(0); PG8_BAR; PG8_SCHED;
;             PG8_LDA(At, 0, 1); PG8_STAGE(PG8_SB(0, 0), b2, voffB); PG8_STAGE(PG8_SB(0, 1), b2 + hstep, voffB); PG8_STAGE(PG8_SA(0, 0), a2, voffA);
;             PG8_WAIT_V(8); PG8_WAIT_L(0); PG8_BAR; __builtin_amdgcn_s_setprio(1); PG8_MMA_NP(1, 0, At, B0); PG8_MMA_NP(1, 1, At, B1); __builtin_amdgcn_s_setprio(0); PG8_BAR; PG8_SCHED;
;             PG8_LDB(B0, 1, 0); PG8_LDB(B1, 1, 1); PG8_SCHED; PG8_LDA(At, 1, 0); PG8_STAGE(PG8_SA(0, 1), a2 + hstep, voffA);
;             PG8_WAIT_V(8); PG8_WAIT_L(0); PG8_BAR; __builtin_amdgcn_s_setprio(1); PG8_MMA_NP(0, 0, At, B0); PG8_MMA_NP(0, 1, At, B1); __builtin_amdgcn_s_setprio(0); PG8_BAR; PG8_SCHED;
;             PG8_LDA(At, 1, 1); PG8_STAGE(PG8_SB(1, 0), b3, voffB); PG8_STAGE(PG8_SB(1, 1), b3 + hstep, voffB); PG8_STAGE(PG8_SA(1, 0), a3, voffA);
;             PG8_WAIT_V(8); PG8_WAIT_L(0); PG8_BAR; __builtin_amdgcn_s_setprio(1); PG8_MMA_NP(1, 0, At, B0); PG8_MMA_NP(1, 1, At, B1); __builtin_amdgcn_s_setprio(0); PG8_BAR; PG8_SCHED;
	s_add_i32 s22, s22, s29
	v_lshl_add_u64 v[162:163], v[162:163], 0, s[20:21]
	s_mov_b32 m0, s22
	ds_read_b128 v[204:207], v203 offset:49152
	ds_read_b128 v[208:211], v203 offset:50176
	ds_read_b128 v[212:215], v203 offset:51200
	ds_read_b128 v[216:219], v203 offset:52224
	ds_read_b128 v[220:223], v203 offset:53248
	ds_read_b128 v[224:227], v203 offset:54272
	ds_read_b128 v[228:231], v203 offset:55296
	ds_read_b128 v[232:235], v203 offset:56320
	global_load_lds_dwordx4 v[162:163], off
	s_add_i32 m0, s22, 0x2000
	s_add_u32 s14, s14, 0x40080
	v_lshl_add_u64 v[162:163], v[236:237], 0, s[20:21]
	s_addc_u32 s15, s15, 0
	s_add_i32 s22, s23, s29
	global_load_lds_dwordx4 v[162:163], off
	v_lshl_add_u64 v[162:163], s[14:15], 0, v[0:1]
	s_mov_b32 m0, s22
	s_nop 0
	global_load_lds_dwordx4 v[162:163], off
	v_lshl_add_u64 v[162:163], s[14:15], 0, v[134:135]
	s_add_i32 m0, s22, 0x2000
	s_nop 0
	global_load_lds_dwordx4 v[162:163], off
	v_lshl_add_u64 v[162:163], v[238:239], 0, s[20:21]
	s_mov_b32 m0, s62
	s_nop 0
	global_load_lds_dwordx4 v[162:163], off
	v_lshl_add_u64 v[162:163], v[240:241], 0, s[20:21]
	s_mov_b32 m0, s63
	s_nop 0
	global_load_lds_dwordx4 v[162:163], off
	s_waitcnt vmcnt(8)
	s_waitcnt lgkmcnt(0)
	s_barrier
	s_waitcnt lgkmcnt(0)
	v_mfma_f32_16x16x32_bf16 v[62:65], v[130:133], v[204:207], v[62:65]
	v_mfma_f32_16x16x32_bf16 v[58:61], v[150:153], v[204:207], v[58:61]
	v_mfma_f32_16x16x32_bf16 v[46:49], v[130:133], v[212:215], v[46:49]
	v_mfma_f32_16x16x32_bf16 v[42:45], v[150:153], v[212:215], v[42:45]
	v_mfma_f32_16x16x32_bf16 v[30:33], v[130:133], v[220:223], v[30:33]
	v_mfma_f32_16x16x32_bf16 v[26:29], v[150:153], v[220:223], v[26:29]
	v_mfma_f32_16x16x32_bf16 v[14:17], v[130:133], v[228:231], v[14:17]
	v_mfma_f32_16x16x32_bf16 v[10:13], v[150:153], v[228:231], v[10:13]
	v_mfma_f32_16x16x32_bf16 v[54:57], v[158:161], v[204:207], v[54:57]
	v_mfma_f32_16x16x32_bf16 v[50:53], v[182:185], v[204:207], v[50:53]
	v_mfma_f32_16x16x32_bf16 v[38:41], v[158:161], v[212:215], v[38:41]
	v_mfma_f32_16x16x32_bf16 v[34:37], v[182:185], v[212:215], v[34:37]
	v_mfma_f32_16x16x32_bf16 v[22:25], v[158:161], v[220:223], v[22:25]
	v_mfma_f32_16x16x32_bf16 v[18:21], v[182:185], v[220:223], v[18:21]
	v_mfma_f32_16x16x32_bf16 v[6:9], v[158:161], v[228:231], v[6:9]
	v_mfma_f32_16x16x32_bf16 v[2:5], v[182:185], v[228:231], v[2:5]
	v_mfma_f32_16x16x32_bf16 v[62:65], v[146:149], v[208:211], v[62:65]
	v_mfma_f32_16x16x32_bf16 v[58:61], v[154:157], v[208:211], v[58:61]
	v_mfma_f32_16x16x32_bf16 v[46:49], v[146:149], v[216:219], v[46:49]
	v_mfma_f32_16x16x32_bf16 v[42:45], v[154:157], v[216:219], v[42:45]
	v_mfma_f32_16x16x32_bf16 v[30:33], v[146:149], v[224:227], v[30:33]
	v_mfma_f32_16x16x32_bf16 v[26:29], v[154:157], v[224:227], v[26:29]
	v_mfma_f32_16x16x32_bf16 v[14:17], v[146:149], v[232:235], v[14:17]
	v_mfma_f32_16x16x32_bf16 v[10:13], v[154:157], v[232:235], v[10:13]
	v_mfma_f32_16x16x32_bf16 v[54:57], v[178:181], v[208:211], v[54:57]
	v_mfma_f32_16x16x32_bf16 v[50:53], v[186:189], v[208:211], v[50:53]
	v_mfma_f32_16x16x32_bf16 v[38:41], v[178:181], v[216:219], v[38:41]
	v_mfma_f32_16x16x32_bf16 v[34:37], v[186:189], v[216:219], v[34:37]
	v_mfma_f32_16x16x32_bf16 v[22:25], v[178:181], v[224:227], v[22:25]
	v_mfma_f32_16x16x32_bf16 v[18:21], v[186:189], v[224:227], v[18:21]
	v_mfma_f32_16x16x32_bf16 v[6:9], v[178:181], v[232:235], v[6:9]
	v_mfma_f32_16x16x32_bf16 v[2:5], v[186:189], v[232:235], v[2:5]
	s_barrier
	s_add_i32 s65, s65, 2
	s_add_u32 s12, s12, 0x100
	s_addc_u32 s13, s13, 0
	s_add_u32 s53, s53, 0x100
	s_addc_u32 s55, s55, 0
	s_cmp_gt_u32 s65, 13
	s_cbranch_scc0 .LBB0_370
	s_branch .Lkexit_2
.LBB0_370:
	s_add_u32 s14, s12, 0xfffc0080
	s_addc_u32 s15, s13, -1
	s_add_i32 s22, 0, 0x10000
	s_cmp_eq_u32 s65, 12
	s_cselect_b32 s41, s46, s15
	s_cselect_b32 s40, s47, s14
	s_cselect_b32 s15, s48, s55
	s_cselect_b32 s14, s49, s53
	s_add_i32 s23, 0, 0x14000
	v_add_u32_e32 v154, s22, v191
	v_add_u32_e32 v162, s23, v191
	ds_read_b128 v[130:133], v154
	ds_read_b128 v[146:149], v154 offset:1024
	ds_read_b128 v[150:153], v154 offset:2048
	ds_read_b128 v[154:157], v154 offset:3072
	ds_read_b128 v[158:161], v162
	ds_read_b128 v[178:181], v162 offset:1024
	ds_read_b128 v[182:185], v162 offset:2048
	ds_read_b128 v[186:189], v162 offset:3072
	v_lshl_add_u64 v[162:163], s[12:13], 0, v[142:143]
	s_add_i32 m0, s30, 0xc000
	ds_read_b128 v[204:207], v203
	ds_read_b128 v[208:211], v203 offset:1024
	ds_read_b128 v[212:215], v203 offset:2048
	ds_read_b128 v[216:219], v203 offset:3072
	ds_read_b128 v[220:223], v203 offset:4096
	ds_read_b128 v[224:227], v203 offset:5120
	ds_read_b128 v[228:231], v203 offset:6144
	ds_read_b128 v[232:235], v203 offset:7168
	global_load_lds_dwordx4 v[162:163], off
	v_lshl_add_u64 v[162:163], s[12:13], 0, v[144:145]
	s_add_i32 m0, s30, 0xe000
	s_nop 0
	global_load_lds_dwordx4 v[162:163], off
	s_waitcnt vmcnt(8)
	s_waitcnt lgkmcnt(0)
	s_barrier
; #define PG8_STAGE(bufoff, gbase, voff) do { _Pragma("unroll") for (int _i = 0; _i < 2; ++_i) \
;         __builtin_amdgcn_global_load_lds((const unsigned*)((const char*)(gbase) + (voff)[_i]), (PG8_LAS unsigned*)(lds + (bufoff) + ldsw + _i * 8192), 16, 0, 0); } while (0)
; #define PG8_LDA(dst, b, h) do { _Pragma("unroll") for (int m = 0; m < 4; ++m) _Pragma("unroll") for (int k = 0; k < 2; ++k) dst[m][k] = *(const PG8_LAS bf16x8*)(lds + PG8_SA(b, h) + aoff + m * 2048 + k * 1024); } while (0)
; #define PG8_MMA_NP(ai, bj, At, Bt) do { _Pragma("unroll") for (int m = 0; m < 4; ++m) _Pragma("unroll") for (int n = 0; n < 2; ++n) _Pragma("unroll") for (int k = 0; k < 2; ++k) \
;         acc[ai][bj][m][n] = __builtin_amdgcn_mfma_f32_16x16x32_bf16(Bt[n][k], At[m][k], acc[ai][bj][m][n], 0, 0, 0); } while (0)
; #define PG8_WAIT_V(n) asm volatile("s_waitcnt vmcnt(" #n ")" ::: "memory")
; #define PG8_WAIT_L(n) asm volatile("s_waitcnt lgkmcnt(" #n ")" ::: "memory")
; #define PG8_BAR __builtin_amdgcn_s_barrier()
; #define PG8_SCHED __builtin_amdgcn_sched_barrier(0)
; template <class Epi, class Sched, bool ALIGN_EPI = false, bool SP2 = false>
; __device__ __forceinline__ void gemm_phase(PG8_LAS unsigned char* lds, const Gemm g, const Sched& S, const Epi& E) {
;     ...
;             PG8_WAIT_V(8); PG8_WAIT_L(0); PG8_BAR; __builtin_amdgcn_s_setprio(1); PG8_MMA_NP(0, 0, At, B0); PG8_MMA_NP(0, 1, At, B1); __builtin_amdgcn_s_setprio(0); PG8_BAR; PG8_SCHED;
;             PG8_LDA(At, 0, 1); PG8_STAGE(PG8_SB(0, 0), b2, voffB); PG8_STAGE(PG8_SB(0, 1), b2 + hstep, voffB); PG8_STAGE(PG8_SA(0, 0), a2, voffA);
;             PG8_WAIT_V(8); PG8_WAIT_L(0); PG8_BAR; __builtin_amdgcn_s_setprio(1); PG8_MMA_NP(1, 0, At, B0); PG8_MMA_NP(1, 1, At, B1); __builtin_amdgcn_s_setprio(0); PG8_BAR; PG8_SCHED;
	s_waitcnt lgkmcnt(0)
	v_mfma_f32_16x16x32_bf16 v[126:129], v[130:133], v[204:207], v[126:129]
	v_mfma_f32_16x16x32_bf16 v[122:125], v[150:153], v[204:207], v[122:125]
	v_mfma_f32_16x16x32_bf16 v[110:113], v[130:133], v[212:215], v[110:113]
	v_mfma_f32_16x16x32_bf16 v[106:109], v[150:153], v[212:215], v[106:109]
	v_mfma_f32_16x16x32_bf16 v[94:97], v[130:133], v[220:223], v[94:97]
	v_mfma_f32_16x16x32_bf16 v[90:93], v[150:153], v[220:223], v[90:93]
	v_mfma_f32_16x16x32_bf16 v[78:81], v[130:133], v[228:231], v[78:81]
	v_mfma_f32_16x16x32_bf16 v[74:77], v[150:153], v[228:231], v[74:77]
	v_mfma_f32_16x16x32_bf16 v[118:121], v[158:161], v[204:207], v[118:121]
	v_mfma_f32_16x16x32_bf16 v[114:117], v[182:185], v[204:207], v[114:117]
	v_mfma_f32_16x16x32_bf16 v[102:105], v[158:161], v[212:215], v[102:105]
	v_mfma_f32_16x16x32_bf16 v[98:101], v[182:185], v[212:215], v[98:101]
	v_mfma_f32_16x16x32_bf16 v[86:89], v[158:161], v[220:223], v[86:89]
	v_mfma_f32_16x16x32_bf16 v[82:85], v[182:185], v[220:223], v[82:85]
	v_mfma_f32_16x16x32_bf16 v[70:73], v[158:161], v[228:231], v[70:73]
	v_mfma_f32_16x16x32_bf16 v[66:69], v[182:185], v[228:231], v[66:69]
	v_mfma_f32_16x16x32_bf16 v[126:129], v[146:149], v[208:211], v[126:129]
	v_mfma_f32_16x16x32_bf16 v[122:125], v[154:157], v[208:211], v[122:125]
	v_mfma_f32_16x16x32_bf16 v[110:113], v[146:149], v[216:219], v[110:113]
	v_mfma_f32_16x16x32_bf16 v[106:109], v[154:157], v[216:219], v[106:109]
	v_mfma_f32_16x16x32_bf16 v[94:97], v[146:149], v[224:227], v[94:97]
	v_mfma_f32_16x16x32_bf16 v[90:93], v[154:157], v[224:227], v[90:93]
	v_mfma_f32_16x16x32_bf16 v[78:81], v[146:149], v[232:235], v[78:81]
	v_mfma_f32_16x16x32_bf16 v[74:77], v[154:157], v[232:235], v[74:77]
	v_mfma_f32_16x16x32_bf16 v[118:121], v[178:181], v[208:211], v[118:121]
	v_mfma_f32_16x16x32_bf16 v[114:117], v[186:189], v[208:211], v[114:117]
	v_mfma_f32_16x16x32_bf16 v[102:105], v[178:181], v[216:219], v[102:105]
	v_mfma_f32_16x16x32_bf16 v[98:101], v[186:189], v[216:219], v[98:101]
	v_mfma_f32_16x16x32_bf16 v[86:89], v[178:181], v[224:227], v[86:89]
	v_mfma_f32_16x16x32_bf16 v[82:85], v[186:189], v[224:227], v[82:85]
	v_mfma_f32_16x16x32_bf16 v[70:73], v[178:181], v[232:235], v[70:73]
	v_mfma_f32_16x16x32_bf16 v[66:69], v[186:189], v[232:235], v[66:69]
	s_barrier
	s_add_i32 s22, s22, s29
	v_lshl_add_u64 v[162:163], s[14:15], 0, v[0:1]
	s_mov_b32 m0, s22
	ds_read_b128 v[204:207], v203 offset:16384
	ds_read_b128 v[208:211], v203 offset:17408
	ds_read_b128 v[212:215], v203 offset:18432
	ds_read_b128 v[216:219], v203 offset:19456
	ds_read_b128 v[220:223], v203 offset:20480
	ds_read_b128 v[224:227], v203 offset:21504
	ds_read_b128 v[228:231], v203 offset:22528
	ds_read_b128 v[232:235], v203 offset:23552
	global_load_lds_dwordx4 v[162:163], off
	s_add_i32 m0, s22, 0x2000
	s_add_u32 s66, s14, 0x40000
	v_lshl_add_u64 v[236:237], s[14:15], 0, v[134:135]
	s_addc_u32 s67, s15, 0
	s_add_i32 s22, s23, s29
	global_load_lds_dwordx4 v[236:237], off
	v_lshl_add_u64 v[238:239], s[66:67], 0, v[0:1]
	s_mov_b32 m0, s22
	v_lshl_add_u64 v[240:241], s[40:41], 0, v[136:137]
	global_load_lds_dwordx4 v[238:239], off
	v_lshl_add_u64 v[238:239], s[66:67], 0, v[134:135]
	s_add_i32 m0, s22, 0x2000
	s_nop 0
	global_load_lds_dwordx4 v[238:239], off
	v_lshl_add_u64 v[238:239], s[40:41], 0, v[138:139]
	s_mov_b32 m0, s30
	s_nop 0
	global_load_lds_dwordx4 v[238:239], off
	s_mov_b32 m0, s31
	s_nop 0
	global_load_lds_dwordx4 v[240:241], off
	s_waitcnt vmcnt(8)
	s_waitcnt lgkmcnt(0)
	s_barrier
	s_waitcnt lgkmcnt(0)
	v_mfma_f32_16x16x32_bf16 v[62:65], v[130:133], v[204:207], v[62:65]
	v_mfma_f32_16x16x32_bf16 v[58:61], v[150:153], v[204:207], v[58:61]
	v_mfma_f32_16x16x32_bf16 v[46:49], v[130:133], v[212:215], v[46:49]
	v_mfma_f32_16x16x32_bf16 v[42:45], v[150:153], v[212:215], v[42:45]
	v_mfma_f32_16x16x32_bf16 v[30:33], v[130:133], v[220:223], v[30:33]
	v_mfma_f32_16x16x32_bf16 v[26:29], v[150:153], v[220:223], v[26:29]
	v_mfma_f32_16x16x32_bf16 v[14:17], v[130:133], v[228:231], v[14:17]
	v_mfma_f32_16x16x32_bf16 v[10:13], v[150:153], v[228:231], v[10:13]
	v_mfma_f32_16x16x32_bf16 v[54:57], v[158:161], v[204:207], v[54:57]
	v_mfma_f32_16x16x32_bf16 v[50:53], v[182:185], v[204:207], v[50:53]
	v_mfma_f32_16x16x32_bf16 v[38:41], v[158:161], v[212:215], v[38:41]
	v_mfma_f32_16x16x32_bf16 v[34:37], v[182:185], v[212:215], v[34:37]
	v_mfma_f32_16x16x32_bf16 v[22:25], v[158:161], v[220:223], v[22:25]
	v_mfma_f32_16x16x32_bf16 v[18:21], v[182:185], v[220:223], v[18:21]
	v_mfma_f32_16x16x32_bf16 v[6:9], v[158:161], v[228:231], v[6:9]
	v_mfma_f32_16x16x32_bf16 v[2:5], v[182:185], v[228:231], v[2:5]
	v_mfma_f32_16x16x32_bf16 v[62:65], v[146:149], v[208:211], v[62:65]
	v_mfma_f32_16x16x32_bf16 v[58:61], v[154:157], v[208:211], v[58:61]
	v_mfma_f32_16x16x32_bf16 v[46:49], v[146:149], v[216:219], v[46:49]
	v_mfma_f32_16x16x32_bf16 v[42:45], v[154:157], v[216:219], v[42:45]
	v_mfma_f32_16x16x32_bf16 v[30:33], v[146:149], v[224:227], v[30:33]
	v_mfma_f32_16x16x32_bf16 v[26:29], v[154:157], v[224:227], v[26:29]
	v_mfma_f32_16x16x32_bf16 v[14:17], v[146:149], v[232:235], v[14:17]
	v_mfma_f32_16x16x32_bf16 v[10:13], v[154:157], v[232:235], v[10:13]
	v_mfma_f32_16x16x32_bf16 v[54:57], v[178:181], v[208:211], v[54:57]
	v_mfma_f32_16x16x32_bf16 v[50:53], v[186:189], v[208:211], v[50:53]
	v_mfma_f32_16x16x32_bf16 v[38:41], v[178:181], v[216:219], v[38:41]
	v_mfma_f32_16x16x32_bf16 v[34:37], v[186:189], v[216:219], v[34:37]
	v_mfma_f32_16x16x32_bf16 v[22:25], v[178:181], v[224:227], v[22:25]
	v_mfma_f32_16x16x32_bf16 v[18:21], v[186:189], v[224:227], v[18:21]
	v_mfma_f32_16x16x32_bf16 v[6:9], v[178:181], v[232:235], v[6:9]
	v_mfma_f32_16x16x32_bf16 v[2:5], v[186:189], v[232:235], v[2:5]
	s_barrier
; #define PG8_STAGE(bufoff, gbase, voff) do { _Pragma("unroll") for (int _i = 0; _i < 2; ++_i) \
;         __builtin_amdgcn_global_load_lds((const unsigned*)((const char*)(gbase) + (voff)[_i]), (PG8_LAS unsigned*)(lds + (bufoff) + ldsw + _i * 8192), 16, 0, 0); } while (0)
; #define PG8_LDA(dst, b, h) do { _Pragma("unroll") for (int m = 0; m < 4; ++m) _Pragma("unroll") for (int k = 0; k < 2; ++k) dst[m][k] = *(const PG8_LAS bf16x8*)(lds + PG8_SA(b, h) + aoff + m * 2048 + k * 1024); } while (0)
; #define PG8_LDB(dst, b, h) do { _Pragma("unroll") for (int n = 0; n < 2; ++n) _Pragma("unroll") for (int k = 0; k < 2; ++k) dst[n][k] = *(const PG8_LAS bf16x8*)(lds + PG8_SB(b, h) + boff + n * 2048 + k * 1024); } while (0)
; #define PG8_MMA_NP(ai, bj, At, Bt) do { _Pragma("unroll") for (int m = 0; m < 4; ++m) _Pragma("unroll") for (int n = 0; n < 2; ++n) _Pragma("unroll") for (int k = 0; k < 2; ++k) \
;         acc[ai][bj][m][n] = __builtin_amdgcn_mfma_f32_16x16x32_bf16(Bt[n][k], At[m][k], acc[ai][bj][m][n], 0, 0, 0); } while (0)
; #define PG8_WAIT_V(n) asm volatile("s_waitcnt vmcnt(" #n ")" ::: "memory")
; #define PG8_WAIT_L(n) asm volatile("s_waitcnt lgkmcnt(" #n ")" ::: "memory")
; #define PG8_BAR __builtin_amdgcn_s_barrier()
; #define PG8_SCHED __builtin_amdgcn_sched_barrier(0)
; template <class Epi, class Sched, bool ALIGN_EPI = false, bool SP2 = false>
; __device__ __forceinline__ void gemm_phase(PG8_LAS unsigned char* lds, const Gemm g, const Sched& S, const Epi& E) {
;     ...
;             PG8_LDB(B0, 1, 0); PG8_LDB(B1, 1, 1); PG8_SCHED; PG8_LDA(At, 1, 0); PG8_STAGE(PG8_SA(0, 1), a2 + hstep, voffA);
;             PG8_WAIT_V(8); PG8_WAIT_L(0); PG8_BAR; __builtin_amdgcn_s_setprio(1); PG8_MMA_NP(0, 0, At, B0); PG8_MMA_NP(0, 1, At, B1); __builtin_amdgcn_s_setprio(0); PG8_BAR; PG8_SCHED;
	s_add_i32 s22, 0, 0x18000
	s_add_i32 s23, 0, 0x1c000
	v_add_u32_e32 v154, s22, v191
	v_add_u32_e32 v186, s23, v191
	ds_read_b128 v[130:133], v154
	ds_read_b128 v[146:149], v154 offset:1024
	ds_read_b128 v[150:153], v154 offset:2048
	ds_read_b128 v[154:157], v154 offset:3072
	ds_read_b128 v[158:161], v186
	ds_read_b128 v[178:181], v186 offset:1024
	ds_read_b128 v[182:185], v186 offset:2048
	ds_read_b128 v[186:189], v186 offset:3072
	s_add_u32 s40, s40, 0x40000
	s_addc_u32 s41, s41, 0
	s_mov_b32 m0, s60
	v_lshl_add_u64 v[242:243], s[40:41], 0, v[138:139]
	ds_read_b128 v[204:207], v203 offset:32768
	ds_read_b128 v[208:211], v203 offset:33792
	ds_read_b128 v[212:215], v203 offset:34816
	ds_read_b128 v[216:219], v203 offset:35840
	ds_read_b128 v[220:223], v203 offset:36864
	ds_read_b128 v[224:227], v203 offset:37888
	ds_read_b128 v[228:231], v203 offset:38912
	ds_read_b128 v[232:235], v203 offset:39936
	global_load_lds_dwordx4 v[242:243], off
	v_lshl_add_u64 v[242:243], s[40:41], 0, v[136:137]
	s_mov_b32 m0, s61
	s_nop 0
	global_load_lds_dwordx4 v[242:243], off
	s_waitcnt vmcnt(8)
	s_waitcnt lgkmcnt(0)
	s_barrier
	s_waitcnt lgkmcnt(0)
	v_mfma_f32_16x16x32_bf16 v[126:129], v[130:133], v[204:207], v[126:129]
	v_mfma_f32_16x16x32_bf16 v[122:125], v[150:153], v[204:207], v[122:125]
	v_mfma_f32_16x16x32_bf16 v[110:113], v[130:133], v[212:215], v[110:113]
	v_mfma_f32_16x16x32_bf16 v[106:109], v[150:153], v[212:215], v[106:109]
	v_mfma_f32_16x16x32_bf16 v[94:97], v[130:133], v[220:223], v[94:97]
	v_mfma_f32_16x16x32_bf16 v[90:93], v[150:153], v[220:223], v[90:93]
	v_mfma_f32_16x16x32_bf16 v[78:81], v[130:133], v[228:231], v[78:81]
	v_mfma_f32_16x16x32_bf16 v[74:77], v[150:153], v[228:231], v[74:77]
	v_mfma_f32_16x16x32_bf16 v[118:121], v[158:161], v[204:207], v[118:121]
	v_mfma_f32_16x16x32_bf16 v[114:117], v[182:185], v[204:207], v[114:117]
	v_mfma_f32_16x16x32_bf16 v[102:105], v[158:161], v[212:215], v[102:105]
	v_mfma_f32_16x16x32_bf16 v[98:101], v[182:185], v[212:215], v[98:101]
	v_mfma_f32_16x16x32_bf16 v[86:89], v[158:161], v[220:223], v[86:89]
	v_mfma_f32_16x16x32_bf16 v[82:85], v[182:185], v[220:223], v[82:85]
	v_mfma_f32_16x16x32_bf16 v[70:73], v[158:161], v[228:231], v[70:73]
	v_mfma_f32_16x16x32_bf16 v[66:69], v[182:185], v[228:231], v[66:69]
	v_mfma_f32_16x16x32_bf16 v[126:129], v[146:149], v[208:211], v[126:129]
	v_mfma_f32_16x16x32_bf16 v[122:125], v[154:157], v[208:211], v[122:125]
	v_mfma_f32_16x16x32_bf16 v[110:113], v[146:149], v[216:219], v[110:113]
	v_mfma_f32_16x16x32_bf16 v[106:109], v[154:157], v[216:219], v[106:109]
	v_mfma_f32_16x16x32_bf16 v[94:97], v[146:149], v[224:227], v[94:97]
	v_mfma_f32_16x16x32_bf16 v[90:93], v[154:157], v[224:227], v[90:93]
	v_mfma_f32_16x16x32_bf16 v[78:81], v[146:149], v[232:235], v[78:81]
	v_mfma_f32_16x16x32_bf16 v[74:77], v[154:157], v[232:235], v[74:77]
	v_mfma_f32_16x16x32_bf16 v[118:121], v[178:181], v[208:211], v[118:121]
	v_mfma_f32_16x16x32_bf16 v[114:117], v[186:189], v[208:211], v[114:117]
	v_mfma_f32_16x16x32_bf16 v[102:105], v[178:181], v[216:219], v[102:105]
	v_mfma_f32_16x16x32_bf16 v[98:101], v[186:189], v[216:219], v[98:101]
	v_mfma_f32_16x16x32_bf16 v[86:89], v[178:181], v[224:227], v[86:89]
	v_mfma_f32_16x16x32_bf16 v[82:85], v[186:189], v[224:227], v[82:85]
	v_mfma_f32_16x16x32_bf16 v[70:73], v[178:181], v[232:235], v[70:73]
	v_mfma_f32_16x16x32_bf16 v[66:69], v[186:189], v[232:235], v[66:69]
	s_barrier
; #define PG8_STAGE(bufoff, gbase, voff) do { _Pragma("unroll") for (int _i = 0; _i < 2; ++_i) \
;         __builtin_amdgcn_global_load_lds((const unsigned*)((const char*)(gbase) + (voff)[_i]), (PG8_LAS unsigned*)(lds + (bufoff) + ldsw + _i * 8192), 16, 0, 0); } while (0)
; #define PG8_LDA(dst, b, h) do { _Pragma("unroll") for (int m = 0; m < 4; ++m) _Pragma("unroll") for (int k = 0; k < 2; ++k) dst[m][k] = *(const PG8_LAS bf16x8*)(lds + PG8_SA(b, h) + aoff + m * 2048 + k * 1024); } while (0)
; #define PG8_MMA_NP(ai, bj, At, Bt) do { _Pragma("unroll") for (int m = 0; m < 4; ++m) _Pragma("unroll") for (int n = 0; n < 2; ++n) _Pragma("unroll") for (int k = 0; k < 2; ++k) \
;         acc[ai][bj][m][n] = __builtin_amdgcn_mfma_f32_16x16x32_bf16(Bt[n][k], At[m][k], acc[ai][bj][m][n], 0, 0, 0); } while (0)
; #define PG8_WAIT_V(n) asm volatile("s_waitcnt vmcnt(" #n ")" ::: "memory")
; #define PG8_WAIT_L(n) asm volatile("s_waitcnt lgkmcnt(" #n ")" ::: "memory")
; #define PG8_BAR __builtin_amdgcn_s_barrier()
; #define PG8_SCHED __builtin_amdgcn_sched_barrier(0)
; template <class Epi, class Sched, bool ALIGN_EPI = false, bool SP2 = false>
; __device__ __forceinline__ void gemm_phase(PG8_LAS unsigned char* lds, const Gemm g, const Sched& S, const Epi& E) {
;     ...
;         for (int t = 0; t < nt; t += 2) {
;     ...
;             PG8_LDA(At, 1, 1); PG8_STAGE(PG8_SB(1, 0), b3, voffB); PG8_STAGE(PG8_SB(1, 1), b3 + hstep, voffB); PG8_STAGE(PG8_SA(1, 0), a3, voffA);
;             PG8_WAIT_V(8); PG8_WAIT_L(0); PG8_BAR; __builtin_amdgcn_s_setprio(1); PG8_MMA_NP(1, 0, At, B0); PG8_MMA_NP(1, 1, At, B1); __builtin_amdgcn_s_setprio(0); PG8_BAR; PG8_SCHED;
	s_add_i32 s22, s22, s29
	v_lshl_add_u64 v[162:163], v[162:163], 0, s[20:21]
	s_mov_b32 m0, s22
	ds_read_b128 v[204:207], v203 offset:49152
	ds_read_b128 v[208:211], v203 offset:50176
	ds_read_b128 v[212:215], v203 offset:51200
	ds_read_b128 v[216:219], v203 offset:52224
	ds_read_b128 v[220:223], v203 offset:53248
	ds_read_b128 v[224:227], v203 offset:54272
	ds_read_b128 v[228:231], v203 offset:55296
	ds_read_b128 v[232:235], v203 offset:56320
	global_load_lds_dwordx4 v[162:163], off
	s_add_i32 m0, s22, 0x2000
	s_add_u32 s14, s14, 0x40080
	v_lshl_add_u64 v[162:163], v[236:237], 0, s[20:21]
	s_addc_u32 s15, s15, 0
	s_add_i32 s22, s23, s29
	global_load_lds_dwordx4 v[162:163], off
	v_lshl_add_u64 v[162:163], s[14:15], 0, v[0:1]
	s_mov_b32 m0, s22
	s_nop 0
	global_load_lds_dwordx4 v[162:163], off
	v_lshl_add_u64 v[162:163], s[14:15], 0, v[134:135]
	s_add_i32 m0, s22, 0x2000
	s_nop 0
	global_load_lds_dwordx4 v[162:163], off
	v_lshl_add_u64 v[162:163], v[238:239], 0, s[20:21]
	s_mov_b32 m0, s62
	s_nop 0
	global_load_lds_dwordx4 v[162:163], off
	v_lshl_add_u64 v[162:163], v[240:241], 0, s[20:21]
	s_mov_b32 m0, s63
	s_nop 0
	global_load_lds_dwordx4 v[162:163], off
	s_waitcnt vmcnt(8)
	s_waitcnt lgkmcnt(0)
	s_barrier
	s_waitcnt lgkmcnt(0)
	v_mfma_f32_16x16x32_bf16 v[62:65], v[130:133], v[204:207], v[62:65]
	v_mfma_f32_16x16x32_bf16 v[58:61], v[150:153], v[204:207], v[58:61]
	v_mfma_f32_16x16x32_bf16 v[46:49], v[130:133], v[212:215], v[46:49]
	v_mfma_f32_16x16x32_bf16 v[42:45], v[150:153], v[212:215], v[42:45]
	v_mfma_f32_16x16x32_bf16 v[30:33], v[130:133], v[220:223], v[30:33]
	v_mfma_f32_16x16x32_bf16 v[26:29], v[150:153], v[220:223], v[26:29]
	v_mfma_f32_16x16x32_bf16 v[14:17], v[130:133], v[228:231], v[14:17]
	v_mfma_f32_16x16x32_bf16 v[10:13], v[150:153], v[228:231], v[10:13]
	v_mfma_f32_16x16x32_bf16 v[54:57], v[158:161], v[204:207], v[54:57]
	v_mfma_f32_16x16x32_bf16 v[50:53], v[182:185], v[204:207], v[50:53]
	v_mfma_f32_16x16x32_bf16 v[38:41], v[158:161], v[212:215], v[38:41]
	v_mfma_f32_16x16x32_bf16 v[34:37], v[182:185], v[212:215], v[34:37]
	v_mfma_f32_16x16x32_bf16 v[22:25], v[158:161], v[220:223], v[22:25]
	v_mfma_f32_16x16x32_bf16 v[18:21], v[182:185], v[220:223], v[18:21]
	v_mfma_f32_16x16x32_bf16 v[6:9], v[158:161], v[228:231], v[6:9]
	v_mfma_f32_16x16x32_bf16 v[2:5], v[182:185], v[228:231], v[2:5]
	v_mfma_f32_16x16x32_bf16 v[62:65], v[146:149], v[208:211], v[62:65]
	v_mfma_f32_16x16x32_bf16 v[58:61], v[154:157], v[208:211], v[58:61]
	v_mfma_f32_16x16x32_bf16 v[46:49], v[146:149], v[216:219], v[46:49]
	v_mfma_f32_16x16x32_bf16 v[42:45], v[154:157], v[216:219], v[42:45]
	v_mfma_f32_16x16x32_bf16 v[30:33], v[146:149], v[224:227], v[30:33]
	v_mfma_f32_16x16x32_bf16 v[26:29], v[154:157], v[224:227], v[26:29]
	v_mfma_f32_16x16x32_bf16 v[14:17], v[146:149], v[232:235], v[14:17]
	v_mfma_f32_16x16x32_bf16 v[10:13], v[154:157], v[232:235], v[10:13]
	v_mfma_f32_16x16x32_bf16 v[54:57], v[178:181], v[208:211], v[54:57]
	v_mfma_f32_16x16x32_bf16 v[50:53], v[186:189], v[208:211], v[50:53]
	v_mfma_f32_16x16x32_bf16 v[38:41], v[178:181], v[216:219], v[38:41]
	v_mfma_f32_16x16x32_bf16 v[34:37], v[186:189], v[216:219], v[34:37]
	v_mfma_f32_16x16x32_bf16 v[22:25], v[178:181], v[224:227], v[22:25]
	v_mfma_f32_16x16x32_bf16 v[18:21], v[186:189], v[224:227], v[18:21]
	v_mfma_f32_16x16x32_bf16 v[6:9], v[178:181], v[232:235], v[6:9]
	v_mfma_f32_16x16x32_bf16 v[2:5], v[186:189], v[232:235], v[2:5]
	s_barrier
	s_add_i32 s65, s65, 2
	s_add_u32 s12, s12, 0x100
	s_addc_u32 s13, s13, 0
	s_add_u32 s53, s53, 0x100
	s_addc_u32 s55, s55, 0
	s_cmp_gt_u32 s65, 13
	s_cbranch_scc0 .LBB0_370

; #define PG8_STAGE(bufoff, gbase, voff) do { _Pragma("unroll") for (int _i = 0; _i < 2; ++_i) \
;         __builtin_amdgcn_global_load_lds((const unsigned*)((const char*)(gbase) + (voff)[_i]), (PG8_LAS unsigned*)(lds + (bufoff) + ldsw + _i * 8192), 16, 0, 0); } while (0)
; #define PG8_LDA(dst, b, h) do { _Pragma("unroll") for (int m = 0; m < 4; ++m) _Pragma("unroll") for (int k = 0; k < 2; ++k) dst[m][k] = *(const PG8_LAS bf16x8*)(lds + PG8_SA(b, h) + aoff + m * 2048 + k * 1024); } while (0)
; #define PG8_LDB(dst, b, h) do { _Pragma("unroll") for (int n = 0; n < 2; ++n) _Pragma("unroll") for (int k = 0; k < 2; ++k) dst[n][k] = *(const PG8_LAS bf16x8*)(lds + PG8_SB(b, h) + boff + n * 2048 + k * 1024); } while (0)
; #define PG8_MMA_NP(ai, bj, At, Bt) do { _Pragma("unroll") for (int m = 0; m < 4; ++m) _Pragma("unroll") for (int n = 0; n < 2; ++n) _Pragma("unroll") for (int k = 0; k < 2; ++k) \
;         acc[ai][bj][m][n] = __builtin_amdgcn_mfma_f32_16x16x32_bf16(Bt[n][k], At[m][k], acc[ai][bj][m][n], 0, 0, 0); } while (0)
; template <class Epi, class Sched, bool ALIGN_EPI = false, bool SP2 = false>
; __device__ __forceinline__ void gemm_phase(PG8_LAS unsigned char* lds, const Gemm g, const Sched& S, const Epi& E) {
;     ...
;         const bool has_next = S.next(ui + 1, nxt);
;         const char* nA = has_next ? (const char*)g.A + (size_t)nxt.pm * tstep : cA; const char* nB = has_next ? (const char*)g.Bt + (size_t)nxt.pn * tstep : cB;
;         for (int t = 0; t < nt; t += 2) {
;             const bool last = (t == nt - 2);
;             const char* a1 = cA + (size_t)(t + 1) * kstep;
;             const char* a2 = last ? nA : cA + (size_t)(t + 2) * kstep; const char* b2 = last ? nB : cB + (size_t)(t + 2) * kstep;
;             const char* a3 = a2 + kstep; const char* b3 = b2 + kstep;
;             if (last && has_next) S.a_ready(nxt);
;             if constexpr (SP2) {
;             PG8_LDB(B0, 0, 0); PG8_LDB(B1, 0, 1); PG8_SCHED; PG8_LDA(At, 0, 0); PG8_STAGE(PG8_SA(1, 1), a1 + hstep, voffA);
;             PG8_WAIT_V(8); PG8_WAIT_L(0); PG8_BAR; __builtin_amdgcn_s_setprio(1); PG8_MMA_NP(0, 0, At, B0); PG8_MMA_NP(0, 1, At, B1); __builtin_amdgcn_s_setprio(0); PG8_BAR; PG8_SCHED;
;             PG8_LDA(At, 0, 1); PG8_STAGE(PG8_SB(0, 0), b2, voffB); PG8_STAGE(PG8_SB(0, 1), b2 + hstep, voffB); PG8_STAGE(PG8_SA(0, 0), a2, voffA);
.LBB0_431:
	s_ashr_i32 s49, s48, 31
	s_lshl_b64 s[14:15], s[48:49], 19
	s_add_u32 s50, s10, s14
	s_addc_u32 s51, s29, s15
	s_and_b64 s[14:15], s[42:43], exec
	s_cselect_b32 s49, s51, s3
	s_cselect_b32 s59, s50, s2
	s_ashr_i32 s47, s46, 31
	s_lshl_b64 s[14:15], s[46:47], 19
	s_add_u32 s52, s86, s14
	s_addc_u32 s53, s87, s15
	s_and_b64 s[14:15], s[42:43], exec
	s_cselect_b32 s47, s53, s13
	s_cselect_b32 s60, s52, s12
	s_add_u32 s2, s2, 0x40080
	s_addc_u32 s3, s3, 0
	s_add_u32 s61, s12, 0x100
	s_addc_u32 s62, s13, 0
	s_mov_b32 s63, -2
	s_add_u32 s12, s2, 0xfffc0080
	s_addc_u32 s13, s3, -1
	s_add_i32 s22, 0, 0x10000
	s_cmp_eq_u32 s63, 12
	s_cselect_b32 s15, s49, s13
	s_cselect_b32 s14, s59, s12
	s_cselect_b32 s13, s47, s62
	s_cselect_b32 s12, s60, s61
	s_add_i32 s23, 0, 0x14000
	v_add_u32_e32 v154, s22, v159
	v_add_u32_e32 v162, s23, v159
	ds_read_b128 v[142:145], v154
	ds_read_b128 v[146:149], v154 offset:1024
	ds_read_b128 v[150:153], v154 offset:2048
	ds_read_b128 v[154:157], v154 offset:3072
	ds_read_b128 v[178:181], v162
	ds_read_b128 v[182:185], v162 offset:1024
	ds_read_b128 v[186:189], v162 offset:2048
	ds_read_b128 v[202:205], v162 offset:3072
	v_lshl_add_u64 v[162:163], s[2:3], 0, v[138:139]
	s_add_i32 m0, s30, 0xc000
	ds_read_b128 v[206:209], v161
	ds_read_b128 v[210:213], v161 offset:1024
	ds_read_b128 v[214:217], v161 offset:2048
	ds_read_b128 v[218:221], v161 offset:3072
	ds_read_b128 v[222:225], v161 offset:4096
	ds_read_b128 v[226:229], v161 offset:5120
	ds_read_b128 v[230:233], v161 offset:6144
	ds_read_b128 v[234:237], v161 offset:7168
	global_load_lds_dwordx4 v[162:163], off
	v_lshl_add_u64 v[162:163], s[2:3], 0, v[140:141]
	s_add_i32 m0, s30, 0xe000
	s_nop 0
	global_load_lds_dwordx4 v[162:163], off
	s_waitcnt vmcnt(8)
	s_waitcnt lgkmcnt(0)
	s_barrier
	s_waitcnt lgkmcnt(0)
	v_mfma_f32_16x16x32_bf16 v[126:129], v[142:145], v[206:209], 0
	v_mfma_f32_16x16x32_bf16 v[122:125], v[150:153], v[206:209], 0
	v_mfma_f32_16x16x32_bf16 v[118:121], v[142:145], v[214:217], 0
	v_mfma_f32_16x16x32_bf16 v[114:117], v[150:153], v[214:217], 0
	v_mfma_f32_16x16x32_bf16 v[110:113], v[142:145], v[222:225], 0
	v_mfma_f32_16x16x32_bf16 v[106:109], v[150:153], v[222:225], 0
	v_mfma_f32_16x16x32_bf16 v[102:105], v[142:145], v[230:233], 0
	v_mfma_f32_16x16x32_bf16 v[98:101], v[150:153], v[230:233], 0
	v_mfma_f32_16x16x32_bf16 v[62:65], v[178:181], v[206:209], 0
	v_mfma_f32_16x16x32_bf16 v[58:61], v[186:189], v[206:209], 0
	v_mfma_f32_16x16x32_bf16 v[54:57], v[178:181], v[214:217], 0
	v_mfma_f32_16x16x32_bf16 v[50:53], v[186:189], v[214:217], 0
	v_mfma_f32_16x16x32_bf16 v[46:49], v[178:181], v[222:225], 0
	v_mfma_f32_16x16x32_bf16 v[42:45], v[186:189], v[222:225], 0
	v_mfma_f32_16x16x32_bf16 v[38:41], v[178:181], v[230:233], 0
	v_mfma_f32_16x16x32_bf16 v[34:37], v[186:189], v[230:233], 0
	v_mfma_f32_16x16x32_bf16 v[126:129], v[146:149], v[210:213], v[126:129]
	v_mfma_f32_16x16x32_bf16 v[122:125], v[154:157], v[210:213], v[122:125]
	v_mfma_f32_16x16x32_bf16 v[118:121], v[146:149], v[218:221], v[118:121]
	v_mfma_f32_16x16x32_bf16 v[114:117], v[154:157], v[218:221], v[114:117]
	v_mfma_f32_16x16x32_bf16 v[110:113], v[146:149], v[226:229], v[110:113]
	v_mfma_f32_16x16x32_bf16 v[106:109], v[154:157], v[226:229], v[106:109]
	v_mfma_f32_16x16x32_bf16 v[102:105], v[146:149], v[234:237], v[102:105]
	v_mfma_f32_16x16x32_bf16 v[98:101], v[154:157], v[234:237], v[98:101]
	v_mfma_f32_16x16x32_bf16 v[62:65], v[182:185], v[210:213], v[62:65]
	v_mfma_f32_16x16x32_bf16 v[58:61], v[202:205], v[210:213], v[58:61]
	v_mfma_f32_16x16x32_bf16 v[54:57], v[182:185], v[218:221], v[54:57]
	v_mfma_f32_16x16x32_bf16 v[50:53], v[202:205], v[218:221], v[50:53]
	v_mfma_f32_16x16x32_bf16 v[46:49], v[182:185], v[226:229], v[46:49]
	v_mfma_f32_16x16x32_bf16 v[42:45], v[202:205], v[226:229], v[42:45]
	v_mfma_f32_16x16x32_bf16 v[38:41], v[182:185], v[234:237], v[38:41]
	v_mfma_f32_16x16x32_bf16 v[34:37], v[202:205], v[234:237], v[34:37]
	s_barrier
	s_add_i32 s22, s22, s8
	v_lshl_add_u64 v[162:163], s[12:13], 0, v[0:1]
	s_mov_b32 m0, s22
	ds_read_b128 v[206:209], v161 offset:16384
	ds_read_b128 v[210:213], v161 offset:17408
	ds_read_b128 v[214:217], v161 offset:18432
	ds_read_b128 v[218:221], v161 offset:19456
	ds_read_b128 v[222:225], v161 offset:20480
	ds_read_b128 v[226:229], v161 offset:21504
	ds_read_b128 v[230:233], v161 offset:22528
	ds_read_b128 v[234:237], v161 offset:23552
	global_load_lds_dwordx4 v[162:163], off
	s_add_i32 m0, s22, 0x2000
	s_add_u32 s64, s12, 0x40000
	v_lshl_add_u64 v[190:191], s[12:13], 0, v[130:131]
	s_addc_u32 s65, s13, 0
	s_add_i32 s22, s23, s8
	global_load_lds_dwordx4 v[190:191], off
	v_lshl_add_u64 v[238:239], s[64:65], 0, v[0:1]
	s_mov_b32 m0, s22
	v_lshl_add_u64 v[240:241], s[14:15], 0, v[132:133]
	global_load_lds_dwordx4 v[238:239], off
	v_lshl_add_u64 v[238:239], s[64:65], 0, v[130:131]
	s_add_i32 m0, s22, 0x2000
	s_nop 0
	global_load_lds_dwordx4 v[238:239], off
	v_lshl_add_u64 v[238:239], s[14:15], 0, v[134:135]
	s_mov_b32 m0, s30
	s_nop 0
	global_load_lds_dwordx4 v[238:239], off
	s_mov_b32 m0, s31
	s_nop 0
	global_load_lds_dwordx4 v[240:241], off
	s_waitcnt vmcnt(8)
	s_waitcnt lgkmcnt(0)
	s_barrier
; #define PG8_STAGE(bufoff, gbase, voff) do { _Pragma("unroll") for (int _i = 0; _i < 2; ++_i) \
;         __builtin_amdgcn_global_load_lds((const unsigned*)((const char*)(gbase) + (voff)[_i]), (PG8_LAS unsigned*)(lds + (bufoff) + ldsw + _i * 8192), 16, 0, 0); } while (0)
; #define PG8_LDA(dst, b, h) do { _Pragma("unroll") for (int m = 0; m < 4; ++m) _Pragma("unroll") for (int k = 0; k < 2; ++k) dst[m][k] = *(const PG8_LAS bf16x8*)(lds + PG8_SA(b, h) + aoff + m * 2048 + k * 1024); } while (0)
; #define PG8_LDB(dst, b, h) do { _Pragma("unroll") for (int n = 0; n < 2; ++n) _Pragma("unroll") for (int k = 0; k < 2; ++k) dst[n][k] = *(const PG8_LAS bf16x8*)(lds + PG8_SB(b, h) + boff + n * 2048 + k * 1024); } while (0)
; #define PG8_MMA_NP(ai, bj, At, Bt) do { _Pragma("unroll") for (int m = 0; m < 4; ++m) _Pragma("unroll") for (int n = 0; n < 2; ++n) _Pragma("unroll") for (int k = 0; k < 2; ++k) \
;         acc[ai][bj][m][n] = __builtin_amdgcn_mfma_f32_16x16x32_bf16(Bt[n][k], At[m][k], acc[ai][bj][m][n], 0, 0, 0); } while (0)
; #define PG8_WAIT_V(n) asm volatile("s_waitcnt vmcnt(" #n ")" ::: "memory")
; #define PG8_WAIT_L(n) asm volatile("s_waitcnt lgkmcnt(" #n ")" ::: "memory")
; #define PG8_BAR __builtin_amdgcn_s_barrier()
; #define PG8_SCHED __builtin_amdgcn_sched_barrier(0)
; template <class Epi, class Sched, bool ALIGN_EPI = false, bool SP2 = false>
; __device__ __forceinline__ void gemm_phase(PG8_LAS unsigned char* lds, const Gemm g, const Sched& S, const Epi& E) {
;     ...
;             PG8_WAIT_V(8); PG8_WAIT_L(0); PG8_BAR; __builtin_amdgcn_s_setprio(1); PG8_MMA_NP(1, 0, At, B0); PG8_MMA_NP(1, 1, At, B1); __builtin_amdgcn_s_setprio(0); PG8_BAR; PG8_SCHED;
;             PG8_LDB(B0, 1, 0); PG8_LDB(B1, 1, 1); PG8_SCHED; PG8_LDA(At, 1, 0); PG8_STAGE(PG8_SA(0, 1), a2 + hstep, voffA);
;             PG8_WAIT_V(8); PG8_WAIT_L(0); PG8_BAR; __builtin_amdgcn_s_setprio(1); PG8_MMA_NP(0, 0, At, B0); PG8_MMA_NP(0, 1, At, B1); __builtin_amdgcn_s_setprio(0); PG8_BAR; PG8_SCHED;
	s_waitcnt lgkmcnt(0)
	v_mfma_f32_16x16x32_bf16 v[94:97], v[142:145], v[206:209], 0
	v_mfma_f32_16x16x32_bf16 v[90:93], v[150:153], v[206:209], 0
	v_mfma_f32_16x16x32_bf16 v[86:89], v[142:145], v[214:217], 0
	v_mfma_f32_16x16x32_bf16 v[82:85], v[150:153], v[214:217], 0
	v_mfma_f32_16x16x32_bf16 v[78:81], v[142:145], v[222:225], 0
	v_mfma_f32_16x16x32_bf16 v[74:77], v[150:153], v[222:225], 0
	v_mfma_f32_16x16x32_bf16 v[70:73], v[142:145], v[230:233], 0
	v_mfma_f32_16x16x32_bf16 v[66:69], v[150:153], v[230:233], 0
	v_mfma_f32_16x16x32_bf16 v[30:33], v[178:181], v[206:209], 0
	v_mfma_f32_16x16x32_bf16 v[26:29], v[186:189], v[206:209], 0
	v_mfma_f32_16x16x32_bf16 v[22:25], v[178:181], v[214:217], 0
	v_mfma_f32_16x16x32_bf16 v[18:21], v[186:189], v[214:217], 0
	v_mfma_f32_16x16x32_bf16 v[14:17], v[178:181], v[222:225], 0
	v_mfma_f32_16x16x32_bf16 v[10:13], v[186:189], v[222:225], 0
	v_mfma_f32_16x16x32_bf16 v[6:9], v[178:181], v[230:233], 0
	v_mfma_f32_16x16x32_bf16 v[2:5], v[186:189], v[230:233], 0
	v_mfma_f32_16x16x32_bf16 v[94:97], v[146:149], v[210:213], v[94:97]
	v_mfma_f32_16x16x32_bf16 v[90:93], v[154:157], v[210:213], v[90:93]
	v_mfma_f32_16x16x32_bf16 v[86:89], v[146:149], v[218:221], v[86:89]
	v_mfma_f32_16x16x32_bf16 v[82:85], v[154:157], v[218:221], v[82:85]
	v_mfma_f32_16x16x32_bf16 v[78:81], v[146:149], v[226:229], v[78:81]
	v_mfma_f32_16x16x32_bf16 v[74:77], v[154:157], v[226:229], v[74:77]
	v_mfma_f32_16x16x32_bf16 v[70:73], v[146:149], v[234:237], v[70:73]
	v_mfma_f32_16x16x32_bf16 v[66:69], v[154:157], v[234:237], v[66:69]
	v_mfma_f32_16x16x32_bf16 v[30:33], v[182:185], v[210:213], v[30:33]
	v_mfma_f32_16x16x32_bf16 v[26:29], v[202:205], v[210:213], v[26:29]
	v_mfma_f32_16x16x32_bf16 v[22:25], v[182:185], v[218:221], v[22:25]
	v_mfma_f32_16x16x32_bf16 v[18:21], v[202:205], v[218:221], v[18:21]
	v_mfma_f32_16x16x32_bf16 v[14:17], v[182:185], v[226:229], v[14:17]
	v_mfma_f32_16x16x32_bf16 v[10:13], v[202:205], v[226:229], v[10:13]
	v_mfma_f32_16x16x32_bf16 v[6:9], v[182:185], v[234:237], v[6:9]
	v_mfma_f32_16x16x32_bf16 v[2:5], v[202:205], v[234:237], v[2:5]
	s_barrier
	s_add_i32 s22, 0, 0x18000
	s_add_i32 s23, 0, 0x1c000
	v_add_u32_e32 v154, s22, v159
	v_add_u32_e32 v202, s23, v159
	ds_read_b128 v[142:145], v154
	ds_read_b128 v[146:149], v154 offset:1024
	ds_read_b128 v[150:153], v154 offset:2048
	ds_read_b128 v[154:157], v154 offset:3072
	ds_read_b128 v[178:181], v202
	ds_read_b128 v[182:185], v202 offset:1024
	ds_read_b128 v[186:189], v202 offset:2048
	ds_read_b128 v[202:205], v202 offset:3072
	s_add_u32 s14, s14, 0x40000
	s_addc_u32 s15, s15, 0
	s_mov_b32 m0, s40
	v_lshl_add_u64 v[242:243], s[14:15], 0, v[134:135]
	ds_read_b128 v[206:209], v161 offset:32768
	ds_read_b128 v[210:213], v161 offset:33792
	ds_read_b128 v[214:217], v161 offset:34816
	ds_read_b128 v[218:221], v161 offset:35840
	ds_read_b128 v[222:225], v161 offset:36864
	ds_read_b128 v[226:229], v161 offset:37888
	ds_read_b128 v[230:233], v161 offset:38912
	ds_read_b128 v[234:237], v161 offset:39936
	global_load_lds_dwordx4 v[242:243], off
	v_lshl_add_u64 v[242:243], s[14:15], 0, v[132:133]
	s_mov_b32 m0, s41
	s_nop 0
	global_load_lds_dwordx4 v[242:243], off
	s_waitcnt vmcnt(8)
	s_waitcnt lgkmcnt(0)
	s_barrier
	s_waitcnt lgkmcnt(0)
	v_mfma_f32_16x16x32_bf16 v[126:129], v[142:145], v[206:209], v[126:129]
	v_mfma_f32_16x16x32_bf16 v[122:125], v[150:153], v[206:209], v[122:125]
	v_mfma_f32_16x16x32_bf16 v[118:121], v[142:145], v[214:217], v[118:121]
	v_mfma_f32_16x16x32_bf16 v[114:117], v[150:153], v[214:217], v[114:117]
	v_mfma_f32_16x16x32_bf16 v[110:113], v[142:145], v[222:225], v[110:113]
	v_mfma_f32_16x16x32_bf16 v[106:109], v[150:153], v[222:225], v[106:109]
	v_mfma_f32_16x16x32_bf16 v[102:105], v[142:145], v[230:233], v[102:105]
	v_mfma_f32_16x16x32_bf16 v[98:101], v[150:153], v[230:233], v[98:101]
	v_mfma_f32_16x16x32_bf16 v[62:65], v[178:181], v[206:209], v[62:65]
	v_mfma_f32_16x16x32_bf16 v[58:61], v[186:189], v[206:209], v[58:61]
	v_mfma_f32_16x16x32_bf16 v[54:57], v[178:181], v[214:217], v[54:57]
	v_mfma_f32_16x16x32_bf16 v[50:53], v[186:189], v[214:217], v[50:53]
	v_mfma_f32_16x16x32_bf16 v[46:49], v[178:181], v[222:225], v[46:49]
	v_mfma_f32_16x16x32_bf16 v[42:45], v[186:189], v[222:225], v[42:45]
	v_mfma_f32_16x16x32_bf16 v[38:41], v[178:181], v[230:233], v[38:41]
	v_mfma_f32_16x16x32_bf16 v[34:37], v[186:189], v[230:233], v[34:37]
	v_mfma_f32_16x16x32_bf16 v[126:129], v[146:149], v[210:213], v[126:129]
	v_mfma_f32_16x16x32_bf16 v[122:125], v[154:157], v[210:213], v[122:125]
	v_mfma_f32_16x16x32_bf16 v[118:121], v[146:149], v[218:221], v[118:121]
	v_mfma_f32_16x16x32_bf16 v[114:117], v[154:157], v[218:221], v[114:117]
	v_mfma_f32_16x16x32_bf16 v[110:113], v[146:149], v[226:229], v[110:113]
	v_mfma_f32_16x16x32_bf16 v[106:109], v[154:157], v[226:229], v[106:109]
	v_mfma_f32_16x16x32_bf16 v[102:105], v[146:149], v[234:237], v[102:105]
	v_mfma_f32_16x16x32_bf16 v[98:101], v[154:157], v[234:237], v[98:101]
	v_mfma_f32_16x16x32_bf16 v[62:65], v[182:185], v[210:213], v[62:65]
	v_mfma_f32_16x16x32_bf16 v[58:61], v[202:205], v[210:213], v[58:61]
	v_mfma_f32_16x16x32_bf16 v[54:57], v[182:185], v[218:221], v[54:57]
	v_mfma_f32_16x16x32_bf16 v[50:53], v[202:205], v[218:221], v[50:53]
	v_mfma_f32_16x16x32_bf16 v[46:49], v[182:185], v[226:229], v[46:49]
	v_mfma_f32_16x16x32_bf16 v[42:45], v[202:205], v[226:229], v[42:45]
	v_mfma_f32_16x16x32_bf16 v[38:41], v[182:185], v[234:237], v[38:41]
	v_mfma_f32_16x16x32_bf16 v[34:37], v[202:205], v[234:237], v[34:37]
	s_barrier
; #define PG8_STAGE(bufoff, gbase, voff) do { _Pragma("unroll") for (int _i = 0; _i < 2; ++_i) \
;         __builtin_amdgcn_global_load_lds((const unsigned*)((const char*)(gbase) + (voff)[_i]), (PG8_LAS unsigned*)(lds + (bufoff) + ldsw + _i * 8192), 16, 0, 0); } while (0)
; #define PG8_LDA(dst, b, h) do { _Pragma("unroll") for (int m = 0; m < 4; ++m) _Pragma("unroll") for (int k = 0; k < 2; ++k) dst[m][k] = *(const PG8_LAS bf16x8*)(lds + PG8_SA(b, h) + aoff + m * 2048 + k * 1024); } while (0)
; #define PG8_WAIT_V(n) asm volatile("s_waitcnt vmcnt(" #n ")" ::: "memory")
; template <class Epi, class Sched, bool ALIGN_EPI = false, bool SP2 = false>
; __device__ __forceinline__ void gemm_phase(PG8_LAS unsigned char* lds, const Gemm g, const Sched& S, const Epi& E) {
;     ...
;             const char* a2 = last ? nA : cA + (size_t)(t + 2) * kstep; const char* b2 = last ? nB : cB + (size_t)(t + 2) * kstep;
;             const char* a3 = a2 + kstep; const char* b3 = b2 + kstep;
;             if (last && has_next) S.a_ready(nxt);
;             if constexpr (SP2) {
;             PG8_LDB(B0, 0, 0); PG8_LDB(B1, 0, 1); PG8_SCHED; PG8_LDA(At, 0, 0); PG8_STAGE(PG8_SA(1, 1), a1 + hstep, voffA);
;             PG8_WAIT_V(8); PG8_WAIT_L(0); PG8_BAR; __builtin_amdgcn_s_setprio(1); PG8_MMA_NP(0, 0, At, B0); PG8_MMA_NP(0, 1, At, B1); __builtin_amdgcn_s_setprio(0); PG8_BAR; PG8_SCHED;
;             PG8_LDA(At, 0, 1); PG8_STAGE(PG8_SB(0, 0), b2, voffB); PG8_STAGE(PG8_SB(0, 1), b2 + hstep, voffB); PG8_STAGE(PG8_SA(0, 0), a2, voffA);
;             PG8_WAIT_V(8); PG8_WAIT_L(0); PG8_BAR; __builtin_amdgcn_s_setprio(1); PG8_MMA_NP(1, 0, At, B0); PG8_MMA_NP(1, 1, At, B1); __builtin_amdgcn_s_setprio(0); PG8_BAR; PG8_SCHED;
;             PG8_LDB(B0, 1, 0); PG8_LDB(B1, 1, 1); PG8_SCHED; PG8_LDA(At, 1, 0); PG8_STAGE(PG8_SA(0, 1), a2 + hstep, voffA);
;             PG8_WAIT_V(8); PG8_WAIT_L(0); PG8_BAR; __builtin_amdgcn_s_setprio(1); PG8_MMA_NP(0, 0, At, B0); PG8_MMA_NP(0, 1, At, B1); __builtin_amdgcn_s_setprio(0); PG8_BAR; PG8_SCHED;
;             PG8_LDA(At, 1, 1); PG8_STAGE(PG8_SB(1, 0), b3, voffB); PG8_STAGE(PG8_SB(1, 1), b3 + hstep, voffB); PG8_STAGE(PG8_SA(1, 0), a3, voffA);
;             PG8_WAIT_V(8); PG8_WAIT_L(0); PG8_BAR; __builtin_amdgcn_s_setprio(1); PG8_MMA_NP(1, 0, At, B0); PG8_MMA_NP(1, 1, At, B1); __builtin_amdgcn_s_setprio(0); PG8_BAR; PG8_SCHED;
	s_add_i32 s14, s22, s8
	v_lshl_add_u64 v[162:163], v[162:163], 0, s[20:21]
	s_mov_b32 m0, s14
	ds_read_b128 v[206:209], v161 offset:49152
	ds_read_b128 v[210:213], v161 offset:50176
	ds_read_b128 v[214:217], v161 offset:51200
	ds_read_b128 v[218:221], v161 offset:52224
	ds_read_b128 v[222:225], v161 offset:53248
	ds_read_b128 v[226:229], v161 offset:54272
	ds_read_b128 v[230:233], v161 offset:55296
	ds_read_b128 v[234:237], v161 offset:56320
	global_load_lds_dwordx4 v[162:163], off
	s_add_i32 m0, s14, 0x2000
	s_add_u32 s12, s12, 0x40080
	v_lshl_add_u64 v[162:163], v[190:191], 0, s[20:21]
	s_addc_u32 s13, s13, 0
	s_add_i32 s14, s23, s8
	global_load_lds_dwordx4 v[162:163], off
	v_lshl_add_u64 v[162:163], s[12:13], 0, v[0:1]
	s_mov_b32 m0, s14
	s_nop 0
	global_load_lds_dwordx4 v[162:163], off
	v_lshl_add_u64 v[162:163], s[12:13], 0, v[130:131]
	s_add_i32 m0, s14, 0x2000
	s_nop 0
	global_load_lds_dwordx4 v[162:163], off
	v_lshl_add_u64 v[162:163], v[238:239], 0, s[20:21]
	s_mov_b32 m0, s54
	s_nop 0
	global_load_lds_dwordx4 v[162:163], off
	v_lshl_add_u64 v[162:163], v[240:241], 0, s[20:21]
	s_mov_b32 m0, s55
	s_nop 0
	global_load_lds_dwordx4 v[162:163], off
	s_waitcnt vmcnt(8)
	s_waitcnt lgkmcnt(0)
	s_barrier
	s_waitcnt lgkmcnt(0)
	v_mfma_f32_16x16x32_bf16 v[94:97], v[142:145], v[206:209], v[94:97]
	v_mfma_f32_16x16x32_bf16 v[90:93], v[150:153], v[206:209], v[90:93]
	v_mfma_f32_16x16x32_bf16 v[86:89], v[142:145], v[214:217], v[86:89]
	v_mfma_f32_16x16x32_bf16 v[82:85], v[150:153], v[214:217], v[82:85]
	v_mfma_f32_16x16x32_bf16 v[78:81], v[142:145], v[222:225], v[78:81]
	v_mfma_f32_16x16x32_bf16 v[74:77], v[150:153], v[222:225], v[74:77]
	v_mfma_f32_16x16x32_bf16 v[70:73], v[142:145], v[230:233], v[70:73]
	v_mfma_f32_16x16x32_bf16 v[66:69], v[150:153], v[230:233], v[66:69]
	v_mfma_f32_16x16x32_bf16 v[30:33], v[178:181], v[206:209], v[30:33]
	v_mfma_f32_16x16x32_bf16 v[26:29], v[186:189], v[206:209], v[26:29]
	v_mfma_f32_16x16x32_bf16 v[22:25], v[178:181], v[214:217], v[22:25]
	v_mfma_f32_16x16x32_bf16 v[18:21], v[186:189], v[214:217], v[18:21]
	v_mfma_f32_16x16x32_bf16 v[14:17], v[178:181], v[222:225], v[14:17]
	v_mfma_f32_16x16x32_bf16 v[10:13], v[186:189], v[222:225], v[10:13]
	v_mfma_f32_16x16x32_bf16 v[6:9], v[178:181], v[230:233], v[6:9]
	v_mfma_f32_16x16x32_bf16 v[2:5], v[186:189], v[230:233], v[2:5]
	v_mfma_f32_16x16x32_bf16 v[94:97], v[146:149], v[210:213], v[94:97]
	v_mfma_f32_16x16x32_bf16 v[90:93], v[154:157], v[210:213], v[90:93]
	v_mfma_f32_16x16x32_bf16 v[86:89], v[146:149], v[218:221], v[86:89]
	v_mfma_f32_16x16x32_bf16 v[82:85], v[154:157], v[218:221], v[82:85]
	v_mfma_f32_16x16x32_bf16 v[78:81], v[146:149], v[226:229], v[78:81]
	v_mfma_f32_16x16x32_bf16 v[74:77], v[154:157], v[226:229], v[74:77]
	v_mfma_f32_16x16x32_bf16 v[70:73], v[146:149], v[234:237], v[70:73]
	v_mfma_f32_16x16x32_bf16 v[66:69], v[154:157], v[234:237], v[66:69]
	v_mfma_f32_16x16x32_bf16 v[30:33], v[182:185], v[210:213], v[30:33]
	v_mfma_f32_16x16x32_bf16 v[26:29], v[202:205], v[210:213], v[26:29]
	v_mfma_f32_16x16x32_bf16 v[22:25], v[182:185], v[218:221], v[22:25]
	v_mfma_f32_16x16x32_bf16 v[18:21], v[202:205], v[218:221], v[18:21]
	v_mfma_f32_16x16x32_bf16 v[14:17], v[182:185], v[226:229], v[14:17]
	v_mfma_f32_16x16x32_bf16 v[10:13], v[202:205], v[226:229], v[10:13]
	v_mfma_f32_16x16x32_bf16 v[6:9], v[182:185], v[234:237], v[6:9]
	v_mfma_f32_16x16x32_bf16 v[2:5], v[202:205], v[234:237], v[2:5]
	s_barrier
	s_add_i32 s63, s63, 2
	s_add_u32 s2, s2, 0x100
	s_addc_u32 s3, s3, 0
	s_add_u32 s61, s61, 0x100
	s_addc_u32 s62, s62, 0
	s_cmp_gt_u32 s63, 13
	s_cbranch_scc0 .LBB0_432
	s_branch .Lkexit_3
.LBB0_432:
	s_add_u32 s12, s2, 0xfffc0080
	s_addc_u32 s13, s3, -1
	s_add_i32 s22, 0, 0x10000
	s_cmp_eq_u32 s63, 12
	s_cselect_b32 s15, s49, s13
	s_cselect_b32 s14, s59, s12
	s_cselect_b32 s13, s47, s62
	s_cselect_b32 s12, s60, s61
	s_add_i32 s23, 0, 0x14000
	v_add_u32_e32 v154, s22, v159
	v_add_u32_e32 v162, s23, v159
	ds_read_b128 v[142:145], v154
	ds_read_b128 v[146:149], v154 offset:1024
	ds_read_b128 v[150:153], v154 offset:2048
	ds_read_b128 v[154:157], v154 offset:3072
	ds_read_b128 v[178:181], v162
	ds_read_b128 v[182:185], v162 offset:1024
	ds_read_b128 v[186:189], v162 offset:2048
	ds_read_b128 v[202:205], v162 offset:3072
	v_lshl_add_u64 v[162:163], s[2:3], 0, v[138:139]
	s_add_i32 m0, s30, 0xc000
	ds_read_b128 v[206:209], v161
	ds_read_b128 v[210:213], v161 offset:1024
	ds_read_b128 v[214:217], v161 offset:2048
	ds_read_b128 v[218:221], v161 offset:3072
	ds_read_b128 v[222:225], v161 offset:4096
	ds_read_b128 v[226:229], v161 offset:5120
	ds_read_b128 v[230:233], v161 offset:6144
	ds_read_b128 v[234:237], v161 offset:7168
	global_load_lds_dwordx4 v[162:163], off
	v_lshl_add_u64 v[162:163], s[2:3], 0, v[140:141]
	s_add_i32 m0, s30, 0xe000
	s_nop 0
	global_load_lds_dwordx4 v[162:163], off
	s_waitcnt vmcnt(8)
	s_waitcnt lgkmcnt(0)
	s_barrier
; #define PG8_STAGE(bufoff, gbase, voff) do { _Pragma("unroll") for (int _i = 0; _i < 2; ++_i) \
;         __builtin_amdgcn_global_load_lds((const unsigned*)((const char*)(gbase) + (voff)[_i]), (PG8_LAS unsigned*)(lds + (bufoff) + ldsw + _i * 8192), 16, 0, 0); } while (0)
; #define PG8_LDA(dst, b, h) do { _Pragma("unroll") for (int m = 0; m < 4; ++m) _Pragma("unroll") for (int k = 0; k < 2; ++k) dst[m][k] = *(const PG8_LAS bf16x8*)(lds + PG8_SA(b, h) + aoff + m * 2048 + k * 1024); } while (0)
; #define PG8_MMA_NP(ai, bj, At, Bt) do { _Pragma("unroll") for (int m = 0; m < 4; ++m) _Pragma("unroll") for (int n = 0; n < 2; ++n) _Pragma("unroll") for (int k = 0; k < 2; ++k) \
;         acc[ai][bj][m][n] = __builtin_amdgcn_mfma_f32_16x16x32_bf16(Bt[n][k], At[m][k], acc[ai][bj][m][n], 0, 0, 0); } while (0)
; #define PG8_WAIT_V(n) asm volatile("s_waitcnt vmcnt(" #n ")" ::: "memory")
; #define PG8_WAIT_L(n) asm volatile("s_waitcnt lgkmcnt(" #n ")" ::: "memory")
; #define PG8_BAR __builtin_amdgcn_s_barrier()
; #define PG8_SCHED __builtin_amdgcn_sched_barrier(0)
; template <class Epi, class Sched, bool ALIGN_EPI = false, bool SP2 = false>
; __device__ __forceinline__ void gemm_phase(PG8_LAS unsigned char* lds, const Gemm g, const Sched& S, const Epi& E) {
;     ...
;             PG8_WAIT_V(8); PG8_WAIT_L(0); PG8_BAR; __builtin_amdgcn_s_setprio(1); PG8_MMA_NP(0, 0, At, B0); PG8_MMA_NP(0, 1, At, B1); __builtin_amdgcn_s_setprio(0); PG8_BAR; PG8_SCHED;
;             PG8_LDA(At, 0, 1); PG8_STAGE(PG8_SB(0, 0), b2, voffB); PG8_STAGE(PG8_SB(0, 1), b2 + hstep, voffB); PG8_STAGE(PG8_SA(0, 0), a2, voffA);
;             PG8_WAIT_V(8); PG8_WAIT_L(0); PG8_BAR; __builtin_amdgcn_s_setprio(1); PG8_MMA_NP(1, 0, At, B0); PG8_MMA_NP(1, 1, At, B1); __builtin_amdgcn_s_setprio(0); PG8_BAR; PG8_SCHED;
	s_waitcnt lgkmcnt(0)
	v_mfma_f32_16x16x32_bf16 v[126:129], v[142:145], v[206:209], v[126:129]
	v_mfma_f32_16x16x32_bf16 v[122:125], v[150:153], v[206:209], v[122:125]
	v_mfma_f32_16x16x32_bf16 v[118:121], v[142:145], v[214:217], v[118:121]
	v_mfma_f32_16x16x32_bf16 v[114:117], v[150:153], v[214:217], v[114:117]
	v_mfma_f32_16x16x32_bf16 v[110:113], v[142:145], v[222:225], v[110:113]
	v_mfma_f32_16x16x32_bf16 v[106:109], v[150:153], v[222:225], v[106:109]
	v_mfma_f32_16x16x32_bf16 v[102:105], v[142:145], v[230:233], v[102:105]
	v_mfma_f32_16x16x32_bf16 v[98:101], v[150:153], v[230:233], v[98:101]
	v_mfma_f32_16x16x32_bf16 v[62:65], v[178:181], v[206:209], v[62:65]
	v_mfma_f32_16x16x32_bf16 v[58:61], v[186:189], v[206:209], v[58:61]
	v_mfma_f32_16x16x32_bf16 v[54:57], v[178:181], v[214:217], v[54:57]
	v_mfma_f32_16x16x32_bf16 v[50:53], v[186:189], v[214:217], v[50:53]
	v_mfma_f32_16x16x32_bf16 v[46:49], v[178:181], v[222:225], v[46:49]
	v_mfma_f32_16x16x32_bf16 v[42:45], v[186:189], v[222:225], v[42:45]
	v_mfma_f32_16x16x32_bf16 v[38:41], v[178:181], v[230:233], v[38:41]
	v_mfma_f32_16x16x32_bf16 v[34:37], v[186:189], v[230:233], v[34:37]
	v_mfma_f32_16x16x32_bf16 v[126:129], v[146:149], v[210:213], v[126:129]
	v_mfma_f32_16x16x32_bf16 v[122:125], v[154:157], v[210:213], v[122:125]
	v_mfma_f32_16x16x32_bf16 v[118:121], v[146:149], v[218:221], v[118:121]
	v_mfma_f32_16x16x32_bf16 v[114:117], v[154:157], v[218:221], v[114:117]
	v_mfma_f32_16x16x32_bf16 v[110:113], v[146:149], v[226:229], v[110:113]
	v_mfma_f32_16x16x32_bf16 v[106:109], v[154:157], v[226:229], v[106:109]
	v_mfma_f32_16x16x32_bf16 v[102:105], v[146:149], v[234:237], v[102:105]
	v_mfma_f32_16x16x32_bf16 v[98:101], v[154:157], v[234:237], v[98:101]
	v_mfma_f32_16x16x32_bf16 v[62:65], v[182:185], v[210:213], v[62:65]
	v_mfma_f32_16x16x32_bf16 v[58:61], v[202:205], v[210:213], v[58:61]
	v_mfma_f32_16x16x32_bf16 v[54:57], v[182:185], v[218:221], v[54:57]
	v_mfma_f32_16x16x32_bf16 v[50:53], v[202:205], v[218:221], v[50:53]
	v_mfma_f32_16x16x32_bf16 v[46:49], v[182:185], v[226:229], v[46:49]
	v_mfma_f32_16x16x32_bf16 v[42:45], v[202:205], v[226:229], v[42:45]
	v_mfma_f32_16x16x32_bf16 v[38:41], v[182:185], v[234:237], v[38:41]
	v_mfma_f32_16x16x32_bf16 v[34:37], v[202:205], v[234:237], v[34:37]
	s_barrier
	s_add_i32 s22, s22, s8
	v_lshl_add_u64 v[162:163], s[12:13], 0, v[0:1]
	s_mov_b32 m0, s22
	ds_read_b128 v[206:209], v161 offset:16384
	ds_read_b128 v[210:213], v161 offset:17408
	ds_read_b128 v[214:217], v161 offset:18432
	ds_read_b128 v[218:221], v161 offset:19456
	ds_read_b128 v[222:225], v161 offset:20480
	ds_read_b128 v[226:229], v161 offset:21504
	ds_read_b128 v[230:233], v161 offset:22528
	ds_read_b128 v[234:237], v161 offset:23552
	global_load_lds_dwordx4 v[162:163], off
	s_add_i32 m0, s22, 0x2000
	s_add_u32 s64, s12, 0x40000
	v_lshl_add_u64 v[190:191], s[12:13], 0, v[130:131]
	s_addc_u32 s65, s13, 0
	s_add_i32 s22, s23, s8
	global_load_lds_dwordx4 v[190:191], off
	v_lshl_add_u64 v[238:239], s[64:65], 0, v[0:1]
	s_mov_b32 m0, s22
	v_lshl_add_u64 v[240:241], s[14:15], 0, v[132:133]
	global_load_lds_dwordx4 v[238:239], off
	v_lshl_add_u64 v[238:239], s[64:65], 0, v[130:131]
	s_add_i32 m0, s22, 0x2000
	s_nop 0
	global_load_lds_dwordx4 v[238:239], off
	v_lshl_add_u64 v[238:239], s[14:15], 0, v[134:135]
	s_mov_b32 m0, s30
	s_nop 0
	global_load_lds_dwordx4 v[238:239], off
	s_mov_b32 m0, s31
	s_nop 0
	global_load_lds_dwordx4 v[240:241], off
	s_waitcnt vmcnt(8)
	s_waitcnt lgkmcnt(0)
	s_barrier
	s_waitcnt lgkmcnt(0)
	v_mfma_f32_16x16x32_bf16 v[94:97], v[142:145], v[206:209], v[94:97]
	v_mfma_f32_16x16x32_bf16 v[90:93], v[150:153], v[206:209], v[90:93]
	v_mfma_f32_16x16x32_bf16 v[86:89], v[142:145], v[214:217], v[86:89]
	v_mfma_f32_16x16x32_bf16 v[82:85], v[150:153], v[214:217], v[82:85]
	v_mfma_f32_16x16x32_bf16 v[78:81], v[142:145], v[222:225], v[78:81]
	v_mfma_f32_16x16x32_bf16 v[74:77], v[150:153], v[222:225], v[74:77]
	v_mfma_f32_16x16x32_bf16 v[70:73], v[142:145], v[230:233], v[70:73]
	v_mfma_f32_16x16x32_bf16 v[66:69], v[150:153], v[230:233], v[66:69]
	v_mfma_f32_16x16x32_bf16 v[30:33], v[178:181], v[206:209], v[30:33]
	v_mfma_f32_16x16x32_bf16 v[26:29], v[186:189], v[206:209], v[26:29]
	v_mfma_f32_16x16x32_bf16 v[22:25], v[178:181], v[214:217], v[22:25]
	v_mfma_f32_16x16x32_bf16 v[18:21], v[186:189], v[214:217], v[18:21]
	v_mfma_f32_16x16x32_bf16 v[14:17], v[178:181], v[222:225], v[14:17]
	v_mfma_f32_16x16x32_bf16 v[10:13], v[186:189], v[222:225], v[10:13]
	v_mfma_f32_16x16x32_bf16 v[6:9], v[178:181], v[230:233], v[6:9]
	v_mfma_f32_16x16x32_bf16 v[2:5], v[186:189], v[230:233], v[2:5]
	v_mfma_f32_16x16x32_bf16 v[94:97], v[146:149], v[210:213], v[94:97]
	v_mfma_f32_16x16x32_bf16 v[90:93], v[154:157], v[210:213], v[90:93]
	v_mfma_f32_16x16x32_bf16 v[86:89], v[146:149], v[218:221], v[86:89]
	v_mfma_f32_16x16x32_bf16 v[82:85], v[154:157], v[218:221], v[82:85]
	v_mfma_f32_16x16x32_bf16 v[78:81], v[146:149], v[226:229], v[78:81]
	v_mfma_f32_16x16x32_bf16 v[74:77], v[154:157], v[226:229], v[74:77]
	v_mfma_f32_16x16x32_bf16 v[70:73], v[146:149], v[234:237], v[70:73]
	v_mfma_f32_16x16x32_bf16 v[66:69], v[154:157], v[234:237], v[66:69]
	v_mfma_f32_16x16x32_bf16 v[30:33], v[182:185], v[210:213], v[30:33]
	v_mfma_f32_16x16x32_bf16 v[26:29], v[202:205], v[210:213], v[26:29]
	v_mfma_f32_16x16x32_bf16 v[22:25], v[182:185], v[218:221], v[22:25]
	v_mfma_f32_16x16x32_bf16 v[18:21], v[202:205], v[218:221], v[18:21]
	v_mfma_f32_16x16x32_bf16 v[14:17], v[182:185], v[226:229], v[14:17]
	v_mfma_f32_16x16x32_bf16 v[10:13], v[202:205], v[226:229], v[10:13]
	v_mfma_f32_16x16x32_bf16 v[6:9], v[182:185], v[234:237], v[6:9]
	v_mfma_f32_16x16x32_bf16 v[2:5], v[202:205], v[234:237], v[2:5]
	s_barrier
; #define PG8_STAGE(bufoff, gbase, voff) do { _Pragma("unroll") for (int _i = 0; _i < 2; ++_i) \
;         __builtin_amdgcn_global_load_lds((const unsigned*)((const char*)(gbase) + (voff)[_i]), (PG8_LAS unsigned*)(lds + (bufoff) + ldsw + _i * 8192), 16, 0, 0); } while (0)
; #define PG8_LDA(dst, b, h) do { _Pragma("unroll") for (int m = 0; m < 4; ++m) _Pragma("unroll") for (int k = 0; k < 2; ++k) dst[m][k] = *(const PG8_LAS bf16x8*)(lds + PG8_SA(b, h) + aoff + m * 2048 + k * 1024); } while (0)
; #define PG8_LDB(dst, b, h) do { _Pragma("unroll") for (int n = 0; n < 2; ++n) _Pragma("unroll") for (int k = 0; k < 2; ++k) dst[n][k] = *(const PG8_LAS bf16x8*)(lds + PG8_SB(b, h) + boff + n * 2048 + k * 1024); } while (0)
; #define PG8_MMA_NP(ai, bj, At, Bt) do { _Pragma("unroll") for (int m = 0; m < 4; ++m) _Pragma("unroll") for (int n = 0; n < 2; ++n) _Pragma("unroll") for (int k = 0; k < 2; ++k) \
;         acc[ai][bj][m][n] = __builtin_amdgcn_mfma_f32_16x16x32_bf16(Bt[n][k], At[m][k], acc[ai][bj][m][n], 0, 0, 0); } while (0)
; #define PG8_WAIT_V(n) asm volatile("s_waitcnt vmcnt(" #n ")" ::: "memory")
; #define PG8_WAIT_L(n) asm volatile("s_waitcnt lgkmcnt(" #n ")" ::: "memory")
; #define PG8_BAR __builtin_amdgcn_s_barrier()
; #define PG8_SCHED __builtin_amdgcn_sched_barrier(0)
; template <class Epi, class Sched, bool ALIGN_EPI = false, bool SP2 = false>
; __device__ __forceinline__ void gemm_phase(PG8_LAS unsigned char* lds, const Gemm g, const Sched& S, const Epi& E) {
;     ...
;             PG8_LDB(B0, 1, 0); PG8_LDB(B1, 1, 1); PG8_SCHED; PG8_LDA(At, 1, 0); PG8_STAGE(PG8_SA(0, 1), a2 + hstep, voffA);
;             PG8_WAIT_V(8); PG8_WAIT_L(0); PG8_BAR; __builtin_amdgcn_s_setprio(1); PG8_MMA_NP(0, 0, At, B0); PG8_MMA_NP(0, 1, At, B1); __builtin_amdgcn_s_setprio(0); PG8_BAR; PG8_SCHED;
;             PG8_LDA(At, 1, 1); PG8_STAGE(PG8_SB(1, 0), b3, voffB); PG8_STAGE(PG8_SB(1, 1), b3 + hstep, voffB); PG8_STAGE(PG8_SA(1, 0), a3, voffA);
;             PG8_WAIT_V(8); PG8_WAIT_L(0); PG8_BAR; __builtin_amdgcn_s_setprio(1); PG8_MMA_NP(1, 0, At, B0); PG8_MMA_NP(1, 1, At, B1); __builtin_amdgcn_s_setprio(0); PG8_BAR; PG8_SCHED;
	s_add_i32 s22, 0, 0x18000
	s_add_i32 s23, 0, 0x1c000
	v_add_u32_e32 v154, s22, v159
	v_add_u32_e32 v202, s23, v159
	ds_read_b128 v[142:145], v154
	ds_read_b128 v[146:149], v154 offset:1024
	ds_read_b128 v[150:153], v154 offset:2048
	ds_read_b128 v[154:157], v154 offset:3072
	ds_read_b128 v[178:181], v202
	ds_read_b128 v[182:185], v202 offset:1024
	ds_read_b128 v[186:189], v202 offset:2048
	ds_read_b128 v[202:205], v202 offset:3072
	s_add_u32 s14, s14, 0x40000
	s_addc_u32 s15, s15, 0
	s_mov_b32 m0, s40
	v_lshl_add_u64 v[242:243], s[14:15], 0, v[134:135]
	ds_read_b128 v[206:209], v161 offset:32768
	ds_read_b128 v[210:213], v161 offset:33792
	ds_read_b128 v[214:217], v161 offset:34816
	ds_read_b128 v[218:221], v161 offset:35840
	ds_read_b128 v[222:225], v161 offset:36864
	ds_read_b128 v[226:229], v161 offset:37888
	ds_read_b128 v[230:233], v161 offset:38912
	ds_read_b128 v[234:237], v161 offset:39936
	global_load_lds_dwordx4 v[242:243], off
	v_lshl_add_u64 v[242:243], s[14:15], 0, v[132:133]
	s_mov_b32 m0, s41
	s_nop 0
	global_load_lds_dwordx4 v[242:243], off
	s_waitcnt vmcnt(8)
	s_waitcnt lgkmcnt(0)
	s_barrier
	s_waitcnt lgkmcnt(0)
	v_mfma_f32_16x16x32_bf16 v[126:129], v[142:145], v[206:209], v[126:129]
	v_mfma_f32_16x16x32_bf16 v[122:125], v[150:153], v[206:209], v[122:125]
	v_mfma_f32_16x16x32_bf16 v[118:121], v[142:145], v[214:217], v[118:121]
	v_mfma_f32_16x16x32_bf16 v[114:117], v[150:153], v[214:217], v[114:117]
	v_mfma_f32_16x16x32_bf16 v[110:113], v[142:145], v[222:225], v[110:113]
	v_mfma_f32_16x16x32_bf16 v[106:109], v[150:153], v[222:225], v[106:109]
	v_mfma_f32_16x16x32_bf16 v[102:105], v[142:145], v[230:233], v[102:105]
	v_mfma_f32_16x16x32_bf16 v[98:101], v[150:153], v[230:233], v[98:101]
	v_mfma_f32_16x16x32_bf16 v[62:65], v[178:181], v[206:209], v[62:65]
	v_mfma_f32_16x16x32_bf16 v[58:61], v[186:189], v[206:209], v[58:61]
	v_mfma_f32_16x16x32_bf16 v[54:57], v[178:181], v[214:217], v[54:57]
	v_mfma_f32_16x16x32_bf16 v[50:53], v[186:189], v[214:217], v[50:53]
	v_mfma_f32_16x16x32_bf16 v[46:49], v[178:181], v[222:225], v[46:49]
	v_mfma_f32_16x16x32_bf16 v[42:45], v[186:189], v[222:225], v[42:45]
	v_mfma_f32_16x16x32_bf16 v[38:41], v[178:181], v[230:233], v[38:41]
	v_mfma_f32_16x16x32_bf16 v[34:37], v[186:189], v[230:233], v[34:37]
	v_mfma_f32_16x16x32_bf16 v[126:129], v[146:149], v[210:213], v[126:129]
	v_mfma_f32_16x16x32_bf16 v[122:125], v[154:157], v[210:213], v[122:125]
	v_mfma_f32_16x16x32_bf16 v[118:121], v[146:149], v[218:221], v[118:121]
	v_mfma_f32_16x16x32_bf16 v[114:117], v[154:157], v[218:221], v[114:117]
	v_mfma_f32_16x16x32_bf16 v[110:113], v[146:149], v[226:229], v[110:113]
	v_mfma_f32_16x16x32_bf16 v[106:109], v[154:157], v[226:229], v[106:109]
	v_mfma_f32_16x16x32_bf16 v[102:105], v[146:149], v[234:237], v[102:105]
	v_mfma_f32_16x16x32_bf16 v[98:101], v[154:157], v[234:237], v[98:101]
	v_mfma_f32_16x16x32_bf16 v[62:65], v[182:185], v[210:213], v[62:65]
	v_mfma_f32_16x16x32_bf16 v[58:61], v[202:205], v[210:213], v[58:61]
	v_mfma_f32_16x16x32_bf16 v[54:57], v[182:185], v[218:221], v[54:57]
	v_mfma_f32_16x16x32_bf16 v[50:53], v[202:205], v[218:221], v[50:53]
	v_mfma_f32_16x16x32_bf16 v[46:49], v[182:185], v[226:229], v[46:49]
	v_mfma_f32_16x16x32_bf16 v[42:45], v[202:205], v[226:229], v[42:45]
	v_mfma_f32_16x16x32_bf16 v[38:41], v[182:185], v[234:237], v[38:41]
	v_mfma_f32_16x16x32_bf16 v[34:37], v[202:205], v[234:237], v[34:37]
	s_barrier
	s_add_i32 s14, s22, s8
	v_lshl_add_u64 v[162:163], v[162:163], 0, s[20:21]
	s_mov_b32 m0, s14
	ds_read_b128 v[206:209], v161 offset:49152
	ds_read_b128 v[210:213], v161 offset:50176
	ds_read_b128 v[214:217], v161 offset:51200
	ds_read_b128 v[218:221], v161 offset:52224
	ds_read_b128 v[222:225], v161 offset:53248
	ds_read_b128 v[226:229], v161 offset:54272
	ds_read_b128 v[230:233], v161 offset:55296
	ds_read_b128 v[234:237], v161 offset:56320
	global_load_lds_dwordx4 v[162:163], off
	s_add_i32 m0, s14, 0x2000
	s_add_u32 s12, s12, 0x40080
	v_lshl_add_u64 v[162:163], v[190:191], 0, s[20:21]
	s_addc_u32 s13, s13, 0
	s_add_i32 s14, s23, s8
	global_load_lds_dwordx4 v[162:163], off
	v_lshl_add_u64 v[162:163], s[12:13], 0, v[0:1]
	s_mov_b32 m0, s14
	s_nop 0
	global_load_lds_dwordx4 v[162:163], off
	v_lshl_add_u64 v[162:163], s[12:13], 0, v[130:131]
	s_add_i32 m0, s14, 0x2000
	s_nop 0
	global_load_lds_dwordx4 v[162:163], off
	v_lshl_add_u64 v[162:163], v[238:239], 0, s[20:21]
	s_mov_b32 m0, s54
	s_nop 0
	global_load_lds_dwordx4 v[162:163], off
	v_lshl_add_u64 v[162:163], v[240:241], 0, s[20:21]
	s_mov_b32 m0, s55
	s_nop 0
	global_load_lds_dwordx4 v[162:163], off
	s_waitcnt vmcnt(8)
	s_waitcnt lgkmcnt(0)
	s_barrier
	s_waitcnt lgkmcnt(0)
	v_mfma_f32_16x16x32_bf16 v[94:97], v[142:145], v[206:209], v[94:97]
	v_mfma_f32_16x16x32_bf16 v[90:93], v[150:153], v[206:209], v[90:93]
	v_mfma_f32_16x16x32_bf16 v[86:89], v[142:145], v[214:217], v[86:89]
	v_mfma_f32_16x16x32_bf16 v[82:85], v[150:153], v[214:217], v[82:85]
	v_mfma_f32_16x16x32_bf16 v[78:81], v[142:145], v[222:225], v[78:81]
	v_mfma_f32_16x16x32_bf16 v[74:77], v[150:153], v[222:225], v[74:77]
	v_mfma_f32_16x16x32_bf16 v[70:73], v[142:145], v[230:233], v[70:73]
	v_mfma_f32_16x16x32_bf16 v[66:69], v[150:153], v[230:233], v[66:69]
	v_mfma_f32_16x16x32_bf16 v[30:33], v[178:181], v[206:209], v[30:33]
	v_mfma_f32_16x16x32_bf16 v[26:29], v[186:189], v[206:209], v[26:29]
	v_mfma_f32_16x16x32_bf16 v[22:25], v[178:181], v[214:217], v[22:25]
	v_mfma_f32_16x16x32_bf16 v[18:21], v[186:189], v[214:217], v[18:21]
	v_mfma_f32_16x16x32_bf16 v[14:17], v[178:181], v[222:225], v[14:17]
	v_mfma_f32_16x16x32_bf16 v[10:13], v[186:189], v[222:225], v[10:13]
	v_mfma_f32_16x16x32_bf16 v[6:9], v[178:181], v[230:233], v[6:9]
	v_mfma_f32_16x16x32_bf16 v[2:5], v[186:189], v[230:233], v[2:5]
	v_mfma_f32_16x16x32_bf16 v[94:97], v[146:149], v[210:213], v[94:97]
	v_mfma_f32_16x16x32_bf16 v[90:93], v[154:157], v[210:213], v[90:93]
	v_mfma_f32_16x16x32_bf16 v[86:89], v[146:149], v[218:221], v[86:89]
	v_mfma_f32_16x16x32_bf16 v[82:85], v[154:157], v[218:221], v[82:85]
	v_mfma_f32_16x16x32_bf16 v[78:81], v[146:149], v[226:229], v[78:81]
	v_mfma_f32_16x16x32_bf16 v[74:77], v[154:157], v[226:229], v[74:77]
	v_mfma_f32_16x16x32_bf16 v[70:73], v[146:149], v[234:237], v[70:73]
	v_mfma_f32_16x16x32_bf16 v[66:69], v[154:157], v[234:237], v[66:69]
	v_mfma_f32_16x16x32_bf16 v[30:33], v[182:185], v[210:213], v[30:33]
	v_mfma_f32_16x16x32_bf16 v[26:29], v[202:205], v[210:213], v[26:29]
	v_mfma_f32_16x16x32_bf16 v[22:25], v[182:185], v[218:221], v[22:25]
	v_mfma_f32_16x16x32_bf16 v[18:21], v[202:205], v[218:221], v[18:21]
	v_mfma_f32_16x16x32_bf16 v[14:17], v[182:185], v[226:229], v[14:17]
	v_mfma_f32_16x16x32_bf16 v[10:13], v[202:205], v[226:229], v[10:13]
	v_mfma_f32_16x16x32_bf16 v[6:9], v[182:185], v[234:237], v[6:9]
	v_mfma_f32_16x16x32_bf16 v[2:5], v[202:205], v[234:237], v[2:5]
	s_barrier
	s_add_i32 s63, s63, 2
	s_add_u32 s2, s2, 0x100
	s_addc_u32 s3, s3, 0
	s_add_u32 s61, s61, 0x100
	s_addc_u32 s62, s62, 0
	s_cmp_gt_u32 s63, 13
	s_cbranch_scc0 .LBB0_432

; #define PG8_STAGE(bufoff, gbase, voff) do { _Pragma("unroll") for (int _i = 0; _i < 2; ++_i) \
;         __builtin_amdgcn_global_load_lds((const unsigned*)((const char*)(gbase) + (voff)[_i]), (PG8_LAS unsigned*)(lds + (bufoff) + ldsw + _i * 8192), 16, 0, 0); } while (0)
; #define PG8_LDA(dst, b, h) do { _Pragma("unroll") for (int m = 0; m < 4; ++m) _Pragma("unroll") for (int k = 0; k < 2; ++k) dst[m][k] = *(const PG8_LAS bf16x8*)(lds + PG8_SA(b, h) + aoff + m * 2048 + k * 1024); } while (0)
; #define PG8_LDB(dst, b, h) do { _Pragma("unroll") for (int n = 0; n < 2; ++n) _Pragma("unroll") for (int k = 0; k < 2; ++k) dst[n][k] = *(const PG8_LAS bf16x8*)(lds + PG8_SB(b, h) + boff + n * 2048 + k * 1024); } while (0)
; #define PG8_MMA_NP(ai, bj, At, Bt) do { _Pragma("unroll") for (int m = 0; m < 4; ++m) _Pragma("unroll") for (int n = 0; n < 2; ++n) _Pragma("unroll") for (int k = 0; k < 2; ++k) \
;         acc[ai][bj][m][n] = __builtin_amdgcn_mfma_f32_16x16x32_bf16(Bt[n][k], At[m][k], acc[ai][bj][m][n], 0, 0, 0); } while (0)
; template <class Epi, class Sched, bool ALIGN_EPI = false, bool SP2 = false>
; __device__ __forceinline__ void gemm_phase(PG8_LAS unsigned char* lds, const Gemm g, const Sched& S, const Epi& E) {
;     ...
;         const bool has_next = S.next(ui + 1, nxt);
;         const char* nA = has_next ? (const char*)g.A + (size_t)nxt.pm * tstep : cA; const char* nB = has_next ? (const char*)g.Bt + (size_t)nxt.pn * tstep : cB;
;         for (int t = 0; t < nt; t += 2) {
;             const bool last = (t == nt - 2);
;             const char* a1 = cA + (size_t)(t + 1) * kstep;
;             const char* a2 = last ? nA : cA + (size_t)(t + 2) * kstep; const char* b2 = last ? nB : cB + (size_t)(t + 2) * kstep;
;             const char* a3 = a2 + kstep; const char* b3 = b2 + kstep;
;             if (last && has_next) S.a_ready(nxt);
;             if constexpr (SP2) {
;             PG8_LDB(B0, 0, 0); PG8_LDB(B1, 0, 1); PG8_SCHED; PG8_LDA(At, 0, 0); PG8_STAGE(PG8_SA(1, 1), a1 + hstep, voffA);
;             PG8_WAIT_V(8); PG8_WAIT_L(0); PG8_BAR; __builtin_amdgcn_s_setprio(1); PG8_MMA_NP(0, 0, At, B0); PG8_MMA_NP(0, 1, At, B1); __builtin_amdgcn_s_setprio(0); PG8_BAR; PG8_SCHED;
;             PG8_LDA(At, 0, 1); PG8_STAGE(PG8_SB(0, 0), b2, voffB); PG8_STAGE(PG8_SB(0, 1), b2 + hstep, voffB); PG8_STAGE(PG8_SA(0, 0), a2, voffA);
.LBB0_1015:
	s_ashr_i32 s51, s50, 31
	s_lshl_b64 s[14:15], s[50:51], 19
	s_add_u32 s52, s90, s14
	s_addc_u32 s53, s91, s15
	s_and_b64 s[14:15], s[44:45], exec
	s_cselect_b32 s29, s53, s13
	s_cselect_b32 s30, s52, s12
	s_ashr_i32 s49, s48, 31
	s_lshl_b64 s[14:15], s[48:49], 19
	s_add_u32 s54, s31, s14
	s_addc_u32 s55, s40, s15
	s_and_b64 s[14:15], s[44:45], exec
	s_cselect_b32 s49, s55, s39
	s_cselect_b32 s51, s54, s38
	s_add_u32 s12, s12, 0x40080
	s_addc_u32 s13, s13, 0
	s_add_u32 s64, s38, 0x100
	s_addc_u32 s65, s39, 0
	s_mov_b32 s66, -2
	s_waitcnt lgkmcnt(0)
	s_add_u32 s14, s12, 0xfffc0080
	s_addc_u32 s15, s13, -1
	s_add_i32 s22, 0, 0x10000
	s_cmp_eq_u32 s66, 12
	s_cselect_b32 s39, s29, s15
	s_cselect_b32 s38, s30, s14
	v_add_u32_e32 v144, s22, v147
	s_cselect_b32 s15, s49, s65
	s_cselect_b32 s14, s51, s64
	s_add_i32 s67, 0, 0x14000
	ds_read_b128 v[140:143], v144
	ds_read_b128 v[150:153], v144 offset:1024
	ds_read_b128 v[154:157], v144 offset:2048
	ds_read_b128 v[158:161], v144 offset:3072
	v_add_u32_e32 v144, s67, v147
	ds_read_b128 v[178:181], v144
	ds_read_b128 v[182:185], v144 offset:1024
	ds_read_b128 v[186:189], v144 offset:2048
	ds_read_b128 v[202:205], v144 offset:3072
	v_lshl_add_u64 v[144:145], s[12:13], 0, v[136:137]
	s_add_i32 m0, s56, 0xc000
	ds_read_b128 v[206:209], v149
	ds_read_b128 v[210:213], v149 offset:1024
	ds_read_b128 v[214:217], v149 offset:2048
	ds_read_b128 v[218:221], v149 offset:3072
	ds_read_b128 v[222:225], v149 offset:4096
	ds_read_b128 v[226:229], v149 offset:5120
	ds_read_b128 v[230:233], v149 offset:6144
	ds_read_b128 v[234:237], v149 offset:7168
	global_load_lds_dwordx4 v[144:145], off
	v_lshl_add_u64 v[144:145], s[12:13], 0, v[138:139]
	s_add_i32 m0, s56, 0xe000
	s_nop 0
	global_load_lds_dwordx4 v[144:145], off
	s_waitcnt vmcnt(8)
	s_waitcnt lgkmcnt(0)
	s_barrier
	s_waitcnt lgkmcnt(0)
	v_mfma_f32_16x16x32_bf16 v[126:129], v[140:143], v[206:209], 0
	v_mfma_f32_16x16x32_bf16 v[122:125], v[154:157], v[206:209], 0
	v_mfma_f32_16x16x32_bf16 v[110:113], v[140:143], v[214:217], 0
	v_mfma_f32_16x16x32_bf16 v[106:109], v[154:157], v[214:217], 0
	v_mfma_f32_16x16x32_bf16 v[94:97], v[140:143], v[222:225], 0
	v_mfma_f32_16x16x32_bf16 v[90:93], v[154:157], v[222:225], 0
	v_mfma_f32_16x16x32_bf16 v[78:81], v[140:143], v[230:233], 0
	v_mfma_f32_16x16x32_bf16 v[74:77], v[154:157], v[230:233], 0
	v_mfma_f32_16x16x32_bf16 v[118:121], v[178:181], v[206:209], 0
	v_mfma_f32_16x16x32_bf16 v[114:117], v[186:189], v[206:209], 0
	v_mfma_f32_16x16x32_bf16 v[102:105], v[178:181], v[214:217], 0
	v_mfma_f32_16x16x32_bf16 v[98:101], v[186:189], v[214:217], 0
	v_mfma_f32_16x16x32_bf16 v[86:89], v[178:181], v[222:225], 0
	v_mfma_f32_16x16x32_bf16 v[82:85], v[186:189], v[222:225], 0
	v_mfma_f32_16x16x32_bf16 v[70:73], v[178:181], v[230:233], 0
	v_mfma_f32_16x16x32_bf16 v[66:69], v[186:189], v[230:233], 0
	v_mfma_f32_16x16x32_bf16 v[126:129], v[150:153], v[210:213], v[126:129]
	v_mfma_f32_16x16x32_bf16 v[122:125], v[158:161], v[210:213], v[122:125]
	v_mfma_f32_16x16x32_bf16 v[110:113], v[150:153], v[218:221], v[110:113]
	v_mfma_f32_16x16x32_bf16 v[106:109], v[158:161], v[218:221], v[106:109]
	v_mfma_f32_16x16x32_bf16 v[94:97], v[150:153], v[226:229], v[94:97]
	v_mfma_f32_16x16x32_bf16 v[90:93], v[158:161], v[226:229], v[90:93]
	v_mfma_f32_16x16x32_bf16 v[78:81], v[150:153], v[234:237], v[78:81]
	v_mfma_f32_16x16x32_bf16 v[74:77], v[158:161], v[234:237], v[74:77]
	v_mfma_f32_16x16x32_bf16 v[118:121], v[182:185], v[210:213], v[118:121]
	v_mfma_f32_16x16x32_bf16 v[114:117], v[202:205], v[210:213], v[114:117]
	v_mfma_f32_16x16x32_bf16 v[102:105], v[182:185], v[218:221], v[102:105]
	v_mfma_f32_16x16x32_bf16 v[98:101], v[202:205], v[218:221], v[98:101]
	v_mfma_f32_16x16x32_bf16 v[86:89], v[182:185], v[226:229], v[86:89]
	v_mfma_f32_16x16x32_bf16 v[82:85], v[202:205], v[226:229], v[82:85]
	v_mfma_f32_16x16x32_bf16 v[70:73], v[182:185], v[234:237], v[70:73]
	v_mfma_f32_16x16x32_bf16 v[66:69], v[202:205], v[234:237], v[66:69]
	s_barrier
	s_add_i32 s22, s22, s41
	v_lshl_add_u64 v[144:145], s[14:15], 0, v[0:1]
	s_mov_b32 m0, s22
	ds_read_b128 v[206:209], v149 offset:16384
	ds_read_b128 v[210:213], v149 offset:17408
	ds_read_b128 v[214:217], v149 offset:18432
	ds_read_b128 v[218:221], v149 offset:19456
	ds_read_b128 v[222:225], v149 offset:20480
	ds_read_b128 v[226:229], v149 offset:21504
	ds_read_b128 v[230:233], v149 offset:22528
	ds_read_b128 v[234:237], v149 offset:23552
	global_load_lds_dwordx4 v[144:145], off
	s_add_i32 m0, s22, 0x2000
	s_add_u32 s22, s14, 0x40000
	v_lshl_add_u64 v[162:163], s[14:15], 0, v[130:131]
	s_addc_u32 s23, s15, 0
	s_add_i32 s67, s67, s41
	global_load_lds_dwordx4 v[162:163], off
	v_lshl_add_u64 v[190:191], s[22:23], 0, v[0:1]
	s_mov_b32 m0, s67
	v_lshl_add_u64 v[238:239], s[38:39], 0, v[132:133]
	global_load_lds_dwordx4 v[190:191], off
	v_lshl_add_u64 v[190:191], s[22:23], 0, v[130:131]
	s_add_i32 m0, s67, 0x2000
	s_nop 0
	global_load_lds_dwordx4 v[190:191], off
	v_lshl_add_u64 v[190:191], s[38:39], 0, v[134:135]
	s_mov_b32 m0, s56
	s_nop 0
	global_load_lds_dwordx4 v[190:191], off
	s_mov_b32 m0, s57
	s_nop 0
	global_load_lds_dwordx4 v[238:239], off
	s_waitcnt vmcnt(8)
	s_waitcnt lgkmcnt(0)
	s_barrier
; #define PG8_STAGE(bufoff, gbase, voff) do { _Pragma("unroll") for (int _i = 0; _i < 2; ++_i) \
;         __builtin_amdgcn_global_load_lds((const unsigned*)((const char*)(gbase) + (voff)[_i]), (PG8_LAS unsigned*)(lds + (bufoff) + ldsw + _i * 8192), 16, 0, 0); } while (0)
; #define PG8_LDA(dst, b, h) do { _Pragma("unroll") for (int m = 0; m < 4; ++m) _Pragma("unroll") for (int k = 0; k < 2; ++k) dst[m][k] = *(const PG8_LAS bf16x8*)(lds + PG8_SA(b, h) + aoff + m * 2048 + k * 1024); } while (0)
; #define PG8_LDB(dst, b, h) do { _Pragma("unroll") for (int n = 0; n < 2; ++n) _Pragma("unroll") for (int k = 0; k < 2; ++k) dst[n][k] = *(const PG8_LAS bf16x8*)(lds + PG8_SB(b, h) + boff + n * 2048 + k * 1024); } while (0)
; #define PG8_MMA_NP(ai, bj, At, Bt) do { _Pragma("unroll") for (int m = 0; m < 4; ++m) _Pragma("unroll") for (int n = 0; n < 2; ++n) _Pragma("unroll") for (int k = 0; k < 2; ++k) \
;         acc[ai][bj][m][n] = __builtin_amdgcn_mfma_f32_16x16x32_bf16(Bt[n][k], At[m][k], acc[ai][bj][m][n], 0, 0, 0); } while (0)
; #define PG8_WAIT_V(n) asm volatile("s_waitcnt vmcnt(" #n ")" ::: "memory")
; #define PG8_WAIT_L(n) asm volatile("s_waitcnt lgkmcnt(" #n ")" ::: "memory")
; #define PG8_BAR __builtin_amdgcn_s_barrier()
; #define PG8_SCHED __builtin_amdgcn_sched_barrier(0)
; template <class Epi, class Sched, bool ALIGN_EPI = false, bool SP2 = false>
; __device__ __forceinline__ void gemm_phase(PG8_LAS unsigned char* lds, const Gemm g, const Sched& S, const Epi& E) {
;     ...
;             PG8_WAIT_V(8); PG8_WAIT_L(0); PG8_BAR; __builtin_amdgcn_s_setprio(1); PG8_MMA_NP(1, 0, At, B0); PG8_MMA_NP(1, 1, At, B1); __builtin_amdgcn_s_setprio(0); PG8_BAR; PG8_SCHED;
;             PG8_LDB(B0, 1, 0); PG8_LDB(B1, 1, 1); PG8_SCHED; PG8_LDA(At, 1, 0); PG8_STAGE(PG8_SA(0, 1), a2 + hstep, voffA);
;             PG8_WAIT_V(8); PG8_WAIT_L(0); PG8_BAR; __builtin_amdgcn_s_setprio(1); PG8_MMA_NP(0, 0, At, B0); PG8_MMA_NP(0, 1, At, B1); __builtin_amdgcn_s_setprio(0); PG8_BAR; PG8_SCHED;
	s_waitcnt lgkmcnt(0)
	v_mfma_f32_16x16x32_bf16 v[62:65], v[140:143], v[206:209], 0
	v_mfma_f32_16x16x32_bf16 v[58:61], v[154:157], v[206:209], 0
	v_mfma_f32_16x16x32_bf16 v[46:49], v[140:143], v[214:217], 0
	v_mfma_f32_16x16x32_bf16 v[42:45], v[154:157], v[214:217], 0
	v_mfma_f32_16x16x32_bf16 v[30:33], v[140:143], v[222:225], 0
	v_mfma_f32_16x16x32_bf16 v[26:29], v[154:157], v[222:225], 0
	v_mfma_f32_16x16x32_bf16 v[14:17], v[140:143], v[230:233], 0
	v_mfma_f32_16x16x32_bf16 v[10:13], v[154:157], v[230:233], 0
	v_mfma_f32_16x16x32_bf16 v[54:57], v[178:181], v[206:209], 0
	v_mfma_f32_16x16x32_bf16 v[50:53], v[186:189], v[206:209], 0
	v_mfma_f32_16x16x32_bf16 v[38:41], v[178:181], v[214:217], 0
	v_mfma_f32_16x16x32_bf16 v[34:37], v[186:189], v[214:217], 0
	v_mfma_f32_16x16x32_bf16 v[22:25], v[178:181], v[222:225], 0
	v_mfma_f32_16x16x32_bf16 v[18:21], v[186:189], v[222:225], 0
	v_mfma_f32_16x16x32_bf16 v[6:9], v[178:181], v[230:233], 0
	v_mfma_f32_16x16x32_bf16 v[2:5], v[186:189], v[230:233], 0
	v_mfma_f32_16x16x32_bf16 v[62:65], v[150:153], v[210:213], v[62:65]
	v_mfma_f32_16x16x32_bf16 v[58:61], v[158:161], v[210:213], v[58:61]
	v_mfma_f32_16x16x32_bf16 v[46:49], v[150:153], v[218:221], v[46:49]
	v_mfma_f32_16x16x32_bf16 v[42:45], v[158:161], v[218:221], v[42:45]
	v_mfma_f32_16x16x32_bf16 v[30:33], v[150:153], v[226:229], v[30:33]
	v_mfma_f32_16x16x32_bf16 v[26:29], v[158:161], v[226:229], v[26:29]
	v_mfma_f32_16x16x32_bf16 v[14:17], v[150:153], v[234:237], v[14:17]
	v_mfma_f32_16x16x32_bf16 v[10:13], v[158:161], v[234:237], v[10:13]
	v_mfma_f32_16x16x32_bf16 v[54:57], v[182:185], v[210:213], v[54:57]
	v_mfma_f32_16x16x32_bf16 v[50:53], v[202:205], v[210:213], v[50:53]
	v_mfma_f32_16x16x32_bf16 v[38:41], v[182:185], v[218:221], v[38:41]
	v_mfma_f32_16x16x32_bf16 v[34:37], v[202:205], v[218:221], v[34:37]
	v_mfma_f32_16x16x32_bf16 v[22:25], v[182:185], v[226:229], v[22:25]
	v_mfma_f32_16x16x32_bf16 v[18:21], v[202:205], v[226:229], v[18:21]
	v_mfma_f32_16x16x32_bf16 v[6:9], v[182:185], v[234:237], v[6:9]
	v_mfma_f32_16x16x32_bf16 v[2:5], v[202:205], v[234:237], v[2:5]
	s_barrier
	s_add_i32 s67, 0, 0x18000
	s_add_i32 s68, 0, 0x1c000
	v_add_u32_e32 v158, s67, v147
	v_add_u32_e32 v202, s68, v147
	ds_read_b128 v[140:143], v158
	ds_read_b128 v[150:153], v158 offset:1024
	ds_read_b128 v[154:157], v158 offset:2048
	ds_read_b128 v[158:161], v158 offset:3072
	ds_read_b128 v[178:181], v202
	ds_read_b128 v[182:185], v202 offset:1024
	ds_read_b128 v[186:189], v202 offset:2048
	ds_read_b128 v[202:205], v202 offset:3072
	s_add_u32 s22, s38, 0x40000
	s_addc_u32 s23, s39, 0
	s_mov_b32 m0, s58
	v_lshl_add_u64 v[240:241], s[22:23], 0, v[134:135]
	ds_read_b128 v[206:209], v149 offset:32768
	ds_read_b128 v[210:213], v149 offset:33792
	ds_read_b128 v[214:217], v149 offset:34816
	ds_read_b128 v[218:221], v149 offset:35840
	ds_read_b128 v[222:225], v149 offset:36864
	ds_read_b128 v[226:229], v149 offset:37888
	ds_read_b128 v[230:233], v149 offset:38912
	ds_read_b128 v[234:237], v149 offset:39936
	global_load_lds_dwordx4 v[240:241], off
	v_lshl_add_u64 v[240:241], s[22:23], 0, v[132:133]
	s_mov_b32 m0, s59
	s_nop 0
	global_load_lds_dwordx4 v[240:241], off
	s_waitcnt vmcnt(8)
	s_waitcnt lgkmcnt(0)
	s_barrier
	s_waitcnt lgkmcnt(0)
	v_mfma_f32_16x16x32_bf16 v[126:129], v[140:143], v[206:209], v[126:129]
	v_mfma_f32_16x16x32_bf16 v[122:125], v[154:157], v[206:209], v[122:125]
	v_mfma_f32_16x16x32_bf16 v[110:113], v[140:143], v[214:217], v[110:113]
	v_mfma_f32_16x16x32_bf16 v[106:109], v[154:157], v[214:217], v[106:109]
	v_mfma_f32_16x16x32_bf16 v[94:97], v[140:143], v[222:225], v[94:97]
	v_mfma_f32_16x16x32_bf16 v[90:93], v[154:157], v[222:225], v[90:93]
	v_mfma_f32_16x16x32_bf16 v[78:81], v[140:143], v[230:233], v[78:81]
	v_mfma_f32_16x16x32_bf16 v[74:77], v[154:157], v[230:233], v[74:77]
	v_mfma_f32_16x16x32_bf16 v[118:121], v[178:181], v[206:209], v[118:121]
	v_mfma_f32_16x16x32_bf16 v[114:117], v[186:189], v[206:209], v[114:117]
	v_mfma_f32_16x16x32_bf16 v[102:105], v[178:181], v[214:217], v[102:105]
	v_mfma_f32_16x16x32_bf16 v[98:101], v[186:189], v[214:217], v[98:101]
	v_mfma_f32_16x16x32_bf16 v[86:89], v[178:181], v[222:225], v[86:89]
	v_mfma_f32_16x16x32_bf16 v[82:85], v[186:189], v[222:225], v[82:85]
	v_mfma_f32_16x16x32_bf16 v[70:73], v[178:181], v[230:233], v[70:73]
	v_mfma_f32_16x16x32_bf16 v[66:69], v[186:189], v[230:233], v[66:69]
	v_mfma_f32_16x16x32_bf16 v[126:129], v[150:153], v[210:213], v[126:129]
	v_mfma_f32_16x16x32_bf16 v[122:125], v[158:161], v[210:213], v[122:125]
	v_mfma_f32_16x16x32_bf16 v[110:113], v[150:153], v[218:221], v[110:113]
	v_mfma_f32_16x16x32_bf16 v[106:109], v[158:161], v[218:221], v[106:109]
	v_mfma_f32_16x16x32_bf16 v[94:97], v[150:153], v[226:229], v[94:97]
	v_mfma_f32_16x16x32_bf16 v[90:93], v[158:161], v[226:229], v[90:93]
	v_mfma_f32_16x16x32_bf16 v[78:81], v[150:153], v[234:237], v[78:81]
	v_mfma_f32_16x16x32_bf16 v[74:77], v[158:161], v[234:237], v[74:77]
	v_mfma_f32_16x16x32_bf16 v[118:121], v[182:185], v[210:213], v[118:121]
	v_mfma_f32_16x16x32_bf16 v[114:117], v[202:205], v[210:213], v[114:117]
	v_mfma_f32_16x16x32_bf16 v[102:105], v[182:185], v[218:221], v[102:105]
	v_mfma_f32_16x16x32_bf16 v[98:101], v[202:205], v[218:221], v[98:101]
	v_mfma_f32_16x16x32_bf16 v[86:89], v[182:185], v[226:229], v[86:89]
	v_mfma_f32_16x16x32_bf16 v[82:85], v[202:205], v[226:229], v[82:85]
	v_mfma_f32_16x16x32_bf16 v[70:73], v[182:185], v[234:237], v[70:73]
	v_mfma_f32_16x16x32_bf16 v[66:69], v[202:205], v[234:237], v[66:69]
	s_barrier
; #define PG8_STAGE(bufoff, gbase, voff) do { _Pragma("unroll") for (int _i = 0; _i < 2; ++_i) \
;         __builtin_amdgcn_global_load_lds((const unsigned*)((const char*)(gbase) + (voff)[_i]), (PG8_LAS unsigned*)(lds + (bufoff) + ldsw + _i * 8192), 16, 0, 0); } while (0)
; #define PG8_LDA(dst, b, h) do { _Pragma("unroll") for (int m = 0; m < 4; ++m) _Pragma("unroll") for (int k = 0; k < 2; ++k) dst[m][k] = *(const PG8_LAS bf16x8*)(lds + PG8_SA(b, h) + aoff + m * 2048 + k * 1024); } while (0)
; #define PG8_WAIT_V(n) asm volatile("s_waitcnt vmcnt(" #n ")" ::: "memory")
; template <class Epi, class Sched, bool ALIGN_EPI = false, bool SP2 = false>
; __device__ __forceinline__ void gemm_phase(PG8_LAS unsigned char* lds, const Gemm g, const Sched& S, const Epi& E) {
;     ...
;             const char* a2 = last ? nA : cA + (size_t)(t + 2) * kstep; const char* b2 = last ? nB : cB + (size_t)(t + 2) * kstep;
;             const char* a3 = a2 + kstep; const char* b3 = b2 + kstep;
;             if (last && has_next) S.a_ready(nxt);
;             if constexpr (SP2) {
;             PG8_LDB(B0, 0, 0); PG8_LDB(B1, 0, 1); PG8_SCHED; PG8_LDA(At, 0, 0); PG8_STAGE(PG8_SA(1, 1), a1 + hstep, voffA);
;             PG8_WAIT_V(8); PG8_WAIT_L(0); PG8_BAR; __builtin_amdgcn_s_setprio(1); PG8_MMA_NP(0, 0, At, B0); PG8_MMA_NP(0, 1, At, B1); __builtin_amdgcn_s_setprio(0); PG8_BAR; PG8_SCHED;
;             PG8_LDA(At, 0, 1); PG8_STAGE(PG8_SB(0, 0), b2, voffB); PG8_STAGE(PG8_SB(0, 1), b2 + hstep, voffB); PG8_STAGE(PG8_SA(0, 0), a2, voffA);
;             PG8_WAIT_V(8); PG8_WAIT_L(0); PG8_BAR; __builtin_amdgcn_s_setprio(1); PG8_MMA_NP(1, 0, At, B0); PG8_MMA_NP(1, 1, At, B1); __builtin_amdgcn_s_setprio(0); PG8_BAR; PG8_SCHED;
;             PG8_LDB(B0, 1, 0); PG8_LDB(B1, 1, 1); PG8_SCHED; PG8_LDA(At, 1, 0); PG8_STAGE(PG8_SA(0, 1), a2 + hstep, voffA);
;             PG8_WAIT_V(8); PG8_WAIT_L(0); PG8_BAR; __builtin_amdgcn_s_setprio(1); PG8_MMA_NP(0, 0, At, B0); PG8_MMA_NP(0, 1, At, B1); __builtin_amdgcn_s_setprio(0); PG8_BAR; PG8_SCHED;
;             PG8_LDA(At, 1, 1); PG8_STAGE(PG8_SB(1, 0), b3, voffB); PG8_STAGE(PG8_SB(1, 1), b3 + hstep, voffB); PG8_STAGE(PG8_SA(1, 0), a3, voffA);
;             PG8_WAIT_V(8); PG8_WAIT_L(0); PG8_BAR; __builtin_amdgcn_s_setprio(1); PG8_MMA_NP(1, 0, At, B0); PG8_MMA_NP(1, 1, At, B1); __builtin_amdgcn_s_setprio(0); PG8_BAR; PG8_SCHED;
	s_add_i32 s22, s67, s41
	v_lshl_add_u64 v[144:145], v[144:145], 0, s[20:21]
	s_mov_b32 m0, s22
	ds_read_b128 v[206:209], v149 offset:49152
	ds_read_b128 v[210:213], v149 offset:50176
	ds_read_b128 v[214:217], v149 offset:51200
	ds_read_b128 v[218:221], v149 offset:52224
	ds_read_b128 v[222:225], v149 offset:53248
	ds_read_b128 v[226:229], v149 offset:54272
	ds_read_b128 v[230:233], v149 offset:55296
	ds_read_b128 v[234:237], v149 offset:56320
	global_load_lds_dwordx4 v[144:145], off
	s_add_i32 m0, s22, 0x2000
	s_add_u32 s14, s14, 0x40080
	v_lshl_add_u64 v[144:145], v[162:163], 0, s[20:21]
	s_addc_u32 s15, s15, 0
	s_add_i32 s22, s68, s41
	global_load_lds_dwordx4 v[144:145], off
	v_lshl_add_u64 v[144:145], s[14:15], 0, v[0:1]
	s_mov_b32 m0, s22
	s_nop 0
	global_load_lds_dwordx4 v[144:145], off
	v_lshl_add_u64 v[144:145], s[14:15], 0, v[130:131]
	s_add_i32 m0, s22, 0x2000
	s_nop 0
	global_load_lds_dwordx4 v[144:145], off
	v_lshl_add_u64 v[144:145], v[190:191], 0, s[20:21]
	s_mov_b32 m0, s61
	s_nop 0
	global_load_lds_dwordx4 v[144:145], off
	v_lshl_add_u64 v[144:145], v[238:239], 0, s[20:21]
	s_mov_b32 m0, s62
	s_nop 0
	global_load_lds_dwordx4 v[144:145], off
	s_waitcnt vmcnt(8)
	s_waitcnt lgkmcnt(0)
	s_barrier
	s_waitcnt lgkmcnt(0)
	v_mfma_f32_16x16x32_bf16 v[62:65], v[140:143], v[206:209], v[62:65]
	v_mfma_f32_16x16x32_bf16 v[58:61], v[154:157], v[206:209], v[58:61]
	v_mfma_f32_16x16x32_bf16 v[46:49], v[140:143], v[214:217], v[46:49]
	v_mfma_f32_16x16x32_bf16 v[42:45], v[154:157], v[214:217], v[42:45]
	v_mfma_f32_16x16x32_bf16 v[30:33], v[140:143], v[222:225], v[30:33]
	v_mfma_f32_16x16x32_bf16 v[26:29], v[154:157], v[222:225], v[26:29]
	v_mfma_f32_16x16x32_bf16 v[14:17], v[140:143], v[230:233], v[14:17]
	v_mfma_f32_16x16x32_bf16 v[10:13], v[154:157], v[230:233], v[10:13]
	v_mfma_f32_16x16x32_bf16 v[54:57], v[178:181], v[206:209], v[54:57]
	v_mfma_f32_16x16x32_bf16 v[50:53], v[186:189], v[206:209], v[50:53]
	v_mfma_f32_16x16x32_bf16 v[38:41], v[178:181], v[214:217], v[38:41]
	v_mfma_f32_16x16x32_bf16 v[34:37], v[186:189], v[214:217], v[34:37]
	v_mfma_f32_16x16x32_bf16 v[22:25], v[178:181], v[222:225], v[22:25]
	v_mfma_f32_16x16x32_bf16 v[18:21], v[186:189], v[222:225], v[18:21]
	v_mfma_f32_16x16x32_bf16 v[6:9], v[178:181], v[230:233], v[6:9]
	v_mfma_f32_16x16x32_bf16 v[2:5], v[186:189], v[230:233], v[2:5]
	v_mfma_f32_16x16x32_bf16 v[62:65], v[150:153], v[210:213], v[62:65]
	v_mfma_f32_16x16x32_bf16 v[58:61], v[158:161], v[210:213], v[58:61]
	v_mfma_f32_16x16x32_bf16 v[46:49], v[150:153], v[218:221], v[46:49]
	v_mfma_f32_16x16x32_bf16 v[42:45], v[158:161], v[218:221], v[42:45]
	v_mfma_f32_16x16x32_bf16 v[30:33], v[150:153], v[226:229], v[30:33]
	v_mfma_f32_16x16x32_bf16 v[26:29], v[158:161], v[226:229], v[26:29]
	v_mfma_f32_16x16x32_bf16 v[14:17], v[150:153], v[234:237], v[14:17]
	v_mfma_f32_16x16x32_bf16 v[10:13], v[158:161], v[234:237], v[10:13]
	v_mfma_f32_16x16x32_bf16 v[54:57], v[182:185], v[210:213], v[54:57]
	v_mfma_f32_16x16x32_bf16 v[50:53], v[202:205], v[210:213], v[50:53]
	v_mfma_f32_16x16x32_bf16 v[38:41], v[182:185], v[218:221], v[38:41]
	v_mfma_f32_16x16x32_bf16 v[34:37], v[202:205], v[218:221], v[34:37]
	v_mfma_f32_16x16x32_bf16 v[22:25], v[182:185], v[226:229], v[22:25]
	v_mfma_f32_16x16x32_bf16 v[18:21], v[202:205], v[226:229], v[18:21]
	v_mfma_f32_16x16x32_bf16 v[6:9], v[182:185], v[234:237], v[6:9]
	v_mfma_f32_16x16x32_bf16 v[2:5], v[202:205], v[234:237], v[2:5]
	s_barrier
	s_add_i32 s66, s66, 2
	s_add_u32 s12, s12, 0x100
	s_addc_u32 s13, s13, 0
	s_add_u32 s64, s64, 0x100
	s_addc_u32 s65, s65, 0
	s_cmp_gt_u32 s66, 13
	s_cbranch_scc0 .LBB0_1016
	s_branch .Lkexit_4
.LBB0_1016:
	s_add_u32 s14, s12, 0xfffc0080
	s_addc_u32 s15, s13, -1
	s_add_i32 s22, 0, 0x10000
	s_cmp_eq_u32 s66, 12
	s_cselect_b32 s39, s29, s15
	s_cselect_b32 s38, s30, s14
	v_add_u32_e32 v144, s22, v147
	s_cselect_b32 s15, s49, s65
	s_cselect_b32 s14, s51, s64
	s_add_i32 s67, 0, 0x14000
	ds_read_b128 v[140:143], v144
	ds_read_b128 v[150:153], v144 offset:1024
	ds_read_b128 v[154:157], v144 offset:2048
	ds_read_b128 v[158:161], v144 offset:3072
	v_add_u32_e32 v144, s67, v147
	ds_read_b128 v[178:181], v144
	ds_read_b128 v[182:185], v144 offset:1024
	ds_read_b128 v[186:189], v144 offset:2048
	ds_read_b128 v[202:205], v144 offset:3072
	v_lshl_add_u64 v[144:145], s[12:13], 0, v[136:137]
	s_add_i32 m0, s56, 0xc000
	ds_read_b128 v[206:209], v149
	ds_read_b128 v[210:213], v149 offset:1024
	ds_read_b128 v[214:217], v149 offset:2048
	ds_read_b128 v[218:221], v149 offset:3072
	ds_read_b128 v[222:225], v149 offset:4096
	ds_read_b128 v[226:229], v149 offset:5120
	ds_read_b128 v[230:233], v149 offset:6144
	ds_read_b128 v[234:237], v149 offset:7168
	global_load_lds_dwordx4 v[144:145], off
	v_lshl_add_u64 v[144:145], s[12:13], 0, v[138:139]
	s_add_i32 m0, s56, 0xe000
	s_nop 0
	global_load_lds_dwordx4 v[144:145], off
	s_waitcnt vmcnt(8)
	s_waitcnt lgkmcnt(0)
	s_barrier
; #define PG8_STAGE(bufoff, gbase, voff) do { _Pragma("unroll") for (int _i = 0; _i < 2; ++_i) \
;         __builtin_amdgcn_global_load_lds((const unsigned*)((const char*)(gbase) + (voff)[_i]), (PG8_LAS unsigned*)(lds + (bufoff) + ldsw + _i * 8192), 16, 0, 0); } while (0)
; #define PG8_LDA(dst, b, h) do { _Pragma("unroll") for (int m = 0; m < 4; ++m) _Pragma("unroll") for (int k = 0; k < 2; ++k) dst[m][k] = *(const PG8_LAS bf16x8*)(lds + PG8_SA(b, h) + aoff + m * 2048 + k * 1024); } while (0)
; #define PG8_MMA_NP(ai, bj, At, Bt) do { _Pragma("unroll") for (int m = 0; m < 4; ++m) _Pragma("unroll") for (int n = 0; n < 2; ++n) _Pragma("unroll") for (int k = 0; k < 2; ++k) \
;         acc[ai][bj][m][n] = __builtin_amdgcn_mfma_f32_16x16x32_bf16(Bt[n][k], At[m][k], acc[ai][bj][m][n], 0, 0, 0); } while (0)
; #define PG8_WAIT_V(n) asm volatile("s_waitcnt vmcnt(" #n ")" ::: "memory")
; #define PG8_WAIT_L(n) asm volatile("s_waitcnt lgkmcnt(" #n ")" ::: "memory")
; #define PG8_BAR __builtin_amdgcn_s_barrier()
; #define PG8_SCHED __builtin_amdgcn_sched_barrier(0)
; template <class Epi, class Sched, bool ALIGN_EPI = false, bool SP2 = false>
; __device__ __forceinline__ void gemm_phase(PG8_LAS unsigned char* lds, const Gemm g, const Sched& S, const Epi& E) {
;     ...
;             PG8_WAIT_V(8); PG8_WAIT_L(0); PG8_BAR; __builtin_amdgcn_s_setprio(1); PG8_MMA_NP(0, 0, At, B0); PG8_MMA_NP(0, 1, At, B1); __builtin_amdgcn_s_setprio(0); PG8_BAR; PG8_SCHED;
;             PG8_LDA(At, 0, 1); PG8_STAGE(PG8_SB(0, 0), b2, voffB); PG8_STAGE(PG8_SB(0, 1), b2 + hstep, voffB); PG8_STAGE(PG8_SA(0, 0), a2, voffA);
;             PG8_WAIT_V(8); PG8_WAIT_L(0); PG8_BAR; __builtin_amdgcn_s_setprio(1); PG8_MMA_NP(1, 0, At, B0); PG8_MMA_NP(1, 1, At, B1); __builtin_amdgcn_s_setprio(0); PG8_BAR; PG8_SCHED;
	s_waitcnt lgkmcnt(0)
	v_mfma_f32_16x16x32_bf16 v[126:129], v[140:143], v[206:209], v[126:129]
	v_mfma_f32_16x16x32_bf16 v[122:125], v[154:157], v[206:209], v[122:125]
	v_mfma_f32_16x16x32_bf16 v[110:113], v[140:143], v[214:217], v[110:113]
	v_mfma_f32_16x16x32_bf16 v[106:109], v[154:157], v[214:217], v[106:109]
	v_mfma_f32_16x16x32_bf16 v[94:97], v[140:143], v[222:225], v[94:97]
	v_mfma_f32_16x16x32_bf16 v[90:93], v[154:157], v[222:225], v[90:93]
	v_mfma_f32_16x16x32_bf16 v[78:81], v[140:143], v[230:233], v[78:81]
	v_mfma_f32_16x16x32_bf16 v[74:77], v[154:157], v[230:233], v[74:77]
	v_mfma_f32_16x16x32_bf16 v[118:121], v[178:181], v[206:209], v[118:121]
	v_mfma_f32_16x16x32_bf16 v[114:117], v[186:189], v[206:209], v[114:117]
	v_mfma_f32_16x16x32_bf16 v[102:105], v[178:181], v[214:217], v[102:105]
	v_mfma_f32_16x16x32_bf16 v[98:101], v[186:189], v[214:217], v[98:101]
	v_mfma_f32_16x16x32_bf16 v[86:89], v[178:181], v[222:225], v[86:89]
	v_mfma_f32_16x16x32_bf16 v[82:85], v[186:189], v[222:225], v[82:85]
	v_mfma_f32_16x16x32_bf16 v[70:73], v[178:181], v[230:233], v[70:73]
	v_mfma_f32_16x16x32_bf16 v[66:69], v[186:189], v[230:233], v[66:69]
	v_mfma_f32_16x16x32_bf16 v[126:129], v[150:153], v[210:213], v[126:129]
	v_mfma_f32_16x16x32_bf16 v[122:125], v[158:161], v[210:213], v[122:125]
	v_mfma_f32_16x16x32_bf16 v[110:113], v[150:153], v[218:221], v[110:113]
	v_mfma_f32_16x16x32_bf16 v[106:109], v[158:161], v[218:221], v[106:109]
	v_mfma_f32_16x16x32_bf16 v[94:97], v[150:153], v[226:229], v[94:97]
	v_mfma_f32_16x16x32_bf16 v[90:93], v[158:161], v[226:229], v[90:93]
	v_mfma_f32_16x16x32_bf16 v[78:81], v[150:153], v[234:237], v[78:81]
	v_mfma_f32_16x16x32_bf16 v[74:77], v[158:161], v[234:237], v[74:77]
	v_mfma_f32_16x16x32_bf16 v[118:121], v[182:185], v[210:213], v[118:121]
	v_mfma_f32_16x16x32_bf16 v[114:117], v[202:205], v[210:213], v[114:117]
	v_mfma_f32_16x16x32_bf16 v[102:105], v[182:185], v[218:221], v[102:105]
	v_mfma_f32_16x16x32_bf16 v[98:101], v[202:205], v[218:221], v[98:101]
	v_mfma_f32_16x16x32_bf16 v[86:89], v[182:185], v[226:229], v[86:89]
	v_mfma_f32_16x16x32_bf16 v[82:85], v[202:205], v[226:229], v[82:85]
	v_mfma_f32_16x16x32_bf16 v[70:73], v[182:185], v[234:237], v[70:73]
	v_mfma_f32_16x16x32_bf16 v[66:69], v[202:205], v[234:237], v[66:69]
	s_barrier
	s_add_i32 s22, s22, s41
	v_lshl_add_u64 v[144:145], s[14:15], 0, v[0:1]
	s_mov_b32 m0, s22
	ds_read_b128 v[206:209], v149 offset:16384
	ds_read_b128 v[210:213], v149 offset:17408
	ds_read_b128 v[214:217], v149 offset:18432
	ds_read_b128 v[218:221], v149 offset:19456
	ds_read_b128 v[222:225], v149 offset:20480
	ds_read_b128 v[226:229], v149 offset:21504
	ds_read_b128 v[230:233], v149 offset:22528
	ds_read_b128 v[234:237], v149 offset:23552
	global_load_lds_dwordx4 v[144:145], off
	s_add_i32 m0, s22, 0x2000
	s_add_u32 s22, s14, 0x40000
	v_lshl_add_u64 v[162:163], s[14:15], 0, v[130:131]
	s_addc_u32 s23, s15, 0
	s_add_i32 s67, s67, s41
	global_load_lds_dwordx4 v[162:163], off
	v_lshl_add_u64 v[190:191], s[22:23], 0, v[0:1]
	s_mov_b32 m0, s67
	v_lshl_add_u64 v[238:239], s[38:39], 0, v[132:133]
	global_load_lds_dwordx4 v[190:191], off
	v_lshl_add_u64 v[190:191], s[22:23], 0, v[130:131]
	s_add_i32 m0, s67, 0x2000
	s_nop 0
	global_load_lds_dwordx4 v[190:191], off
	v_lshl_add_u64 v[190:191], s[38:39], 0, v[134:135]
	s_mov_b32 m0, s56
	s_nop 0
	global_load_lds_dwordx4 v[190:191], off
	s_mov_b32 m0, s57
	s_nop 0
	global_load_lds_dwordx4 v[238:239], off
	s_waitcnt vmcnt(8)
	s_waitcnt lgkmcnt(0)
	s_barrier
	s_waitcnt lgkmcnt(0)
	v_mfma_f32_16x16x32_bf16 v[62:65], v[140:143], v[206:209], v[62:65]
	v_mfma_f32_16x16x32_bf16 v[58:61], v[154:157], v[206:209], v[58:61]
	v_mfma_f32_16x16x32_bf16 v[46:49], v[140:143], v[214:217], v[46:49]
	v_mfma_f32_16x16x32_bf16 v[42:45], v[154:157], v[214:217], v[42:45]
	v_mfma_f32_16x16x32_bf16 v[30:33], v[140:143], v[222:225], v[30:33]
	v_mfma_f32_16x16x32_bf16 v[26:29], v[154:157], v[222:225], v[26:29]
	v_mfma_f32_16x16x32_bf16 v[14:17], v[140:143], v[230:233], v[14:17]
	v_mfma_f32_16x16x32_bf16 v[10:13], v[154:157], v[230:233], v[10:13]
	v_mfma_f32_16x16x32_bf16 v[54:57], v[178:181], v[206:209], v[54:57]
	v_mfma_f32_16x16x32_bf16 v[50:53], v[186:189], v[206:209], v[50:53]
	v_mfma_f32_16x16x32_bf16 v[38:41], v[178:181], v[214:217], v[38:41]
	v_mfma_f32_16x16x32_bf16 v[34:37], v[186:189], v[214:217], v[34:37]
	v_mfma_f32_16x16x32_bf16 v[22:25], v[178:181], v[222:225], v[22:25]
	v_mfma_f32_16x16x32_bf16 v[18:21], v[186:189], v[222:225], v[18:21]
	v_mfma_f32_16x16x32_bf16 v[6:9], v[178:181], v[230:233], v[6:9]
	v_mfma_f32_16x16x32_bf16 v[2:5], v[186:189], v[230:233], v[2:5]
	v_mfma_f32_16x16x32_bf16 v[62:65], v[150:153], v[210:213], v[62:65]
	v_mfma_f32_16x16x32_bf16 v[58:61], v[158:161], v[210:213], v[58:61]
	v_mfma_f32_16x16x32_bf16 v[46:49], v[150:153], v[218:221], v[46:49]
	v_mfma_f32_16x16x32_bf16 v[42:45], v[158:161], v[218:221], v[42:45]
	v_mfma_f32_16x16x32_bf16 v[30:33], v[150:153], v[226:229], v[30:33]
	v_mfma_f32_16x16x32_bf16 v[26:29], v[158:161], v[226:229], v[26:29]
	v_mfma_f32_16x16x32_bf16 v[14:17], v[150:153], v[234:237], v[14:17]
	v_mfma_f32_16x16x32_bf16 v[10:13], v[158:161], v[234:237], v[10:13]
	v_mfma_f32_16x16x32_bf16 v[54:57], v[182:185], v[210:213], v[54:57]
	v_mfma_f32_16x16x32_bf16 v[50:53], v[202:205], v[210:213], v[50:53]
	v_mfma_f32_16x16x32_bf16 v[38:41], v[182:185], v[218:221], v[38:41]
	v_mfma_f32_16x16x32_bf16 v[34:37], v[202:205], v[218:221], v[34:37]
	v_mfma_f32_16x16x32_bf16 v[22:25], v[182:185], v[226:229], v[22:25]
	v_mfma_f32_16x16x32_bf16 v[18:21], v[202:205], v[226:229], v[18:21]
	v_mfma_f32_16x16x32_bf16 v[6:9], v[182:185], v[234:237], v[6:9]
	v_mfma_f32_16x16x32_bf16 v[2:5], v[202:205], v[234:237], v[2:5]
	s_barrier
; #define PG8_STAGE(bufoff, gbase, voff) do { _Pragma("unroll") for (int _i = 0; _i < 2; ++_i) \
;         __builtin_amdgcn_global_load_lds((const unsigned*)((const char*)(gbase) + (voff)[_i]), (PG8_LAS unsigned*)(lds + (bufoff) + ldsw + _i * 8192), 16, 0, 0); } while (0)
; #define PG8_LDA(dst, b, h) do { _Pragma("unroll") for (int m = 0; m < 4; ++m) _Pragma("unroll") for (int k = 0; k < 2; ++k) dst[m][k] = *(const PG8_LAS bf16x8*)(lds + PG8_SA(b, h) + aoff + m * 2048 + k * 1024); } while (0)
; #define PG8_LDB(dst, b, h) do { _Pragma("unroll") for (int n = 0; n < 2; ++n) _Pragma("unroll") for (int k = 0; k < 2; ++k) dst[n][k] = *(const PG8_LAS bf16x8*)(lds + PG8_SB(b, h) + boff + n * 2048 + k * 1024); } while (0)
; #define PG8_MMA_NP(ai, bj, At, Bt) do { _Pragma("unroll") for (int m = 0; m < 4; ++m) _Pragma("unroll") for (int n = 0; n < 2; ++n) _Pragma("unroll") for (int k = 0; k < 2; ++k) \
;         acc[ai][bj][m][n] = __builtin_amdgcn_mfma_f32_16x16x32_bf16(Bt[n][k], At[m][k], acc[ai][bj][m][n], 0, 0, 0); } while (0)
; #define PG8_WAIT_V(n) asm volatile("s_waitcnt vmcnt(" #n ")" ::: "memory")
; #define PG8_WAIT_L(n) asm volatile("s_waitcnt lgkmcnt(" #n ")" ::: "memory")
; #define PG8_BAR __builtin_amdgcn_s_barrier()
; #define PG8_SCHED __builtin_amdgcn_sched_barrier(0)
; template <class Epi, class Sched, bool ALIGN_EPI = false, bool SP2 = false>
; __device__ __forceinline__ void gemm_phase(PG8_LAS unsigned char* lds, const Gemm g, const Sched& S, const Epi& E) {
;     ...
;             PG8_LDB(B0, 1, 0); PG8_LDB(B1, 1, 1); PG8_SCHED; PG8_LDA(At, 1, 0); PG8_STAGE(PG8_SA(0, 1), a2 + hstep, voffA);
;             PG8_WAIT_V(8); PG8_WAIT_L(0); PG8_BAR; __builtin_amdgcn_s_setprio(1); PG8_MMA_NP(0, 0, At, B0); PG8_MMA_NP(0, 1, At, B1); __builtin_amdgcn_s_setprio(0); PG8_BAR; PG8_SCHED;
	s_add_i32 s67, 0, 0x18000
	s_add_i32 s68, 0, 0x1c000
	v_add_u32_e32 v158, s67, v147
	v_add_u32_e32 v202, s68, v147
	ds_read_b128 v[140:143], v158
	ds_read_b128 v[150:153], v158 offset:1024
	ds_read_b128 v[154:157], v158 offset:2048
	ds_read_b128 v[158:161], v158 offset:3072
	ds_read_b128 v[178:181], v202
	ds_read_b128 v[182:185], v202 offset:1024
	ds_read_b128 v[186:189], v202 offset:2048
	ds_read_b128 v[202:205], v202 offset:3072
	s_add_u32 s22, s38, 0x40000
	s_addc_u32 s23, s39, 0
	s_mov_b32 m0, s58
	v_lshl_add_u64 v[240:241], s[22:23], 0, v[134:135]
	ds_read_b128 v[206:209], v149 offset:32768
	ds_read_b128 v[210:213], v149 offset:33792
	ds_read_b128 v[214:217], v149 offset:34816
	ds_read_b128 v[218:221], v149 offset:35840
	ds_read_b128 v[222:225], v149 offset:36864
	ds_read_b128 v[226:229], v149 offset:37888
	ds_read_b128 v[230:233], v149 offset:38912
	ds_read_b128 v[234:237], v149 offset:39936
	global_load_lds_dwordx4 v[240:241], off
	v_lshl_add_u64 v[240:241], s[22:23], 0, v[132:133]
	s_mov_b32 m0, s59
	s_nop 0
	global_load_lds_dwordx4 v[240:241], off
	s_waitcnt vmcnt(8)
	s_waitcnt lgkmcnt(0)
	s_barrier
	s_waitcnt lgkmcnt(0)
	v_mfma_f32_16x16x32_bf16 v[126:129], v[140:143], v[206:209], v[126:129]
	v_mfma_f32_16x16x32_bf16 v[122:125], v[154:157], v[206:209], v[122:125]
	v_mfma_f32_16x16x32_bf16 v[110:113], v[140:143], v[214:217], v[110:113]
	v_mfma_f32_16x16x32_bf16 v[106:109], v[154:157], v[214:217], v[106:109]
	v_mfma_f32_16x16x32_bf16 v[94:97], v[140:143], v[222:225], v[94:97]
	v_mfma_f32_16x16x32_bf16 v[90:93], v[154:157], v[222:225], v[90:93]
	v_mfma_f32_16x16x32_bf16 v[78:81], v[140:143], v[230:233], v[78:81]
	v_mfma_f32_16x16x32_bf16 v[74:77], v[154:157], v[230:233], v[74:77]
	v_mfma_f32_16x16x32_bf16 v[118:121], v[178:181], v[206:209], v[118:121]
	v_mfma_f32_16x16x32_bf16 v[114:117], v[186:189], v[206:209], v[114:117]
	v_mfma_f32_16x16x32_bf16 v[102:105], v[178:181], v[214:217], v[102:105]
	v_mfma_f32_16x16x32_bf16 v[98:101], v[186:189], v[214:217], v[98:101]
	v_mfma_f32_16x16x32_bf16 v[86:89], v[178:181], v[222:225], v[86:89]
	v_mfma_f32_16x16x32_bf16 v[82:85], v[186:189], v[222:225], v[82:85]
	v_mfma_f32_16x16x32_bf16 v[70:73], v[178:181], v[230:233], v[70:73]
	v_mfma_f32_16x16x32_bf16 v[66:69], v[186:189], v[230:233], v[66:69]
	v_mfma_f32_16x16x32_bf16 v[126:129], v[150:153], v[210:213], v[126:129]
	v_mfma_f32_16x16x32_bf16 v[122:125], v[158:161], v[210:213], v[122:125]
	v_mfma_f32_16x16x32_bf16 v[110:113], v[150:153], v[218:221], v[110:113]
	v_mfma_f32_16x16x32_bf16 v[106:109], v[158:161], v[218:221], v[106:109]
	v_mfma_f32_16x16x32_bf16 v[94:97], v[150:153], v[226:229], v[94:97]
	v_mfma_f32_16x16x32_bf16 v[90:93], v[158:161], v[226:229], v[90:93]
	v_mfma_f32_16x16x32_bf16 v[78:81], v[150:153], v[234:237], v[78:81]
	v_mfma_f32_16x16x32_bf16 v[74:77], v[158:161], v[234:237], v[74:77]
	v_mfma_f32_16x16x32_bf16 v[118:121], v[182:185], v[210:213], v[118:121]
	v_mfma_f32_16x16x32_bf16 v[114:117], v[202:205], v[210:213], v[114:117]
	v_mfma_f32_16x16x32_bf16 v[102:105], v[182:185], v[218:221], v[102:105]
	v_mfma_f32_16x16x32_bf16 v[98:101], v[202:205], v[218:221], v[98:101]
	v_mfma_f32_16x16x32_bf16 v[86:89], v[182:185], v[226:229], v[86:89]
	v_mfma_f32_16x16x32_bf16 v[82:85], v[202:205], v[226:229], v[82:85]
	v_mfma_f32_16x16x32_bf16 v[70:73], v[182:185], v[234:237], v[70:73]
	v_mfma_f32_16x16x32_bf16 v[66:69], v[202:205], v[234:237], v[66:69]
	s_barrier
; #define PG8_STAGE(bufoff, gbase, voff) do { _Pragma("unroll") for (int _i = 0; _i < 2; ++_i) \
;         __builtin_amdgcn_global_load_lds((const unsigned*)((const char*)(gbase) + (voff)[_i]), (PG8_LAS unsigned*)(lds + (bufoff) + ldsw + _i * 8192), 16, 0, 0); } while (0)
; #define PG8_LDA(dst, b, h) do { _Pragma("unroll") for (int m = 0; m < 4; ++m) _Pragma("unroll") for (int k = 0; k < 2; ++k) dst[m][k] = *(const PG8_LAS bf16x8*)(lds + PG8_SA(b, h) + aoff + m * 2048 + k * 1024); } while (0)
; #define PG8_MMA_NP(ai, bj, At, Bt) do { _Pragma("unroll") for (int m = 0; m < 4; ++m) _Pragma("unroll") for (int n = 0; n < 2; ++n) _Pragma("unroll") for (int k = 0; k < 2; ++k) \
;         acc[ai][bj][m][n] = __builtin_amdgcn_mfma_f32_16x16x32_bf16(Bt[n][k], At[m][k], acc[ai][bj][m][n], 0, 0, 0); } while (0)
; #define PG8_WAIT_V(n) asm volatile("s_waitcnt vmcnt(" #n ")" ::: "memory")
; #define PG8_WAIT_L(n) asm volatile("s_waitcnt lgkmcnt(" #n ")" ::: "memory")
; #define PG8_BAR __builtin_amdgcn_s_barrier()
; #define PG8_SCHED __builtin_amdgcn_sched_barrier(0)
; template <class Epi, class Sched, bool ALIGN_EPI = false, bool SP2 = false>
; __device__ __forceinline__ void gemm_phase(PG8_LAS unsigned char* lds, const Gemm g, const Sched& S, const Epi& E) {
;     ...
;             PG8_LDA(At, 1, 1); PG8_STAGE(PG8_SB(1, 0), b3, voffB); PG8_STAGE(PG8_SB(1, 1), b3 + hstep, voffB); PG8_STAGE(PG8_SA(1, 0), a3, voffA);
;             PG8_WAIT_V(8); PG8_WAIT_L(0); PG8_BAR; __builtin_amdgcn_s_setprio(1); PG8_MMA_NP(1, 0, At, B0); PG8_MMA_NP(1, 1, At, B1); __builtin_amdgcn_s_setprio(0); PG8_BAR; PG8_SCHED;
	s_add_i32 s22, s67, s41
	v_lshl_add_u64 v[144:145], v[144:145], 0, s[20:21]
	s_mov_b32 m0, s22
	ds_read_b128 v[206:209], v149 offset:49152
	ds_read_b128 v[210:213], v149 offset:50176
	ds_read_b128 v[214:217], v149 offset:51200
	ds_read_b128 v[218:221], v149 offset:52224
	ds_read_b128 v[222:225], v149 offset:53248
	ds_read_b128 v[226:229], v149 offset:54272
	ds_read_b128 v[230:233], v149 offset:55296
	ds_read_b128 v[234:237], v149 offset:56320
	global_load_lds_dwordx4 v[144:145], off
	s_add_i32 m0, s22, 0x2000
	s_add_u32 s14, s14, 0x40080
	v_lshl_add_u64 v[144:145], v[162:163], 0, s[20:21]
	s_addc_u32 s15, s15, 0
	s_add_i32 s22, s68, s41
	global_load_lds_dwordx4 v[144:145], off
	v_lshl_add_u64 v[144:145], s[14:15], 0, v[0:1]
	s_mov_b32 m0, s22
	s_nop 0
	global_load_lds_dwordx4 v[144:145], off
	v_lshl_add_u64 v[144:145], s[14:15], 0, v[130:131]
	s_add_i32 m0, s22, 0x2000
	s_nop 0
	global_load_lds_dwordx4 v[144:145], off
	v_lshl_add_u64 v[144:145], v[190:191], 0, s[20:21]
	s_mov_b32 m0, s61
	s_nop 0
	global_load_lds_dwordx4 v[144:145], off
	v_lshl_add_u64 v[144:145], v[238:239], 0, s[20:21]
	s_mov_b32 m0, s62
	s_nop 0
	global_load_lds_dwordx4 v[144:145], off
	s_waitcnt vmcnt(8)
	s_waitcnt lgkmcnt(0)
	s_barrier
	s_waitcnt lgkmcnt(0)
	v_mfma_f32_16x16x32_bf16 v[62:65], v[140:143], v[206:209], v[62:65]
	v_mfma_f32_16x16x32_bf16 v[58:61], v[154:157], v[206:209], v[58:61]
	v_mfma_f32_16x16x32_bf16 v[46:49], v[140:143], v[214:217], v[46:49]
	v_mfma_f32_16x16x32_bf16 v[42:45], v[154:157], v[214:217], v[42:45]
	v_mfma_f32_16x16x32_bf16 v[30:33], v[140:143], v[222:225], v[30:33]
	v_mfma_f32_16x16x32_bf16 v[26:29], v[154:157], v[222:225], v[26:29]
	v_mfma_f32_16x16x32_bf16 v[14:17], v[140:143], v[230:233], v[14:17]
	v_mfma_f32_16x16x32_bf16 v[10:13], v[154:157], v[230:233], v[10:13]
	v_mfma_f32_16x16x32_bf16 v[54:57], v[178:181], v[206:209], v[54:57]
	v_mfma_f32_16x16x32_bf16 v[50:53], v[186:189], v[206:209], v[50:53]
	v_mfma_f32_16x16x32_bf16 v[38:41], v[178:181], v[214:217], v[38:41]
	v_mfma_f32_16x16x32_bf16 v[34:37], v[186:189], v[214:217], v[34:37]
	v_mfma_f32_16x16x32_bf16 v[22:25], v[178:181], v[222:225], v[22:25]
	v_mfma_f32_16x16x32_bf16 v[18:21], v[186:189], v[222:225], v[18:21]
	v_mfma_f32_16x16x32_bf16 v[6:9], v[178:181], v[230:233], v[6:9]
	v_mfma_f32_16x16x32_bf16 v[2:5], v[186:189], v[230:233], v[2:5]
	v_mfma_f32_16x16x32_bf16 v[62:65], v[150:153], v[210:213], v[62:65]
	v_mfma_f32_16x16x32_bf16 v[58:61], v[158:161], v[210:213], v[58:61]
	v_mfma_f32_16x16x32_bf16 v[46:49], v[150:153], v[218:221], v[46:49]
	v_mfma_f32_16x16x32_bf16 v[42:45], v[158:161], v[218:221], v[42:45]
	v_mfma_f32_16x16x32_bf16 v[30:33], v[150:153], v[226:229], v[30:33]
	v_mfma_f32_16x16x32_bf16 v[26:29], v[158:161], v[226:229], v[26:29]
	v_mfma_f32_16x16x32_bf16 v[14:17], v[150:153], v[234:237], v[14:17]
	v_mfma_f32_16x16x32_bf16 v[10:13], v[158:161], v[234:237], v[10:13]
	v_mfma_f32_16x16x32_bf16 v[54:57], v[182:185], v[210:213], v[54:57]
	v_mfma_f32_16x16x32_bf16 v[50:53], v[202:205], v[210:213], v[50:53]
	v_mfma_f32_16x16x32_bf16 v[38:41], v[182:185], v[218:221], v[38:41]
	v_mfma_f32_16x16x32_bf16 v[34:37], v[202:205], v[218:221], v[34:37]
	v_mfma_f32_16x16x32_bf16 v[22:25], v[182:185], v[226:229], v[22:25]
	v_mfma_f32_16x16x32_bf16 v[18:21], v[202:205], v[226:229], v[18:21]
	v_mfma_f32_16x16x32_bf16 v[6:9], v[182:185], v[234:237], v[6:9]
	v_mfma_f32_16x16x32_bf16 v[2:5], v[202:205], v[234:237], v[2:5]
	s_barrier
	s_add_i32 s66, s66, 2
	s_add_u32 s12, s12, 0x100
	s_addc_u32 s13, s13, 0
	s_add_u32 s64, s64, 0x100
	s_addc_u32 s65, s65, 0
	s_cmp_gt_u32 s66, 13
	s_cbranch_scc0 .LBB0_1016

; #define PG8_STAGE(bufoff, gbase, voff) do { _Pragma("unroll") for (int _i = 0; _i < 2; ++_i) \
;         __builtin_amdgcn_global_load_lds((const unsigned*)((const char*)(gbase) + (voff)[_i]), (PG8_LAS unsigned*)(lds + (bufoff) + ldsw + _i * 8192), 16, 0, 0); } while (0)
; #define PG8_LDA(dst, b, h) do { _Pragma("unroll") for (int m = 0; m < 4; ++m) _Pragma("unroll") for (int k = 0; k < 2; ++k) dst[m][k] = *(const PG8_LAS bf16x8*)(lds + PG8_SA(b, h) + aoff + m * 2048 + k * 1024); } while (0)
; #define PG8_LDB(dst, b, h) do { _Pragma("unroll") for (int n = 0; n < 2; ++n) _Pragma("unroll") for (int k = 0; k < 2; ++k) dst[n][k] = *(const PG8_LAS bf16x8*)(lds + PG8_SB(b, h) + boff + n * 2048 + k * 1024); } while (0)
; #define PG8_MMA_NP(ai, bj, At, Bt) do { _Pragma("unroll") for (int m = 0; m < 4; ++m) _Pragma("unroll") for (int n = 0; n < 2; ++n) _Pragma("unroll") for (int k = 0; k < 2; ++k) \
;         acc[ai][bj][m][n] = __builtin_amdgcn_mfma_f32_16x16x32_bf16(Bt[n][k], At[m][k], acc[ai][bj][m][n], 0, 0, 0); } while (0)
; template <class Epi, class Sched, bool ALIGN_EPI = false, bool SP2 = false>
; __device__ __forceinline__ void gemm_phase(PG8_LAS unsigned char* lds, const Gemm g, const Sched& S, const Epi& E) {
;     ...
;         const bool has_next = S.next(ui + 1, nxt);
;         const char* nA = has_next ? (const char*)g.A + (size_t)nxt.pm * tstep : cA; const char* nB = has_next ? (const char*)g.Bt + (size_t)nxt.pn * tstep : cB;
;         for (int t = 0; t < nt; t += 2) {
;             const bool last = (t == nt - 2);
;             const char* a1 = cA + (size_t)(t + 1) * kstep;
;             const char* a2 = last ? nA : cA + (size_t)(t + 2) * kstep; const char* b2 = last ? nB : cB + (size_t)(t + 2) * kstep;
;             const char* a3 = a2 + kstep; const char* b3 = b2 + kstep;
;             if (last && has_next) S.a_ready(nxt);
;             if constexpr (SP2) {
;             PG8_LDB(B0, 0, 0); PG8_LDB(B1, 0, 1); PG8_SCHED; PG8_LDA(At, 0, 0); PG8_STAGE(PG8_SA(1, 1), a1 + hstep, voffA);
;             PG8_WAIT_V(8); PG8_WAIT_L(0); PG8_BAR; __builtin_amdgcn_s_setprio(1); PG8_MMA_NP(0, 0, At, B0); PG8_MMA_NP(0, 1, At, B1); __builtin_amdgcn_s_setprio(0); PG8_BAR; PG8_SCHED;
;             PG8_LDA(At, 0, 1); PG8_STAGE(PG8_SB(0, 0), b2, voffB); PG8_STAGE(PG8_SB(0, 1), b2 + hstep, voffB); PG8_STAGE(PG8_SA(0, 0), a2, voffA);
.LBB0_1121:
	s_ashr_i32 s49, s48, 31
	s_lshl_b64 s[14:15], s[48:49], 19
	s_add_u32 s50, s86, s14
	s_addc_u32 s51, s87, s15
	s_and_b64 s[14:15], s[38:39], exec
	s_cselect_b32 s49, s51, s3
	s_cselect_b32 s59, s50, s2
	s_ashr_i32 s47, s46, 31
	s_lshl_b64 s[14:15], s[46:47], 19
	s_add_u32 s52, s8, s14
	s_addc_u32 s53, s10, s15
	s_and_b64 s[14:15], s[38:39], exec
	s_cselect_b32 s47, s53, s13
	s_cselect_b32 s60, s52, s12
	s_add_u32 s2, s2, 0x40080
	s_addc_u32 s3, s3, 0
	s_add_u32 s61, s12, 0x100
	s_addc_u32 s62, s13, 0
	s_mov_b32 s63, -2
	s_add_u32 s12, s2, 0xfffc0080
	s_addc_u32 s13, s3, -1
	s_add_i32 s22, 0, 0x10000
	s_cmp_eq_u32 s63, 12
	s_cselect_b32 s15, s49, s13
	s_cselect_b32 s14, s59, s12
	s_cselect_b32 s13, s47, s62
	s_cselect_b32 s12, s60, s61
	s_add_i32 s64, 0, 0x14000
	v_add_u32_e32 v154, s22, v183
	v_add_u32_e32 v162, s64, v183
	ds_read_b128 v[130:133], v154
	ds_read_b128 v[146:149], v154 offset:1024
	ds_read_b128 v[150:153], v154 offset:2048
	ds_read_b128 v[154:157], v154 offset:3072
	ds_read_b128 v[158:161], v162
	ds_read_b128 v[178:181], v162 offset:1024
	ds_read_b128 v[186:189], v162 offset:2048
	ds_read_b128 v[202:205], v162 offset:3072
	v_lshl_add_u64 v[162:163], s[2:3], 0, v[142:143]
	s_add_i32 m0, s30, 0xc000
	ds_read_b128 v[206:209], v185
	ds_read_b128 v[210:213], v185 offset:1024
	ds_read_b128 v[214:217], v185 offset:2048
	ds_read_b128 v[218:221], v185 offset:3072
	ds_read_b128 v[222:225], v185 offset:4096
	ds_read_b128 v[226:229], v185 offset:5120
	ds_read_b128 v[230:233], v185 offset:6144
	ds_read_b128 v[234:237], v185 offset:7168
	global_load_lds_dwordx4 v[162:163], off
	v_lshl_add_u64 v[162:163], s[2:3], 0, v[144:145]
	s_add_i32 m0, s30, 0xe000
	s_nop 0
	global_load_lds_dwordx4 v[162:163], off
	s_waitcnt vmcnt(8)
	s_waitcnt lgkmcnt(0)
	s_barrier
	s_waitcnt lgkmcnt(0)
	v_mfma_f32_16x16x32_bf16 v[126:129], v[130:133], v[206:209], 0
	v_mfma_f32_16x16x32_bf16 v[118:121], v[150:153], v[206:209], 0
	v_mfma_f32_16x16x32_bf16 v[110:113], v[130:133], v[214:217], 0
	v_mfma_f32_16x16x32_bf16 v[102:105], v[150:153], v[214:217], 0
	v_mfma_f32_16x16x32_bf16 v[94:97], v[130:133], v[222:225], 0
	v_mfma_f32_16x16x32_bf16 v[86:89], v[150:153], v[222:225], 0
	v_mfma_f32_16x16x32_bf16 v[78:81], v[130:133], v[230:233], 0
	v_mfma_f32_16x16x32_bf16 v[70:73], v[150:153], v[230:233], 0
	v_mfma_f32_16x16x32_bf16 v[122:125], v[158:161], v[206:209], 0
	v_mfma_f32_16x16x32_bf16 v[114:117], v[186:189], v[206:209], 0
	v_mfma_f32_16x16x32_bf16 v[106:109], v[158:161], v[214:217], 0
	v_mfma_f32_16x16x32_bf16 v[98:101], v[186:189], v[214:217], 0
	v_mfma_f32_16x16x32_bf16 v[90:93], v[158:161], v[222:225], 0
	v_mfma_f32_16x16x32_bf16 v[82:85], v[186:189], v[222:225], 0
	v_mfma_f32_16x16x32_bf16 v[74:77], v[158:161], v[230:233], 0
	v_mfma_f32_16x16x32_bf16 v[66:69], v[186:189], v[230:233], 0
	v_mfma_f32_16x16x32_bf16 v[126:129], v[146:149], v[210:213], v[126:129]
	v_mfma_f32_16x16x32_bf16 v[118:121], v[154:157], v[210:213], v[118:121]
	v_mfma_f32_16x16x32_bf16 v[110:113], v[146:149], v[218:221], v[110:113]
	v_mfma_f32_16x16x32_bf16 v[102:105], v[154:157], v[218:221], v[102:105]
	v_mfma_f32_16x16x32_bf16 v[94:97], v[146:149], v[226:229], v[94:97]
	v_mfma_f32_16x16x32_bf16 v[86:89], v[154:157], v[226:229], v[86:89]
	v_mfma_f32_16x16x32_bf16 v[78:81], v[146:149], v[234:237], v[78:81]
	v_mfma_f32_16x16x32_bf16 v[70:73], v[154:157], v[234:237], v[70:73]
	v_mfma_f32_16x16x32_bf16 v[122:125], v[178:181], v[210:213], v[122:125]
	v_mfma_f32_16x16x32_bf16 v[114:117], v[202:205], v[210:213], v[114:117]
	v_mfma_f32_16x16x32_bf16 v[106:109], v[178:181], v[218:221], v[106:109]
	v_mfma_f32_16x16x32_bf16 v[98:101], v[202:205], v[218:221], v[98:101]
	v_mfma_f32_16x16x32_bf16 v[90:93], v[178:181], v[226:229], v[90:93]
	v_mfma_f32_16x16x32_bf16 v[82:85], v[202:205], v[226:229], v[82:85]
	v_mfma_f32_16x16x32_bf16 v[74:77], v[178:181], v[234:237], v[74:77]
	v_mfma_f32_16x16x32_bf16 v[66:69], v[202:205], v[234:237], v[66:69]
	s_barrier
	s_add_i32 s22, s22, s29
	v_lshl_add_u64 v[162:163], s[12:13], 0, v[0:1]
	s_mov_b32 m0, s22
	ds_read_b128 v[206:209], v185 offset:16384
	ds_read_b128 v[210:213], v185 offset:17408
	ds_read_b128 v[214:217], v185 offset:18432
	ds_read_b128 v[218:221], v185 offset:19456
	ds_read_b128 v[222:225], v185 offset:20480
	ds_read_b128 v[226:229], v185 offset:21504
	ds_read_b128 v[230:233], v185 offset:22528
	ds_read_b128 v[234:237], v185 offset:23552
	global_load_lds_dwordx4 v[162:163], off
	s_add_i32 m0, s22, 0x2000
	s_add_u32 s22, s12, 0x40000
	v_lshl_add_u64 v[190:191], s[12:13], 0, v[134:135]
	s_addc_u32 s23, s13, 0
	s_add_i32 s64, s64, s29
	global_load_lds_dwordx4 v[190:191], off
	v_lshl_add_u64 v[238:239], s[22:23], 0, v[0:1]
	s_mov_b32 m0, s64
	v_lshl_add_u64 v[240:241], s[14:15], 0, v[136:137]
	global_load_lds_dwordx4 v[238:239], off
	v_lshl_add_u64 v[238:239], s[22:23], 0, v[134:135]
	s_add_i32 m0, s64, 0x2000
	s_nop 0
	global_load_lds_dwordx4 v[238:239], off
	v_lshl_add_u64 v[238:239], s[14:15], 0, v[138:139]
	s_mov_b32 m0, s30
	s_nop 0
	global_load_lds_dwordx4 v[238:239], off
	s_mov_b32 m0, s31
	s_nop 0
	global_load_lds_dwordx4 v[240:241], off
	s_waitcnt vmcnt(8)
	s_waitcnt lgkmcnt(0)
	s_barrier
; #define PG8_STAGE(bufoff, gbase, voff) do { _Pragma("unroll") for (int _i = 0; _i < 2; ++_i) \
;         __builtin_amdgcn_global_load_lds((const unsigned*)((const char*)(gbase) + (voff)[_i]), (PG8_LAS unsigned*)(lds + (bufoff) + ldsw + _i * 8192), 16, 0, 0); } while (0)
; #define PG8_LDA(dst, b, h) do { _Pragma("unroll") for (int m = 0; m < 4; ++m) _Pragma("unroll") for (int k = 0; k < 2; ++k) dst[m][k] = *(const PG8_LAS bf16x8*)(lds + PG8_SA(b, h) + aoff + m * 2048 + k * 1024); } while (0)
; #define PG8_LDB(dst, b, h) do { _Pragma("unroll") for (int n = 0; n < 2; ++n) _Pragma("unroll") for (int k = 0; k < 2; ++k) dst[n][k] = *(const PG8_LAS bf16x8*)(lds + PG8_SB(b, h) + boff + n * 2048 + k * 1024); } while (0)
; #define PG8_MMA_NP(ai, bj, At, Bt) do { _Pragma("unroll") for (int m = 0; m < 4; ++m) _Pragma("unroll") for (int n = 0; n < 2; ++n) _Pragma("unroll") for (int k = 0; k < 2; ++k) \
;         acc[ai][bj][m][n] = __builtin_amdgcn_mfma_f32_16x16x32_bf16(Bt[n][k], At[m][k], acc[ai][bj][m][n], 0, 0, 0); } while (0)
; #define PG8_WAIT_V(n) asm volatile("s_waitcnt vmcnt(" #n ")" ::: "memory")
; #define PG8_WAIT_L(n) asm volatile("s_waitcnt lgkmcnt(" #n ")" ::: "memory")
; #define PG8_BAR __builtin_amdgcn_s_barrier()
; #define PG8_SCHED __builtin_amdgcn_sched_barrier(0)
; template <class Epi, class Sched, bool ALIGN_EPI = false, bool SP2 = false>
; __device__ __forceinline__ void gemm_phase(PG8_LAS unsigned char* lds, const Gemm g, const Sched& S, const Epi& E) {
;     ...
;             PG8_WAIT_V(8); PG8_WAIT_L(0); PG8_BAR; __builtin_amdgcn_s_setprio(1); PG8_MMA_NP(1, 0, At, B0); PG8_MMA_NP(1, 1, At, B1); __builtin_amdgcn_s_setprio(0); PG8_BAR; PG8_SCHED;
;             PG8_LDB(B0, 1, 0); PG8_LDB(B1, 1, 1); PG8_SCHED; PG8_LDA(At, 1, 0); PG8_STAGE(PG8_SA(0, 1), a2 + hstep, voffA);
;             PG8_WAIT_V(8); PG8_WAIT_L(0); PG8_BAR; __builtin_amdgcn_s_setprio(1); PG8_MMA_NP(0, 0, At, B0); PG8_MMA_NP(0, 1, At, B1); __builtin_amdgcn_s_setprio(0); PG8_BAR; PG8_SCHED;
	s_waitcnt lgkmcnt(0)
	v_mfma_f32_16x16x32_bf16 v[62:65], v[130:133], v[206:209], 0
	v_mfma_f32_16x16x32_bf16 v[54:57], v[150:153], v[206:209], 0
	v_mfma_f32_16x16x32_bf16 v[46:49], v[130:133], v[214:217], 0
	v_mfma_f32_16x16x32_bf16 v[38:41], v[150:153], v[214:217], 0
	v_mfma_f32_16x16x32_bf16 v[30:33], v[130:133], v[222:225], 0
	v_mfma_f32_16x16x32_bf16 v[22:25], v[150:153], v[222:225], 0
	v_mfma_f32_16x16x32_bf16 v[14:17], v[130:133], v[230:233], 0
	v_mfma_f32_16x16x32_bf16 v[6:9], v[150:153], v[230:233], 0
	v_mfma_f32_16x16x32_bf16 v[58:61], v[158:161], v[206:209], 0
	v_mfma_f32_16x16x32_bf16 v[50:53], v[186:189], v[206:209], 0
	v_mfma_f32_16x16x32_bf16 v[42:45], v[158:161], v[214:217], 0
	v_mfma_f32_16x16x32_bf16 v[34:37], v[186:189], v[214:217], 0
	v_mfma_f32_16x16x32_bf16 v[26:29], v[158:161], v[222:225], 0
	v_mfma_f32_16x16x32_bf16 v[18:21], v[186:189], v[222:225], 0
	v_mfma_f32_16x16x32_bf16 v[10:13], v[158:161], v[230:233], 0
	v_mfma_f32_16x16x32_bf16 v[2:5], v[186:189], v[230:233], 0
	v_mfma_f32_16x16x32_bf16 v[62:65], v[146:149], v[210:213], v[62:65]
	v_mfma_f32_16x16x32_bf16 v[54:57], v[154:157], v[210:213], v[54:57]
	v_mfma_f32_16x16x32_bf16 v[46:49], v[146:149], v[218:221], v[46:49]
	v_mfma_f32_16x16x32_bf16 v[38:41], v[154:157], v[218:221], v[38:41]
	v_mfma_f32_16x16x32_bf16 v[30:33], v[146:149], v[226:229], v[30:33]
	v_mfma_f32_16x16x32_bf16 v[22:25], v[154:157], v[226:229], v[22:25]
	v_mfma_f32_16x16x32_bf16 v[14:17], v[146:149], v[234:237], v[14:17]
	v_mfma_f32_16x16x32_bf16 v[6:9], v[154:157], v[234:237], v[6:9]
	v_mfma_f32_16x16x32_bf16 v[58:61], v[178:181], v[210:213], v[58:61]
	v_mfma_f32_16x16x32_bf16 v[50:53], v[202:205], v[210:213], v[50:53]
	v_mfma_f32_16x16x32_bf16 v[42:45], v[178:181], v[218:221], v[42:45]
	v_mfma_f32_16x16x32_bf16 v[34:37], v[202:205], v[218:221], v[34:37]
	v_mfma_f32_16x16x32_bf16 v[26:29], v[178:181], v[226:229], v[26:29]
	v_mfma_f32_16x16x32_bf16 v[18:21], v[202:205], v[226:229], v[18:21]
	v_mfma_f32_16x16x32_bf16 v[10:13], v[178:181], v[234:237], v[10:13]
	v_mfma_f32_16x16x32_bf16 v[2:5], v[202:205], v[234:237], v[2:5]
	s_barrier
	s_add_i32 s22, 0, 0x18000
	s_add_i32 s23, 0, 0x1c000
	v_add_u32_e32 v154, s22, v183
	v_add_u32_e32 v202, s23, v183
	ds_read_b128 v[130:133], v154
	ds_read_b128 v[146:149], v154 offset:1024
	ds_read_b128 v[150:153], v154 offset:2048
	ds_read_b128 v[154:157], v154 offset:3072
	ds_read_b128 v[158:161], v202
	ds_read_b128 v[178:181], v202 offset:1024
	ds_read_b128 v[186:189], v202 offset:2048
	ds_read_b128 v[202:205], v202 offset:3072
	s_add_u32 s14, s14, 0x40000
	s_addc_u32 s15, s15, 0
	s_mov_b32 m0, s40
	v_lshl_add_u64 v[242:243], s[14:15], 0, v[138:139]
	ds_read_b128 v[206:209], v185 offset:32768
	ds_read_b128 v[210:213], v185 offset:33792
	ds_read_b128 v[214:217], v185 offset:34816
	ds_read_b128 v[218:221], v185 offset:35840
	ds_read_b128 v[222:225], v185 offset:36864
	ds_read_b128 v[226:229], v185 offset:37888
	ds_read_b128 v[230:233], v185 offset:38912
	ds_read_b128 v[234:237], v185 offset:39936
	global_load_lds_dwordx4 v[242:243], off
	v_lshl_add_u64 v[242:243], s[14:15], 0, v[136:137]
	s_mov_b32 m0, s41
	s_nop 0
	global_load_lds_dwordx4 v[242:243], off
	s_waitcnt vmcnt(8)
	s_waitcnt lgkmcnt(0)
	s_barrier
	s_waitcnt lgkmcnt(0)
	v_mfma_f32_16x16x32_bf16 v[126:129], v[130:133], v[206:209], v[126:129]
	v_mfma_f32_16x16x32_bf16 v[118:121], v[150:153], v[206:209], v[118:121]
	v_mfma_f32_16x16x32_bf16 v[110:113], v[130:133], v[214:217], v[110:113]
	v_mfma_f32_16x16x32_bf16 v[102:105], v[150:153], v[214:217], v[102:105]
	v_mfma_f32_16x16x32_bf16 v[94:97], v[130:133], v[222:225], v[94:97]
	v_mfma_f32_16x16x32_bf16 v[86:89], v[150:153], v[222:225], v[86:89]
	v_mfma_f32_16x16x32_bf16 v[78:81], v[130:133], v[230:233], v[78:81]
	v_mfma_f32_16x16x32_bf16 v[70:73], v[150:153], v[230:233], v[70:73]
	v_mfma_f32_16x16x32_bf16 v[122:125], v[158:161], v[206:209], v[122:125]
	v_mfma_f32_16x16x32_bf16 v[114:117], v[186:189], v[206:209], v[114:117]
	v_mfma_f32_16x16x32_bf16 v[106:109], v[158:161], v[214:217], v[106:109]
	v_mfma_f32_16x16x32_bf16 v[98:101], v[186:189], v[214:217], v[98:101]
	v_mfma_f32_16x16x32_bf16 v[90:93], v[158:161], v[222:225], v[90:93]
	v_mfma_f32_16x16x32_bf16 v[82:85], v[186:189], v[222:225], v[82:85]
	v_mfma_f32_16x16x32_bf16 v[74:77], v[158:161], v[230:233], v[74:77]
	v_mfma_f32_16x16x32_bf16 v[66:69], v[186:189], v[230:233], v[66:69]
	v_mfma_f32_16x16x32_bf16 v[126:129], v[146:149], v[210:213], v[126:129]
	v_mfma_f32_16x16x32_bf16 v[118:121], v[154:157], v[210:213], v[118:121]
	v_mfma_f32_16x16x32_bf16 v[110:113], v[146:149], v[218:221], v[110:113]
	v_mfma_f32_16x16x32_bf16 v[102:105], v[154:157], v[218:221], v[102:105]
	v_mfma_f32_16x16x32_bf16 v[94:97], v[146:149], v[226:229], v[94:97]
	v_mfma_f32_16x16x32_bf16 v[86:89], v[154:157], v[226:229], v[86:89]
	v_mfma_f32_16x16x32_bf16 v[78:81], v[146:149], v[234:237], v[78:81]
	v_mfma_f32_16x16x32_bf16 v[70:73], v[154:157], v[234:237], v[70:73]
	v_mfma_f32_16x16x32_bf16 v[122:125], v[178:181], v[210:213], v[122:125]
	v_mfma_f32_16x16x32_bf16 v[114:117], v[202:205], v[210:213], v[114:117]
	v_mfma_f32_16x16x32_bf16 v[106:109], v[178:181], v[218:221], v[106:109]
	v_mfma_f32_16x16x32_bf16 v[98:101], v[202:205], v[218:221], v[98:101]
	v_mfma_f32_16x16x32_bf16 v[90:93], v[178:181], v[226:229], v[90:93]
	v_mfma_f32_16x16x32_bf16 v[82:85], v[202:205], v[226:229], v[82:85]
	v_mfma_f32_16x16x32_bf16 v[74:77], v[178:181], v[234:237], v[74:77]
	v_mfma_f32_16x16x32_bf16 v[66:69], v[202:205], v[234:237], v[66:69]
	s_barrier
; #define PG8_STAGE(bufoff, gbase, voff) do { _Pragma("unroll") for (int _i = 0; _i < 2; ++_i) \
;         __builtin_amdgcn_global_load_lds((const unsigned*)((const char*)(gbase) + (voff)[_i]), (PG8_LAS unsigned*)(lds + (bufoff) + ldsw + _i * 8192), 16, 0, 0); } while (0)
; #define PG8_LDA(dst, b, h) do { _Pragma("unroll") for (int m = 0; m < 4; ++m) _Pragma("unroll") for (int k = 0; k < 2; ++k) dst[m][k] = *(const PG8_LAS bf16x8*)(lds + PG8_SA(b, h) + aoff + m * 2048 + k * 1024); } while (0)
; #define PG8_WAIT_V(n) asm volatile("s_waitcnt vmcnt(" #n ")" ::: "memory")
; template <class Epi, class Sched, bool ALIGN_EPI = false, bool SP2 = false>
; __device__ __forceinline__ void gemm_phase(PG8_LAS unsigned char* lds, const Gemm g, const Sched& S, const Epi& E) {
;     ...
;             const char* a2 = last ? nA : cA + (size_t)(t + 2) * kstep; const char* b2 = last ? nB : cB + (size_t)(t + 2) * kstep;
;             const char* a3 = a2 + kstep; const char* b3 = b2 + kstep;
;             if (last && has_next) S.a_ready(nxt);
;             if constexpr (SP2) {
;             PG8_LDB(B0, 0, 0); PG8_LDB(B1, 0, 1); PG8_SCHED; PG8_LDA(At, 0, 0); PG8_STAGE(PG8_SA(1, 1), a1 + hstep, voffA);
;             PG8_WAIT_V(8); PG8_WAIT_L(0); PG8_BAR; __builtin_amdgcn_s_setprio(1); PG8_MMA_NP(0, 0, At, B0); PG8_MMA_NP(0, 1, At, B1); __builtin_amdgcn_s_setprio(0); PG8_BAR; PG8_SCHED;
;             PG8_LDA(At, 0, 1); PG8_STAGE(PG8_SB(0, 0), b2, voffB); PG8_STAGE(PG8_SB(0, 1), b2 + hstep, voffB); PG8_STAGE(PG8_SA(0, 0), a2, voffA);
;             PG8_WAIT_V(8); PG8_WAIT_L(0); PG8_BAR; __builtin_amdgcn_s_setprio(1); PG8_MMA_NP(1, 0, At, B0); PG8_MMA_NP(1, 1, At, B1); __builtin_amdgcn_s_setprio(0); PG8_BAR; PG8_SCHED;
;             PG8_LDB(B0, 1, 0); PG8_LDB(B1, 1, 1); PG8_SCHED; PG8_LDA(At, 1, 0); PG8_STAGE(PG8_SA(0, 1), a2 + hstep, voffA);
;             PG8_WAIT_V(8); PG8_WAIT_L(0); PG8_BAR; __builtin_amdgcn_s_setprio(1); PG8_MMA_NP(0, 0, At, B0); PG8_MMA_NP(0, 1, At, B1); __builtin_amdgcn_s_setprio(0); PG8_BAR; PG8_SCHED;
;             PG8_LDA(At, 1, 1); PG8_STAGE(PG8_SB(1, 0), b3, voffB); PG8_STAGE(PG8_SB(1, 1), b3 + hstep, voffB); PG8_STAGE(PG8_SA(1, 0), a3, voffA);
;             PG8_WAIT_V(8); PG8_WAIT_L(0); PG8_BAR; __builtin_amdgcn_s_setprio(1); PG8_MMA_NP(1, 0, At, B0); PG8_MMA_NP(1, 1, At, B1); __builtin_amdgcn_s_setprio(0); PG8_BAR; PG8_SCHED;
	s_add_i32 s14, s22, s29
	v_lshl_add_u64 v[162:163], v[162:163], 0, s[20:21]
	s_mov_b32 m0, s14
	ds_read_b128 v[206:209], v185 offset:49152
	ds_read_b128 v[210:213], v185 offset:50176
	ds_read_b128 v[214:217], v185 offset:51200
	ds_read_b128 v[218:221], v185 offset:52224
	ds_read_b128 v[222:225], v185 offset:53248
	ds_read_b128 v[226:229], v185 offset:54272
	ds_read_b128 v[230:233], v185 offset:55296
	ds_read_b128 v[234:237], v185 offset:56320
	global_load_lds_dwordx4 v[162:163], off
	s_add_i32 m0, s14, 0x2000
	s_add_u32 s12, s12, 0x40080
	v_lshl_add_u64 v[162:163], v[190:191], 0, s[20:21]
	s_addc_u32 s13, s13, 0
	s_add_i32 s14, s23, s29
	global_load_lds_dwordx4 v[162:163], off
	v_lshl_add_u64 v[162:163], s[12:13], 0, v[0:1]
	s_mov_b32 m0, s14
	s_nop 0
	global_load_lds_dwordx4 v[162:163], off
	v_lshl_add_u64 v[162:163], s[12:13], 0, v[134:135]
	s_add_i32 m0, s14, 0x2000
	s_nop 0
	global_load_lds_dwordx4 v[162:163], off
	v_lshl_add_u64 v[162:163], v[238:239], 0, s[20:21]
	s_mov_b32 m0, s54
	s_nop 0
	global_load_lds_dwordx4 v[162:163], off
	v_lshl_add_u64 v[162:163], v[240:241], 0, s[20:21]
	s_mov_b32 m0, s55
	s_nop 0
	global_load_lds_dwordx4 v[162:163], off
	s_waitcnt vmcnt(8)
	s_waitcnt lgkmcnt(0)
	s_barrier
	s_waitcnt lgkmcnt(0)
	v_mfma_f32_16x16x32_bf16 v[62:65], v[130:133], v[206:209], v[62:65]
	v_mfma_f32_16x16x32_bf16 v[54:57], v[150:153], v[206:209], v[54:57]
	v_mfma_f32_16x16x32_bf16 v[46:49], v[130:133], v[214:217], v[46:49]
	v_mfma_f32_16x16x32_bf16 v[38:41], v[150:153], v[214:217], v[38:41]
	v_mfma_f32_16x16x32_bf16 v[30:33], v[130:133], v[222:225], v[30:33]
	v_mfma_f32_16x16x32_bf16 v[22:25], v[150:153], v[222:225], v[22:25]
	v_mfma_f32_16x16x32_bf16 v[14:17], v[130:133], v[230:233], v[14:17]
	v_mfma_f32_16x16x32_bf16 v[6:9], v[150:153], v[230:233], v[6:9]
	v_mfma_f32_16x16x32_bf16 v[58:61], v[158:161], v[206:209], v[58:61]
	v_mfma_f32_16x16x32_bf16 v[50:53], v[186:189], v[206:209], v[50:53]
	v_mfma_f32_16x16x32_bf16 v[42:45], v[158:161], v[214:217], v[42:45]
	v_mfma_f32_16x16x32_bf16 v[34:37], v[186:189], v[214:217], v[34:37]
	v_mfma_f32_16x16x32_bf16 v[26:29], v[158:161], v[222:225], v[26:29]
	v_mfma_f32_16x16x32_bf16 v[18:21], v[186:189], v[222:225], v[18:21]
	v_mfma_f32_16x16x32_bf16 v[10:13], v[158:161], v[230:233], v[10:13]
	v_mfma_f32_16x16x32_bf16 v[2:5], v[186:189], v[230:233], v[2:5]
	v_mfma_f32_16x16x32_bf16 v[62:65], v[146:149], v[210:213], v[62:65]
	v_mfma_f32_16x16x32_bf16 v[54:57], v[154:157], v[210:213], v[54:57]
	v_mfma_f32_16x16x32_bf16 v[46:49], v[146:149], v[218:221], v[46:49]
	v_mfma_f32_16x16x32_bf16 v[38:41], v[154:157], v[218:221], v[38:41]
	v_mfma_f32_16x16x32_bf16 v[30:33], v[146:149], v[226:229], v[30:33]
	v_mfma_f32_16x16x32_bf16 v[22:25], v[154:157], v[226:229], v[22:25]
	v_mfma_f32_16x16x32_bf16 v[14:17], v[146:149], v[234:237], v[14:17]
	v_mfma_f32_16x16x32_bf16 v[6:9], v[154:157], v[234:237], v[6:9]
	v_mfma_f32_16x16x32_bf16 v[58:61], v[178:181], v[210:213], v[58:61]
	v_mfma_f32_16x16x32_bf16 v[50:53], v[202:205], v[210:213], v[50:53]
	v_mfma_f32_16x16x32_bf16 v[42:45], v[178:181], v[218:221], v[42:45]
	v_mfma_f32_16x16x32_bf16 v[34:37], v[202:205], v[218:221], v[34:37]
	v_mfma_f32_16x16x32_bf16 v[26:29], v[178:181], v[226:229], v[26:29]
	v_mfma_f32_16x16x32_bf16 v[18:21], v[202:205], v[226:229], v[18:21]
	v_mfma_f32_16x16x32_bf16 v[10:13], v[178:181], v[234:237], v[10:13]
	v_mfma_f32_16x16x32_bf16 v[2:5], v[202:205], v[234:237], v[2:5]
	s_barrier
	s_add_i32 s63, s63, 2
	s_add_u32 s2, s2, 0x100
	s_addc_u32 s3, s3, 0
	s_add_u32 s61, s61, 0x100
	s_addc_u32 s62, s62, 0
	s_cmp_gt_u32 s63, 13
	s_cbranch_scc0 .LBB0_1122
	s_branch .Lkexit_5
.LBB0_1122:
	s_add_u32 s12, s2, 0xfffc0080
	s_addc_u32 s13, s3, -1
	s_add_i32 s22, 0, 0x10000
	s_cmp_eq_u32 s63, 12
	s_cselect_b32 s15, s49, s13
	s_cselect_b32 s14, s59, s12
	s_cselect_b32 s13, s47, s62
	s_cselect_b32 s12, s60, s61
	s_add_i32 s64, 0, 0x14000
	v_add_u32_e32 v154, s22, v183
	v_add_u32_e32 v162, s64, v183
	ds_read_b128 v[130:133], v154
	ds_read_b128 v[146:149], v154 offset:1024
	ds_read_b128 v[150:153], v154 offset:2048
	ds_read_b128 v[154:157], v154 offset:3072
	ds_read_b128 v[158:161], v162
	ds_read_b128 v[178:181], v162 offset:1024
	ds_read_b128 v[186:189], v162 offset:2048
	ds_read_b128 v[202:205], v162 offset:3072
	v_lshl_add_u64 v[162:163], s[2:3], 0, v[142:143]
	s_add_i32 m0, s30, 0xc000
	ds_read_b128 v[206:209], v185
	ds_read_b128 v[210:213], v185 offset:1024
	ds_read_b128 v[214:217], v185 offset:2048
	ds_read_b128 v[218:221], v185 offset:3072
	ds_read_b128 v[222:225], v185 offset:4096
	ds_read_b128 v[226:229], v185 offset:5120
	ds_read_b128 v[230:233], v185 offset:6144
	ds_read_b128 v[234:237], v185 offset:7168
	global_load_lds_dwordx4 v[162:163], off
	v_lshl_add_u64 v[162:163], s[2:3], 0, v[144:145]
	s_add_i32 m0, s30, 0xe000
	s_nop 0
	global_load_lds_dwordx4 v[162:163], off
	s_waitcnt vmcnt(8)
	s_waitcnt lgkmcnt(0)
	s_barrier
; #define PG8_STAGE(bufoff, gbase, voff) do { _Pragma("unroll") for (int _i = 0; _i < 2; ++_i) \
;         __builtin_amdgcn_global_load_lds((const unsigned*)((const char*)(gbase) + (voff)[_i]), (PG8_LAS unsigned*)(lds + (bufoff) + ldsw + _i * 8192), 16, 0, 0); } while (0)
; #define PG8_LDA(dst, b, h) do { _Pragma("unroll") for (int m = 0; m < 4; ++m) _Pragma("unroll") for (int k = 0; k < 2; ++k) dst[m][k] = *(const PG8_LAS bf16x8*)(lds + PG8_SA(b, h) + aoff + m * 2048 + k * 1024); } while (0)
; #define PG8_MMA_NP(ai, bj, At, Bt) do { _Pragma("unroll") for (int m = 0; m < 4; ++m) _Pragma("unroll") for (int n = 0; n < 2; ++n) _Pragma("unroll") for (int k = 0; k < 2; ++k) \
;         acc[ai][bj][m][n] = __builtin_amdgcn_mfma_f32_16x16x32_bf16(Bt[n][k], At[m][k], acc[ai][bj][m][n], 0, 0, 0); } while (0)
; #define PG8_WAIT_V(n) asm volatile("s_waitcnt vmcnt(" #n ")" ::: "memory")
; #define PG8_WAIT_L(n) asm volatile("s_waitcnt lgkmcnt(" #n ")" ::: "memory")
; #define PG8_BAR __builtin_amdgcn_s_barrier()
; #define PG8_SCHED __builtin_amdgcn_sched_barrier(0)
; template <class Epi, class Sched, bool ALIGN_EPI = false, bool SP2 = false>
; __device__ __forceinline__ void gemm_phase(PG8_LAS unsigned char* lds, const Gemm g, const Sched& S, const Epi& E) {
;     ...
;             PG8_WAIT_V(8); PG8_WAIT_L(0); PG8_BAR; __builtin_amdgcn_s_setprio(1); PG8_MMA_NP(0, 0, At, B0); PG8_MMA_NP(0, 1, At, B1); __builtin_amdgcn_s_setprio(0); PG8_BAR; PG8_SCHED;
;             PG8_LDA(At, 0, 1); PG8_STAGE(PG8_SB(0, 0), b2, voffB); PG8_STAGE(PG8_SB(0, 1), b2 + hstep, voffB); PG8_STAGE(PG8_SA(0, 0), a2, voffA);
;             PG8_WAIT_V(8); PG8_WAIT_L(0); PG8_BAR; __builtin_amdgcn_s_setprio(1); PG8_MMA_NP(1, 0, At, B0); PG8_MMA_NP(1, 1, At, B1); __builtin_amdgcn_s_setprio(0); PG8_BAR; PG8_SCHED;
	s_waitcnt lgkmcnt(0)
	v_mfma_f32_16x16x32_bf16 v[126:129], v[130:133], v[206:209], v[126:129]
	v_mfma_f32_16x16x32_bf16 v[118:121], v[150:153], v[206:209], v[118:121]
	v_mfma_f32_16x16x32_bf16 v[110:113], v[130:133], v[214:217], v[110:113]
	v_mfma_f32_16x16x32_bf16 v[102:105], v[150:153], v[214:217], v[102:105]
	v_mfma_f32_16x16x32_bf16 v[94:97], v[130:133], v[222:225], v[94:97]
	v_mfma_f32_16x16x32_bf16 v[86:89], v[150:153], v[222:225], v[86:89]
	v_mfma_f32_16x16x32_bf16 v[78:81], v[130:133], v[230:233], v[78:81]
	v_mfma_f32_16x16x32_bf16 v[70:73], v[150:153], v[230:233], v[70:73]
	v_mfma_f32_16x16x32_bf16 v[122:125], v[158:161], v[206:209], v[122:125]
	v_mfma_f32_16x16x32_bf16 v[114:117], v[186:189], v[206:209], v[114:117]
	v_mfma_f32_16x16x32_bf16 v[106:109], v[158:161], v[214:217], v[106:109]
	v_mfma_f32_16x16x32_bf16 v[98:101], v[186:189], v[214:217], v[98:101]
	v_mfma_f32_16x16x32_bf16 v[90:93], v[158:161], v[222:225], v[90:93]
	v_mfma_f32_16x16x32_bf16 v[82:85], v[186:189], v[222:225], v[82:85]
	v_mfma_f32_16x16x32_bf16 v[74:77], v[158:161], v[230:233], v[74:77]
	v_mfma_f32_16x16x32_bf16 v[66:69], v[186:189], v[230:233], v[66:69]
	v_mfma_f32_16x16x32_bf16 v[126:129], v[146:149], v[210:213], v[126:129]
	v_mfma_f32_16x16x32_bf16 v[118:121], v[154:157], v[210:213], v[118:121]
	v_mfma_f32_16x16x32_bf16 v[110:113], v[146:149], v[218:221], v[110:113]
	v_mfma_f32_16x16x32_bf16 v[102:105], v[154:157], v[218:221], v[102:105]
	v_mfma_f32_16x16x32_bf16 v[94:97], v[146:149], v[226:229], v[94:97]
	v_mfma_f32_16x16x32_bf16 v[86:89], v[154:157], v[226:229], v[86:89]
	v_mfma_f32_16x16x32_bf16 v[78:81], v[146:149], v[234:237], v[78:81]
	v_mfma_f32_16x16x32_bf16 v[70:73], v[154:157], v[234:237], v[70:73]
	v_mfma_f32_16x16x32_bf16 v[122:125], v[178:181], v[210:213], v[122:125]
	v_mfma_f32_16x16x32_bf16 v[114:117], v[202:205], v[210:213], v[114:117]
	v_mfma_f32_16x16x32_bf16 v[106:109], v[178:181], v[218:221], v[106:109]
	v_mfma_f32_16x16x32_bf16 v[98:101], v[202:205], v[218:221], v[98:101]
	v_mfma_f32_16x16x32_bf16 v[90:93], v[178:181], v[226:229], v[90:93]
	v_mfma_f32_16x16x32_bf16 v[82:85], v[202:205], v[226:229], v[82:85]
	v_mfma_f32_16x16x32_bf16 v[74:77], v[178:181], v[234:237], v[74:77]
	v_mfma_f32_16x16x32_bf16 v[66:69], v[202:205], v[234:237], v[66:69]
	s_barrier
	s_add_i32 s22, s22, s29
	v_lshl_add_u64 v[162:163], s[12:13], 0, v[0:1]
	s_mov_b32 m0, s22
	ds_read_b128 v[206:209], v185 offset:16384
	ds_read_b128 v[210:213], v185 offset:17408
	ds_read_b128 v[214:217], v185 offset:18432
	ds_read_b128 v[218:221], v185 offset:19456
	ds_read_b128 v[222:225], v185 offset:20480
	ds_read_b128 v[226:229], v185 offset:21504
	ds_read_b128 v[230:233], v185 offset:22528
	ds_read_b128 v[234:237], v185 offset:23552
	global_load_lds_dwordx4 v[162:163], off
	s_add_i32 m0, s22, 0x2000
	s_add_u32 s22, s12, 0x40000
	v_lshl_add_u64 v[190:191], s[12:13], 0, v[134:135]
	s_addc_u32 s23, s13, 0
	s_add_i32 s64, s64, s29
	global_load_lds_dwordx4 v[190:191], off
	v_lshl_add_u64 v[238:239], s[22:23], 0, v[0:1]
	s_mov_b32 m0, s64
	v_lshl_add_u64 v[240:241], s[14:15], 0, v[136:137]
	global_load_lds_dwordx4 v[238:239], off
	v_lshl_add_u64 v[238:239], s[22:23], 0, v[134:135]
	s_add_i32 m0, s64, 0x2000
	s_nop 0
	global_load_lds_dwordx4 v[238:239], off
	v_lshl_add_u64 v[238:239], s[14:15], 0, v[138:139]
	s_mov_b32 m0, s30
	s_nop 0
	global_load_lds_dwordx4 v[238:239], off
	s_mov_b32 m0, s31
	s_nop 0
	global_load_lds_dwordx4 v[240:241], off
	s_waitcnt vmcnt(8)
	s_waitcnt lgkmcnt(0)
	s_barrier
	s_waitcnt lgkmcnt(0)
	v_mfma_f32_16x16x32_bf16 v[62:65], v[130:133], v[206:209], v[62:65]
	v_mfma_f32_16x16x32_bf16 v[54:57], v[150:153], v[206:209], v[54:57]
	v_mfma_f32_16x16x32_bf16 v[46:49], v[130:133], v[214:217], v[46:49]
	v_mfma_f32_16x16x32_bf16 v[38:41], v[150:153], v[214:217], v[38:41]
	v_mfma_f32_16x16x32_bf16 v[30:33], v[130:133], v[222:225], v[30:33]
	v_mfma_f32_16x16x32_bf16 v[22:25], v[150:153], v[222:225], v[22:25]
	v_mfma_f32_16x16x32_bf16 v[14:17], v[130:133], v[230:233], v[14:17]
	v_mfma_f32_16x16x32_bf16 v[6:9], v[150:153], v[230:233], v[6:9]
	v_mfma_f32_16x16x32_bf16 v[58:61], v[158:161], v[206:209], v[58:61]
	v_mfma_f32_16x16x32_bf16 v[50:53], v[186:189], v[206:209], v[50:53]
	v_mfma_f32_16x16x32_bf16 v[42:45], v[158:161], v[214:217], v[42:45]
	v_mfma_f32_16x16x32_bf16 v[34:37], v[186:189], v[214:217], v[34:37]
	v_mfma_f32_16x16x32_bf16 v[26:29], v[158:161], v[222:225], v[26:29]
	v_mfma_f32_16x16x32_bf16 v[18:21], v[186:189], v[222:225], v[18:21]
	v_mfma_f32_16x16x32_bf16 v[10:13], v[158:161], v[230:233], v[10:13]
	v_mfma_f32_16x16x32_bf16 v[2:5], v[186:189], v[230:233], v[2:5]
	v_mfma_f32_16x16x32_bf16 v[62:65], v[146:149], v[210:213], v[62:65]
	v_mfma_f32_16x16x32_bf16 v[54:57], v[154:157], v[210:213], v[54:57]
	v_mfma_f32_16x16x32_bf16 v[46:49], v[146:149], v[218:221], v[46:49]
	v_mfma_f32_16x16x32_bf16 v[38:41], v[154:157], v[218:221], v[38:41]
	v_mfma_f32_16x16x32_bf16 v[30:33], v[146:149], v[226:229], v[30:33]
	v_mfma_f32_16x16x32_bf16 v[22:25], v[154:157], v[226:229], v[22:25]
	v_mfma_f32_16x16x32_bf16 v[14:17], v[146:149], v[234:237], v[14:17]
	v_mfma_f32_16x16x32_bf16 v[6:9], v[154:157], v[234:237], v[6:9]
	v_mfma_f32_16x16x32_bf16 v[58:61], v[178:181], v[210:213], v[58:61]
	v_mfma_f32_16x16x32_bf16 v[50:53], v[202:205], v[210:213], v[50:53]
	v_mfma_f32_16x16x32_bf16 v[42:45], v[178:181], v[218:221], v[42:45]
	v_mfma_f32_16x16x32_bf16 v[34:37], v[202:205], v[218:221], v[34:37]
	v_mfma_f32_16x16x32_bf16 v[26:29], v[178:181], v[226:229], v[26:29]
	v_mfma_f32_16x16x32_bf16 v[18:21], v[202:205], v[226:229], v[18:21]
	v_mfma_f32_16x16x32_bf16 v[10:13], v[178:181], v[234:237], v[10:13]
	v_mfma_f32_16x16x32_bf16 v[2:5], v[202:205], v[234:237], v[2:5]
	s_barrier
; #define PG8_STAGE(bufoff, gbase, voff) do { _Pragma("unroll") for (int _i = 0; _i < 2; ++_i) \
;         __builtin_amdgcn_global_load_lds((const unsigned*)((const char*)(gbase) + (voff)[_i]), (PG8_LAS unsigned*)(lds + (bufoff) + ldsw + _i * 8192), 16, 0, 0); } while (0)
; #define PG8_LDA(dst, b, h) do { _Pragma("unroll") for (int m = 0; m < 4; ++m) _Pragma("unroll") for (int k = 0; k < 2; ++k) dst[m][k] = *(const PG8_LAS bf16x8*)(lds + PG8_SA(b, h) + aoff + m * 2048 + k * 1024); } while (0)
; #define PG8_LDB(dst, b, h) do { _Pragma("unroll") for (int n = 0; n < 2; ++n) _Pragma("unroll") for (int k = 0; k < 2; ++k) dst[n][k] = *(const PG8_LAS bf16x8*)(lds + PG8_SB(b, h) + boff + n * 2048 + k * 1024); } while (0)
; #define PG8_MMA_NP(ai, bj, At, Bt) do { _Pragma("unroll") for (int m = 0; m < 4; ++m) _Pragma("unroll") for (int n = 0; n < 2; ++n) _Pragma("unroll") for (int k = 0; k < 2; ++k) \
;         acc[ai][bj][m][n] = __builtin_amdgcn_mfma_f32_16x16x32_bf16(Bt[n][k], At[m][k], acc[ai][bj][m][n], 0, 0, 0); } while (0)
; #define PG8_WAIT_V(n) asm volatile("s_waitcnt vmcnt(" #n ")" ::: "memory")
; #define PG8_WAIT_L(n) asm volatile("s_waitcnt lgkmcnt(" #n ")" ::: "memory")
; #define PG8_BAR __builtin_amdgcn_s_barrier()
; #define PG8_SCHED __builtin_amdgcn_sched_barrier(0)
; template <class Epi, class Sched, bool ALIGN_EPI = false, bool SP2 = false>
; __device__ __forceinline__ void gemm_phase(PG8_LAS unsigned char* lds, const Gemm g, const Sched& S, const Epi& E) {
;     ...
;             PG8_LDB(B0, 1, 0); PG8_LDB(B1, 1, 1); PG8_SCHED; PG8_LDA(At, 1, 0); PG8_STAGE(PG8_SA(0, 1), a2 + hstep, voffA);
;             PG8_WAIT_V(8); PG8_WAIT_L(0); PG8_BAR; __builtin_amdgcn_s_setprio(1); PG8_MMA_NP(0, 0, At, B0); PG8_MMA_NP(0, 1, At, B1); __builtin_amdgcn_s_setprio(0); PG8_BAR; PG8_SCHED;
	s_add_i32 s22, 0, 0x18000
	s_add_i32 s23, 0, 0x1c000
	v_add_u32_e32 v154, s22, v183
	v_add_u32_e32 v202, s23, v183
	ds_read_b128 v[130:133], v154
	ds_read_b128 v[146:149], v154 offset:1024
	ds_read_b128 v[150:153], v154 offset:2048
	ds_read_b128 v[154:157], v154 offset:3072
	ds_read_b128 v[158:161], v202
	ds_read_b128 v[178:181], v202 offset:1024
	ds_read_b128 v[186:189], v202 offset:2048
	ds_read_b128 v[202:205], v202 offset:3072
	s_add_u32 s14, s14, 0x40000
	s_addc_u32 s15, s15, 0
	s_mov_b32 m0, s40
	v_lshl_add_u64 v[242:243], s[14:15], 0, v[138:139]
	ds_read_b128 v[206:209], v185 offset:32768
	ds_read_b128 v[210:213], v185 offset:33792
	ds_read_b128 v[214:217], v185 offset:34816
	ds_read_b128 v[218:221], v185 offset:35840
	ds_read_b128 v[222:225], v185 offset:36864
	ds_read_b128 v[226:229], v185 offset:37888
	ds_read_b128 v[230:233], v185 offset:38912
	ds_read_b128 v[234:237], v185 offset:39936
	global_load_lds_dwordx4 v[242:243], off
	v_lshl_add_u64 v[242:243], s[14:15], 0, v[136:137]
	s_mov_b32 m0, s41
	s_nop 0
	global_load_lds_dwordx4 v[242:243], off
	s_waitcnt vmcnt(8)
	s_waitcnt lgkmcnt(0)
	s_barrier
	s_waitcnt lgkmcnt(0)
	v_mfma_f32_16x16x32_bf16 v[126:129], v[130:133], v[206:209], v[126:129]
	v_mfma_f32_16x16x32_bf16 v[118:121], v[150:153], v[206:209], v[118:121]
	v_mfma_f32_16x16x32_bf16 v[110:113], v[130:133], v[214:217], v[110:113]
	v_mfma_f32_16x16x32_bf16 v[102:105], v[150:153], v[214:217], v[102:105]
	v_mfma_f32_16x16x32_bf16 v[94:97], v[130:133], v[222:225], v[94:97]
	v_mfma_f32_16x16x32_bf16 v[86:89], v[150:153], v[222:225], v[86:89]
	v_mfma_f32_16x16x32_bf16 v[78:81], v[130:133], v[230:233], v[78:81]
	v_mfma_f32_16x16x32_bf16 v[70:73], v[150:153], v[230:233], v[70:73]
	v_mfma_f32_16x16x32_bf16 v[122:125], v[158:161], v[206:209], v[122:125]
	v_mfma_f32_16x16x32_bf16 v[114:117], v[186:189], v[206:209], v[114:117]
	v_mfma_f32_16x16x32_bf16 v[106:109], v[158:161], v[214:217], v[106:109]
	v_mfma_f32_16x16x32_bf16 v[98:101], v[186:189], v[214:217], v[98:101]
	v_mfma_f32_16x16x32_bf16 v[90:93], v[158:161], v[222:225], v[90:93]
	v_mfma_f32_16x16x32_bf16 v[82:85], v[186:189], v[222:225], v[82:85]
	v_mfma_f32_16x16x32_bf16 v[74:77], v[158:161], v[230:233], v[74:77]
	v_mfma_f32_16x16x32_bf16 v[66:69], v[186:189], v[230:233], v[66:69]
	v_mfma_f32_16x16x32_bf16 v[126:129], v[146:149], v[210:213], v[126:129]
	v_mfma_f32_16x16x32_bf16 v[118:121], v[154:157], v[210:213], v[118:121]
	v_mfma_f32_16x16x32_bf16 v[110:113], v[146:149], v[218:221], v[110:113]
	v_mfma_f32_16x16x32_bf16 v[102:105], v[154:157], v[218:221], v[102:105]
	v_mfma_f32_16x16x32_bf16 v[94:97], v[146:149], v[226:229], v[94:97]
	v_mfma_f32_16x16x32_bf16 v[86:89], v[154:157], v[226:229], v[86:89]
	v_mfma_f32_16x16x32_bf16 v[78:81], v[146:149], v[234:237], v[78:81]
	v_mfma_f32_16x16x32_bf16 v[70:73], v[154:157], v[234:237], v[70:73]
	v_mfma_f32_16x16x32_bf16 v[122:125], v[178:181], v[210:213], v[122:125]
	v_mfma_f32_16x16x32_bf16 v[114:117], v[202:205], v[210:213], v[114:117]
	v_mfma_f32_16x16x32_bf16 v[106:109], v[178:181], v[218:221], v[106:109]
	v_mfma_f32_16x16x32_bf16 v[98:101], v[202:205], v[218:221], v[98:101]
	v_mfma_f32_16x16x32_bf16 v[90:93], v[178:181], v[226:229], v[90:93]
	v_mfma_f32_16x16x32_bf16 v[82:85], v[202:205], v[226:229], v[82:85]
	v_mfma_f32_16x16x32_bf16 v[74:77], v[178:181], v[234:237], v[74:77]
	v_mfma_f32_16x16x32_bf16 v[66:69], v[202:205], v[234:237], v[66:69]
	s_barrier
; #define PG8_STAGE(bufoff, gbase, voff) do { _Pragma("unroll") for (int _i = 0; _i < 2; ++_i) \
;         __builtin_amdgcn_global_load_lds((const unsigned*)((const char*)(gbase) + (voff)[_i]), (PG8_LAS unsigned*)(lds + (bufoff) + ldsw + _i * 8192), 16, 0, 0); } while (0)
; #define PG8_LDA(dst, b, h) do { _Pragma("unroll") for (int m = 0; m < 4; ++m) _Pragma("unroll") for (int k = 0; k < 2; ++k) dst[m][k] = *(const PG8_LAS bf16x8*)(lds + PG8_SA(b, h) + aoff + m * 2048 + k * 1024); } while (0)
; #define PG8_MMA_NP(ai, bj, At, Bt) do { _Pragma("unroll") for (int m = 0; m < 4; ++m) _Pragma("unroll") for (int n = 0; n < 2; ++n) _Pragma("unroll") for (int k = 0; k < 2; ++k) \
;         acc[ai][bj][m][n] = __builtin_amdgcn_mfma_f32_16x16x32_bf16(Bt[n][k], At[m][k], acc[ai][bj][m][n], 0, 0, 0); } while (0)
; #define PG8_WAIT_V(n) asm volatile("s_waitcnt vmcnt(" #n ")" ::: "memory")
; #define PG8_WAIT_L(n) asm volatile("s_waitcnt lgkmcnt(" #n ")" ::: "memory")
; #define PG8_BAR __builtin_amdgcn_s_barrier()
; #define PG8_SCHED __builtin_amdgcn_sched_barrier(0)
; template <class Epi, class Sched, bool ALIGN_EPI = false, bool SP2 = false>
; __device__ __forceinline__ void gemm_phase(PG8_LAS unsigned char* lds, const Gemm g, const Sched& S, const Epi& E) {
;     ...
;             PG8_LDA(At, 1, 1); PG8_STAGE(PG8_SB(1, 0), b3, voffB); PG8_STAGE(PG8_SB(1, 1), b3 + hstep, voffB); PG8_STAGE(PG8_SA(1, 0), a3, voffA);
;             PG8_WAIT_V(8); PG8_WAIT_L(0); PG8_BAR; __builtin_amdgcn_s_setprio(1); PG8_MMA_NP(1, 0, At, B0); PG8_MMA_NP(1, 1, At, B1); __builtin_amdgcn_s_setprio(0); PG8_BAR; PG8_SCHED;
	s_add_i32 s14, s22, s29
	v_lshl_add_u64 v[162:163], v[162:163], 0, s[20:21]
	s_mov_b32 m0, s14
	ds_read_b128 v[206:209], v185 offset:49152
	ds_read_b128 v[210:213], v185 offset:50176
	ds_read_b128 v[214:217], v185 offset:51200
	ds_read_b128 v[218:221], v185 offset:52224
	ds_read_b128 v[222:225], v185 offset:53248
	ds_read_b128 v[226:229], v185 offset:54272
	ds_read_b128 v[230:233], v185 offset:55296
	ds_read_b128 v[234:237], v185 offset:56320
	global_load_lds_dwordx4 v[162:163], off
	s_add_i32 m0, s14, 0x2000
	s_add_u32 s12, s12, 0x40080
	v_lshl_add_u64 v[162:163], v[190:191], 0, s[20:21]
	s_addc_u32 s13, s13, 0
	s_add_i32 s14, s23, s29
	global_load_lds_dwordx4 v[162:163], off
	v_lshl_add_u64 v[162:163], s[12:13], 0, v[0:1]
	s_mov_b32 m0, s14
	s_nop 0
	global_load_lds_dwordx4 v[162:163], off
	v_lshl_add_u64 v[162:163], s[12:13], 0, v[134:135]
	s_add_i32 m0, s14, 0x2000
	s_nop 0
	global_load_lds_dwordx4 v[162:163], off
	v_lshl_add_u64 v[162:163], v[238:239], 0, s[20:21]
	s_mov_b32 m0, s54
	s_nop 0
	global_load_lds_dwordx4 v[162:163], off
	v_lshl_add_u64 v[162:163], v[240:241], 0, s[20:21]
	s_mov_b32 m0, s55
	s_nop 0
	global_load_lds_dwordx4 v[162:163], off
	s_waitcnt vmcnt(8)
	s_waitcnt lgkmcnt(0)
	s_barrier
	s_waitcnt lgkmcnt(0)
	v_mfma_f32_16x16x32_bf16 v[62:65], v[130:133], v[206:209], v[62:65]
	v_mfma_f32_16x16x32_bf16 v[54:57], v[150:153], v[206:209], v[54:57]
	v_mfma_f32_16x16x32_bf16 v[46:49], v[130:133], v[214:217], v[46:49]
	v_mfma_f32_16x16x32_bf16 v[38:41], v[150:153], v[214:217], v[38:41]
	v_mfma_f32_16x16x32_bf16 v[30:33], v[130:133], v[222:225], v[30:33]
	v_mfma_f32_16x16x32_bf16 v[22:25], v[150:153], v[222:225], v[22:25]
	v_mfma_f32_16x16x32_bf16 v[14:17], v[130:133], v[230:233], v[14:17]
	v_mfma_f32_16x16x32_bf16 v[6:9], v[150:153], v[230:233], v[6:9]
	v_mfma_f32_16x16x32_bf16 v[58:61], v[158:161], v[206:209], v[58:61]
	v_mfma_f32_16x16x32_bf16 v[50:53], v[186:189], v[206:209], v[50:53]
	v_mfma_f32_16x16x32_bf16 v[42:45], v[158:161], v[214:217], v[42:45]
	v_mfma_f32_16x16x32_bf16 v[34:37], v[186:189], v[214:217], v[34:37]
	v_mfma_f32_16x16x32_bf16 v[26:29], v[158:161], v[222:225], v[26:29]
	v_mfma_f32_16x16x32_bf16 v[18:21], v[186:189], v[222:225], v[18:21]
	v_mfma_f32_16x16x32_bf16 v[10:13], v[158:161], v[230:233], v[10:13]
	v_mfma_f32_16x16x32_bf16 v[2:5], v[186:189], v[230:233], v[2:5]
	v_mfma_f32_16x16x32_bf16 v[62:65], v[146:149], v[210:213], v[62:65]
	v_mfma_f32_16x16x32_bf16 v[54:57], v[154:157], v[210:213], v[54:57]
	v_mfma_f32_16x16x32_bf16 v[46:49], v[146:149], v[218:221], v[46:49]
	v_mfma_f32_16x16x32_bf16 v[38:41], v[154:157], v[218:221], v[38:41]
	v_mfma_f32_16x16x32_bf16 v[30:33], v[146:149], v[226:229], v[30:33]
	v_mfma_f32_16x16x32_bf16 v[22:25], v[154:157], v[226:229], v[22:25]
	v_mfma_f32_16x16x32_bf16 v[14:17], v[146:149], v[234:237], v[14:17]
	v_mfma_f32_16x16x32_bf16 v[6:9], v[154:157], v[234:237], v[6:9]
	v_mfma_f32_16x16x32_bf16 v[58:61], v[178:181], v[210:213], v[58:61]
	v_mfma_f32_16x16x32_bf16 v[50:53], v[202:205], v[210:213], v[50:53]
	v_mfma_f32_16x16x32_bf16 v[42:45], v[178:181], v[218:221], v[42:45]
	v_mfma_f32_16x16x32_bf16 v[34:37], v[202:205], v[218:221], v[34:37]
	v_mfma_f32_16x16x32_bf16 v[26:29], v[178:181], v[226:229], v[26:29]
	v_mfma_f32_16x16x32_bf16 v[18:21], v[202:205], v[226:229], v[18:21]
	v_mfma_f32_16x16x32_bf16 v[10:13], v[178:181], v[234:237], v[10:13]
	v_mfma_f32_16x16x32_bf16 v[2:5], v[202:205], v[234:237], v[2:5]
	s_barrier
	s_add_i32 s63, s63, 2
	s_add_u32 s2, s2, 0x100
	s_addc_u32 s3, s3, 0
	s_add_u32 s61, s61, 0x100
	s_addc_u32 s62, s62, 0
	s_cmp_gt_u32 s63, 13
	s_cbranch_scc0 .LBB0_1122

; #define PG8_STAGE(bufoff, gbase, voff) do { _Pragma("unroll") for (int _i = 0; _i < 2; ++_i) \
;         __builtin_amdgcn_global_load_lds((const unsigned*)((const char*)(gbase) + (voff)[_i]), (PG8_LAS unsigned*)(lds + (bufoff) + ldsw + _i * 8192), 16, 0, 0); } while (0)
; #define PG8_LDA(dst, b, h) do { _Pragma("unroll") for (int m = 0; m < 4; ++m) _Pragma("unroll") for (int k = 0; k < 2; ++k) dst[m][k] = *(const PG8_LAS bf16x8*)(lds + PG8_SA(b, h) + aoff + m * 2048 + k * 1024); } while (0)
; #define PG8_LDB(dst, b, h) do { _Pragma("unroll") for (int n = 0; n < 2; ++n) _Pragma("unroll") for (int k = 0; k < 2; ++k) dst[n][k] = *(const PG8_LAS bf16x8*)(lds + PG8_SB(b, h) + boff + n * 2048 + k * 1024); } while (0)
; #define PG8_MMA_NP(ai, bj, At, Bt) do { _Pragma("unroll") for (int m = 0; m < 4; ++m) _Pragma("unroll") for (int n = 0; n < 2; ++n) _Pragma("unroll") for (int k = 0; k < 2; ++k) \
;         acc[ai][bj][m][n] = __builtin_amdgcn_mfma_f32_16x16x32_bf16(Bt[n][k], At[m][k], acc[ai][bj][m][n], 0, 0, 0); } while (0)
; #define PG8_WAIT_V(n) asm volatile("s_waitcnt vmcnt(" #n ")" ::: "memory")
; #define PG8_WAIT_L(n) asm volatile("s_waitcnt lgkmcnt(" #n ")" ::: "memory")
; #define PG8_BAR __builtin_amdgcn_s_barrier()
; #define PG8_SCHED __builtin_amdgcn_sched_barrier(0)
; template <class Epi, class Sched, bool ALIGN_EPI = false, bool SP2 = false>
; __device__ __forceinline__ void gemm_phase(PG8_LAS unsigned char* lds, const Gemm g, const Sched& S, const Epi& E) {
;     ...
;             PG8_LDB(B0, 0, 0); PG8_LDB(B1, 0, 1); PG8_SCHED; PG8_LDA(At, 0, 0); PG8_STAGE(PG8_SA(1, 1), a1 + hstep, voffA);
;             PG8_WAIT_V(8); PG8_WAIT_L(0); PG8_BAR; __builtin_amdgcn_s_setprio(1); PG8_MMA_NP(0, 0, At, B0); PG8_MMA_NP(0, 1, At, B1); __builtin_amdgcn_s_setprio(0); PG8_BAR; PG8_SCHED;
;             PG8_LDA(At, 0, 1); PG8_STAGE(PG8_SB(0, 0), b2, voffB); PG8_STAGE(PG8_SB(0, 1), b2 + hstep, voffB); PG8_STAGE(PG8_SA(0, 0), a2, voffA);
;             PG8_WAIT_V(8); PG8_WAIT_L(0); PG8_BAR; __builtin_amdgcn_s_setprio(1); PG8_MMA_NP(1, 0, At, B0); PG8_MMA_NP(1, 1, At, B1); __builtin_amdgcn_s_setprio(0); PG8_BAR; PG8_SCHED;
.LBB0_1220:
	s_add_u32 s48, s12, 0x100
	s_addc_u32 s49, s13, 0
	s_add_i32 s22, 0, 0x10000
	s_cmp_eq_u32 s64, 40
	s_cselect_b32 s51, s43, s49
	s_cselect_b32 s50, s42, s48
	v_add_u32_e32 v144, s22, v147
	s_cselect_b32 s15, s47, s63
	s_cselect_b32 s14, s46, s62
	s_add_i32 s23, 0, 0x14000
	ds_read_b128 v[140:143], v144
	ds_read_b128 v[150:153], v144 offset:1024
	ds_read_b128 v[154:157], v144 offset:2048
	ds_read_b128 v[158:161], v144 offset:3072
	v_add_u32_e32 v144, s23, v147
	ds_read_b128 v[178:181], v144
	ds_read_b128 v[182:185], v144 offset:1024
	ds_read_b128 v[186:189], v144 offset:2048
	ds_read_b128 v[202:205], v144 offset:3072
	v_lshl_add_u64 v[144:145], s[12:13], 0, v[136:137]
	s_add_i32 m0, s52, 0xc000
	ds_read_b128 v[206:209], v149
	ds_read_b128 v[210:213], v149 offset:1024
	ds_read_b128 v[214:217], v149 offset:2048
	ds_read_b128 v[218:221], v149 offset:3072
	ds_read_b128 v[222:225], v149 offset:4096
	ds_read_b128 v[226:229], v149 offset:5120
	ds_read_b128 v[230:233], v149 offset:6144
	ds_read_b128 v[234:237], v149 offset:7168
	global_load_lds_dwordx4 v[144:145], off
	v_lshl_add_u64 v[144:145], s[12:13], 0, v[138:139]
	s_add_i32 m0, s52, 0xe000
	s_nop 0
	global_load_lds_dwordx4 v[144:145], off
	s_waitcnt vmcnt(8)
	s_waitcnt lgkmcnt(0)
	s_barrier
	s_waitcnt lgkmcnt(0)
	v_mfma_f32_16x16x32_bf16 v[126:129], v[140:143], v[206:209], v[126:129]
	v_mfma_f32_16x16x32_bf16 v[122:125], v[154:157], v[206:209], v[122:125]
	v_mfma_f32_16x16x32_bf16 v[110:113], v[140:143], v[214:217], v[110:113]
	v_mfma_f32_16x16x32_bf16 v[106:109], v[154:157], v[214:217], v[106:109]
	v_mfma_f32_16x16x32_bf16 v[94:97], v[140:143], v[222:225], v[94:97]
	v_mfma_f32_16x16x32_bf16 v[90:93], v[154:157], v[222:225], v[90:93]
	v_mfma_f32_16x16x32_bf16 v[78:81], v[140:143], v[230:233], v[78:81]
	v_mfma_f32_16x16x32_bf16 v[74:77], v[154:157], v[230:233], v[74:77]
	v_mfma_f32_16x16x32_bf16 v[118:121], v[178:181], v[206:209], v[118:121]
	v_mfma_f32_16x16x32_bf16 v[114:117], v[186:189], v[206:209], v[114:117]
	v_mfma_f32_16x16x32_bf16 v[102:105], v[178:181], v[214:217], v[102:105]
	v_mfma_f32_16x16x32_bf16 v[98:101], v[186:189], v[214:217], v[98:101]
	v_mfma_f32_16x16x32_bf16 v[86:89], v[178:181], v[222:225], v[86:89]
	v_mfma_f32_16x16x32_bf16 v[82:85], v[186:189], v[222:225], v[82:85]
	v_mfma_f32_16x16x32_bf16 v[70:73], v[178:181], v[230:233], v[70:73]
	v_mfma_f32_16x16x32_bf16 v[66:69], v[186:189], v[230:233], v[66:69]
	v_mfma_f32_16x16x32_bf16 v[126:129], v[150:153], v[210:213], v[126:129]
	v_mfma_f32_16x16x32_bf16 v[122:125], v[158:161], v[210:213], v[122:125]
	v_mfma_f32_16x16x32_bf16 v[110:113], v[150:153], v[218:221], v[110:113]
	v_mfma_f32_16x16x32_bf16 v[106:109], v[158:161], v[218:221], v[106:109]
	v_mfma_f32_16x16x32_bf16 v[94:97], v[150:153], v[226:229], v[94:97]
	v_mfma_f32_16x16x32_bf16 v[90:93], v[158:161], v[226:229], v[90:93]
	v_mfma_f32_16x16x32_bf16 v[78:81], v[150:153], v[234:237], v[78:81]
	v_mfma_f32_16x16x32_bf16 v[74:77], v[158:161], v[234:237], v[74:77]
	v_mfma_f32_16x16x32_bf16 v[118:121], v[182:185], v[210:213], v[118:121]
	v_mfma_f32_16x16x32_bf16 v[114:117], v[202:205], v[210:213], v[114:117]
	v_mfma_f32_16x16x32_bf16 v[102:105], v[182:185], v[218:221], v[102:105]
	v_mfma_f32_16x16x32_bf16 v[98:101], v[202:205], v[218:221], v[98:101]
	v_mfma_f32_16x16x32_bf16 v[86:89], v[182:185], v[226:229], v[86:89]
	v_mfma_f32_16x16x32_bf16 v[82:85], v[202:205], v[226:229], v[82:85]
	v_mfma_f32_16x16x32_bf16 v[70:73], v[182:185], v[234:237], v[70:73]
	v_mfma_f32_16x16x32_bf16 v[66:69], v[202:205], v[234:237], v[66:69]
	s_barrier
	s_add_i32 s12, s22, s31
	v_lshl_add_u64 v[144:145], s[14:15], 0, v[0:1]
	s_mov_b32 m0, s12
	ds_read_b128 v[206:209], v149 offset:16384
	ds_read_b128 v[210:213], v149 offset:17408
	ds_read_b128 v[214:217], v149 offset:18432
	ds_read_b128 v[218:221], v149 offset:19456
	ds_read_b128 v[222:225], v149 offset:20480
	ds_read_b128 v[226:229], v149 offset:21504
	ds_read_b128 v[230:233], v149 offset:22528
	ds_read_b128 v[234:237], v149 offset:23552
	global_load_lds_dwordx4 v[144:145], off
	s_add_i32 m0, s12, 0x2000
	s_add_u32 s12, s14, 0xb0000
	v_lshl_add_u64 v[162:163], s[14:15], 0, v[130:131]
	s_addc_u32 s13, s15, 0
	s_add_i32 s22, s23, s31
	global_load_lds_dwordx4 v[162:163], off
	v_lshl_add_u64 v[190:191], s[12:13], 0, v[0:1]
	s_mov_b32 m0, s22
	v_lshl_add_u64 v[238:239], s[50:51], 0, v[132:133]
	global_load_lds_dwordx4 v[190:191], off
	v_lshl_add_u64 v[190:191], s[12:13], 0, v[130:131]
	s_add_i32 m0, s22, 0x2000
	s_nop 0
	global_load_lds_dwordx4 v[190:191], off
	v_lshl_add_u64 v[190:191], s[50:51], 0, v[134:135]
	s_mov_b32 m0, s52
	s_nop 0
	global_load_lds_dwordx4 v[190:191], off
	s_mov_b32 m0, s53
	s_nop 0
	global_load_lds_dwordx4 v[238:239], off
	s_waitcnt vmcnt(8)
	s_waitcnt lgkmcnt(0)
	s_barrier
; #define PG8_STAGE(bufoff, gbase, voff) do { _Pragma("unroll") for (int _i = 0; _i < 2; ++_i) \
;         __builtin_amdgcn_global_load_lds((const unsigned*)((const char*)(gbase) + (voff)[_i]), (PG8_LAS unsigned*)(lds + (bufoff) + ldsw + _i * 8192), 16, 0, 0); } while (0)
; #define PG8_LDA(dst, b, h) do { _Pragma("unroll") for (int m = 0; m < 4; ++m) _Pragma("unroll") for (int k = 0; k < 2; ++k) dst[m][k] = *(const PG8_LAS bf16x8*)(lds + PG8_SA(b, h) + aoff + m * 2048 + k * 1024); } while (0)
; #define PG8_LDB(dst, b, h) do { _Pragma("unroll") for (int n = 0; n < 2; ++n) _Pragma("unroll") for (int k = 0; k < 2; ++k) dst[n][k] = *(const PG8_LAS bf16x8*)(lds + PG8_SB(b, h) + boff + n * 2048 + k * 1024); } while (0)
; #define PG8_MMA_NP(ai, bj, At, Bt) do { _Pragma("unroll") for (int m = 0; m < 4; ++m) _Pragma("unroll") for (int n = 0; n < 2; ++n) _Pragma("unroll") for (int k = 0; k < 2; ++k) \
;         acc[ai][bj][m][n] = __builtin_amdgcn_mfma_f32_16x16x32_bf16(Bt[n][k], At[m][k], acc[ai][bj][m][n], 0, 0, 0); } while (0)
; #define PG8_WAIT_V(n) asm volatile("s_waitcnt vmcnt(" #n ")" ::: "memory")
; #define PG8_WAIT_L(n) asm volatile("s_waitcnt lgkmcnt(" #n ")" ::: "memory")
; #define PG8_BAR __builtin_amdgcn_s_barrier()
; #define PG8_SCHED __builtin_amdgcn_sched_barrier(0)
; template <class Epi, class Sched, bool ALIGN_EPI = false, bool SP2 = false>
; __device__ __forceinline__ void gemm_phase(PG8_LAS unsigned char* lds, const Gemm g, const Sched& S, const Epi& E) {
;     ...
;             PG8_WAIT_V(8); PG8_WAIT_L(0); PG8_BAR; __builtin_amdgcn_s_setprio(1); PG8_MMA_NP(1, 0, At, B0); PG8_MMA_NP(1, 1, At, B1); __builtin_amdgcn_s_setprio(0); PG8_BAR; PG8_SCHED;
;             PG8_LDB(B0, 1, 0); PG8_LDB(B1, 1, 1); PG8_SCHED; PG8_LDA(At, 1, 0); PG8_STAGE(PG8_SA(0, 1), a2 + hstep, voffA);
;             PG8_WAIT_V(8); PG8_WAIT_L(0); PG8_BAR; __builtin_amdgcn_s_setprio(1); PG8_MMA_NP(0, 0, At, B0); PG8_MMA_NP(0, 1, At, B1); __builtin_amdgcn_s_setprio(0); PG8_BAR; PG8_SCHED;
;             PG8_LDA(At, 1, 1); PG8_STAGE(PG8_SB(1, 0), b3, voffB); PG8_STAGE(PG8_SB(1, 1), b3 + hstep, voffB); PG8_STAGE(PG8_SA(1, 0), a3, voffA);
	s_waitcnt lgkmcnt(0)
	v_mfma_f32_16x16x32_bf16 v[62:65], v[140:143], v[206:209], v[62:65]
	v_mfma_f32_16x16x32_bf16 v[58:61], v[154:157], v[206:209], v[58:61]
	v_mfma_f32_16x16x32_bf16 v[46:49], v[140:143], v[214:217], v[46:49]
	v_mfma_f32_16x16x32_bf16 v[42:45], v[154:157], v[214:217], v[42:45]
	v_mfma_f32_16x16x32_bf16 v[30:33], v[140:143], v[222:225], v[30:33]
	v_mfma_f32_16x16x32_bf16 v[26:29], v[154:157], v[222:225], v[26:29]
	v_mfma_f32_16x16x32_bf16 v[14:17], v[140:143], v[230:233], v[14:17]
	v_mfma_f32_16x16x32_bf16 v[10:13], v[154:157], v[230:233], v[10:13]
	v_mfma_f32_16x16x32_bf16 v[54:57], v[178:181], v[206:209], v[54:57]
	v_mfma_f32_16x16x32_bf16 v[50:53], v[186:189], v[206:209], v[50:53]
	v_mfma_f32_16x16x32_bf16 v[38:41], v[178:181], v[214:217], v[38:41]
	v_mfma_f32_16x16x32_bf16 v[34:37], v[186:189], v[214:217], v[34:37]
	v_mfma_f32_16x16x32_bf16 v[22:25], v[178:181], v[222:225], v[22:25]
	v_mfma_f32_16x16x32_bf16 v[18:21], v[186:189], v[222:225], v[18:21]
	v_mfma_f32_16x16x32_bf16 v[6:9], v[178:181], v[230:233], v[6:9]
	v_mfma_f32_16x16x32_bf16 v[2:5], v[186:189], v[230:233], v[2:5]
	v_mfma_f32_16x16x32_bf16 v[62:65], v[150:153], v[210:213], v[62:65]
	v_mfma_f32_16x16x32_bf16 v[58:61], v[158:161], v[210:213], v[58:61]
	v_mfma_f32_16x16x32_bf16 v[46:49], v[150:153], v[218:221], v[46:49]
	v_mfma_f32_16x16x32_bf16 v[42:45], v[158:161], v[218:221], v[42:45]
	v_mfma_f32_16x16x32_bf16 v[30:33], v[150:153], v[226:229], v[30:33]
	v_mfma_f32_16x16x32_bf16 v[26:29], v[158:161], v[226:229], v[26:29]
	v_mfma_f32_16x16x32_bf16 v[14:17], v[150:153], v[234:237], v[14:17]
	v_mfma_f32_16x16x32_bf16 v[10:13], v[158:161], v[234:237], v[10:13]
	v_mfma_f32_16x16x32_bf16 v[54:57], v[182:185], v[210:213], v[54:57]
	v_mfma_f32_16x16x32_bf16 v[50:53], v[202:205], v[210:213], v[50:53]
	v_mfma_f32_16x16x32_bf16 v[38:41], v[182:185], v[218:221], v[38:41]
	v_mfma_f32_16x16x32_bf16 v[34:37], v[202:205], v[218:221], v[34:37]
	v_mfma_f32_16x16x32_bf16 v[22:25], v[182:185], v[226:229], v[22:25]
	v_mfma_f32_16x16x32_bf16 v[18:21], v[202:205], v[226:229], v[18:21]
	v_mfma_f32_16x16x32_bf16 v[6:9], v[182:185], v[234:237], v[6:9]
	v_mfma_f32_16x16x32_bf16 v[2:5], v[202:205], v[234:237], v[2:5]
	s_barrier
	s_add_i32 s22, 0, 0x18000
	s_add_i32 s23, 0, 0x1c000
	v_add_u32_e32 v158, s22, v147
	v_add_u32_e32 v202, s23, v147
	ds_read_b128 v[140:143], v158
	ds_read_b128 v[150:153], v158 offset:1024
	ds_read_b128 v[154:157], v158 offset:2048
	ds_read_b128 v[158:161], v158 offset:3072
	ds_read_b128 v[178:181], v202
	ds_read_b128 v[182:185], v202 offset:1024
	ds_read_b128 v[186:189], v202 offset:2048
	ds_read_b128 v[202:205], v202 offset:3072
	s_add_u32 s12, s50, 0xb0000
	s_addc_u32 s13, s51, 0
	s_mov_b32 m0, s54
	v_lshl_add_u64 v[240:241], s[12:13], 0, v[134:135]
	ds_read_b128 v[206:209], v149 offset:32768
	ds_read_b128 v[210:213], v149 offset:33792
	ds_read_b128 v[214:217], v149 offset:34816
	ds_read_b128 v[218:221], v149 offset:35840
	ds_read_b128 v[222:225], v149 offset:36864
	ds_read_b128 v[226:229], v149 offset:37888
	ds_read_b128 v[230:233], v149 offset:38912
	ds_read_b128 v[234:237], v149 offset:39936
	global_load_lds_dwordx4 v[240:241], off
	v_lshl_add_u64 v[240:241], s[12:13], 0, v[132:133]
	s_mov_b32 m0, s55
	s_nop 0
	global_load_lds_dwordx4 v[240:241], off
	s_waitcnt vmcnt(8)
	s_waitcnt lgkmcnt(0)
	s_barrier
	s_waitcnt lgkmcnt(0)
	v_mfma_f32_16x16x32_bf16 v[126:129], v[140:143], v[206:209], v[126:129]
	v_mfma_f32_16x16x32_bf16 v[122:125], v[154:157], v[206:209], v[122:125]
	v_mfma_f32_16x16x32_bf16 v[110:113], v[140:143], v[214:217], v[110:113]
	v_mfma_f32_16x16x32_bf16 v[106:109], v[154:157], v[214:217], v[106:109]
	v_mfma_f32_16x16x32_bf16 v[94:97], v[140:143], v[222:225], v[94:97]
	v_mfma_f32_16x16x32_bf16 v[90:93], v[154:157], v[222:225], v[90:93]
	v_mfma_f32_16x16x32_bf16 v[78:81], v[140:143], v[230:233], v[78:81]
	v_mfma_f32_16x16x32_bf16 v[74:77], v[154:157], v[230:233], v[74:77]
	v_mfma_f32_16x16x32_bf16 v[118:121], v[178:181], v[206:209], v[118:121]
	v_mfma_f32_16x16x32_bf16 v[114:117], v[186:189], v[206:209], v[114:117]
	v_mfma_f32_16x16x32_bf16 v[102:105], v[178:181], v[214:217], v[102:105]
	v_mfma_f32_16x16x32_bf16 v[98:101], v[186:189], v[214:217], v[98:101]
	v_mfma_f32_16x16x32_bf16 v[86:89], v[178:181], v[222:225], v[86:89]
	v_mfma_f32_16x16x32_bf16 v[82:85], v[186:189], v[222:225], v[82:85]
	v_mfma_f32_16x16x32_bf16 v[70:73], v[178:181], v[230:233], v[70:73]
	v_mfma_f32_16x16x32_bf16 v[66:69], v[186:189], v[230:233], v[66:69]
	v_mfma_f32_16x16x32_bf16 v[126:129], v[150:153], v[210:213], v[126:129]
	v_mfma_f32_16x16x32_bf16 v[122:125], v[158:161], v[210:213], v[122:125]
	v_mfma_f32_16x16x32_bf16 v[110:113], v[150:153], v[218:221], v[110:113]
	v_mfma_f32_16x16x32_bf16 v[106:109], v[158:161], v[218:221], v[106:109]
	v_mfma_f32_16x16x32_bf16 v[94:97], v[150:153], v[226:229], v[94:97]
	v_mfma_f32_16x16x32_bf16 v[90:93], v[158:161], v[226:229], v[90:93]
	v_mfma_f32_16x16x32_bf16 v[78:81], v[150:153], v[234:237], v[78:81]
	v_mfma_f32_16x16x32_bf16 v[74:77], v[158:161], v[234:237], v[74:77]
	v_mfma_f32_16x16x32_bf16 v[118:121], v[182:185], v[210:213], v[118:121]
	v_mfma_f32_16x16x32_bf16 v[114:117], v[202:205], v[210:213], v[114:117]
	v_mfma_f32_16x16x32_bf16 v[102:105], v[182:185], v[218:221], v[102:105]
	v_mfma_f32_16x16x32_bf16 v[98:101], v[202:205], v[218:221], v[98:101]
	v_mfma_f32_16x16x32_bf16 v[86:89], v[182:185], v[226:229], v[86:89]
	v_mfma_f32_16x16x32_bf16 v[82:85], v[202:205], v[226:229], v[82:85]
	v_mfma_f32_16x16x32_bf16 v[70:73], v[182:185], v[234:237], v[70:73]
	v_mfma_f32_16x16x32_bf16 v[66:69], v[202:205], v[234:237], v[66:69]
	s_barrier
; #define PG8_STAGE(bufoff, gbase, voff) do { _Pragma("unroll") for (int _i = 0; _i < 2; ++_i) \
;         __builtin_amdgcn_global_load_lds((const unsigned*)((const char*)(gbase) + (voff)[_i]), (PG8_LAS unsigned*)(lds + (bufoff) + ldsw + _i * 8192), 16, 0, 0); } while (0)
; #define PG8_LDA(dst, b, h) do { _Pragma("unroll") for (int m = 0; m < 4; ++m) _Pragma("unroll") for (int k = 0; k < 2; ++k) dst[m][k] = *(const PG8_LAS bf16x8*)(lds + PG8_SA(b, h) + aoff + m * 2048 + k * 1024); } while (0)
; #define PG8_MMA_NP(ai, bj, At, Bt) do { _Pragma("unroll") for (int m = 0; m < 4; ++m) _Pragma("unroll") for (int n = 0; n < 2; ++n) _Pragma("unroll") for (int k = 0; k < 2; ++k) \
;         acc[ai][bj][m][n] = __builtin_amdgcn_mfma_f32_16x16x32_bf16(Bt[n][k], At[m][k], acc[ai][bj][m][n], 0, 0, 0); } while (0)
; #define PG8_WAIT_V(n) asm volatile("s_waitcnt vmcnt(" #n ")" ::: "memory")
; #define PG8_WAIT_L(n) asm volatile("s_waitcnt lgkmcnt(" #n ")" ::: "memory")
; template <class Epi, class Sched, bool ALIGN_EPI = false, bool SP2 = false>
; __device__ __forceinline__ void gemm_phase(PG8_LAS unsigned char* lds, const Gemm g, const Sched& S, const Epi& E) {
;     ...
;             PG8_LDA(At, 1, 1); PG8_STAGE(PG8_SB(1, 0), b3, voffB); PG8_STAGE(PG8_SB(1, 1), b3 + hstep, voffB); PG8_STAGE(PG8_SA(1, 0), a3, voffA);
;             PG8_WAIT_V(8); PG8_WAIT_L(0); PG8_BAR; __builtin_amdgcn_s_setprio(1); PG8_MMA_NP(1, 0, At, B0); PG8_MMA_NP(1, 1, At, B1); __builtin_amdgcn_s_setprio(0); PG8_BAR; PG8_SCHED;
;     DI void operator()(const f32x4 (&acc)[2][2][4][2], const pg8::Unit& u, int wr, int wc, int fr, int fq) const {
;         const int row0 = u.pm * 256 + wr * 64 + fr, col0 = u.pn * 256 + wc * 32 + 8 * fq;
; #pragma unroll
;         for (int ai = 0; ai < 2; ++ai)
; #pragma unroll
;             for (int m = 0; m < 4; ++m) {
;                 const int row = row0 + ai * 128 + m * 16; float ss = 0.f;
; #pragma unroll
;                 for (int bj = 0; bj < 2; ++bj) {
;                     const size_t off = (size_t)row * DM + col0 + bj * 128;
;                     f32x4 b0, b1;
;                     if (base32) { b0 = *(const f32x4*)(base32 + off); b1 = *(const f32x4*)(base32 + off + 4); }
;                     else { const u32x4 bb = *(const u32x4*)(XB + off); b0 = (f32x4){bflo(bb.x), bfhi(bb.x), bflo(bb.y), bfhi(bb.y)}; b1 = (f32x4){bflo(bb.z), bfhi(bb.z), bflo(bb.w), bfhi(bb.w)}; }
	s_add_i32 s12, s22, s31
	v_lshl_add_u64 v[144:145], v[144:145], 0, s[20:21]
	s_mov_b32 m0, s12
	ds_read_b128 v[206:209], v149 offset:49152
	ds_read_b128 v[210:213], v149 offset:50176
	ds_read_b128 v[214:217], v149 offset:51200
	ds_read_b128 v[218:221], v149 offset:52224
	ds_read_b128 v[222:225], v149 offset:53248
	ds_read_b128 v[226:229], v149 offset:54272
	ds_read_b128 v[230:233], v149 offset:55296
	ds_read_b128 v[234:237], v149 offset:56320
	global_load_lds_dwordx4 v[144:145], off
	s_add_i32 m0, s12, 0x2000
	s_add_u32 s12, s14, 0xb0080
	v_lshl_add_u64 v[144:145], v[162:163], 0, s[20:21]
	s_addc_u32 s13, s15, 0
	s_add_i32 s14, s23, s31
	global_load_lds_dwordx4 v[144:145], off
	v_lshl_add_u64 v[144:145], s[12:13], 0, v[0:1]
	s_mov_b32 m0, s14
	s_nop 0
	global_load_lds_dwordx4 v[144:145], off
	v_lshl_add_u64 v[144:145], s[12:13], 0, v[130:131]
	s_add_i32 m0, s14, 0x2000
	s_nop 0
	global_load_lds_dwordx4 v[144:145], off
	v_lshl_add_u64 v[144:145], v[190:191], 0, s[20:21]
	s_mov_b32 m0, s57
	s_nop 0
	global_load_lds_dwordx4 v[144:145], off
	v_lshl_add_u64 v[144:145], v[238:239], 0, s[20:21]
	s_mov_b32 m0, s58
	s_nop 0
	global_load_lds_dwordx4 v[144:145], off
	s_waitcnt vmcnt(8)
	s_waitcnt lgkmcnt(0)
	s_barrier
	s_waitcnt lgkmcnt(0)
	v_mfma_f32_16x16x32_bf16 v[62:65], v[140:143], v[206:209], v[62:65]
	v_mfma_f32_16x16x32_bf16 v[58:61], v[154:157], v[206:209], v[58:61]
	v_mfma_f32_16x16x32_bf16 v[46:49], v[140:143], v[214:217], v[46:49]
	v_mfma_f32_16x16x32_bf16 v[42:45], v[154:157], v[214:217], v[42:45]
	v_mfma_f32_16x16x32_bf16 v[30:33], v[140:143], v[222:225], v[30:33]
	v_mfma_f32_16x16x32_bf16 v[26:29], v[154:157], v[222:225], v[26:29]
	v_mfma_f32_16x16x32_bf16 v[14:17], v[140:143], v[230:233], v[14:17]
	v_mfma_f32_16x16x32_bf16 v[10:13], v[154:157], v[230:233], v[10:13]
	v_mfma_f32_16x16x32_bf16 v[54:57], v[178:181], v[206:209], v[54:57]
	v_mfma_f32_16x16x32_bf16 v[50:53], v[186:189], v[206:209], v[50:53]
	v_mfma_f32_16x16x32_bf16 v[38:41], v[178:181], v[214:217], v[38:41]
	v_mfma_f32_16x16x32_bf16 v[34:37], v[186:189], v[214:217], v[34:37]
	v_mfma_f32_16x16x32_bf16 v[22:25], v[178:181], v[222:225], v[22:25]
	v_mfma_f32_16x16x32_bf16 v[18:21], v[186:189], v[222:225], v[18:21]
	v_mfma_f32_16x16x32_bf16 v[6:9], v[178:181], v[230:233], v[6:9]
	v_mfma_f32_16x16x32_bf16 v[2:5], v[186:189], v[230:233], v[2:5]
	v_mfma_f32_16x16x32_bf16 v[62:65], v[150:153], v[210:213], v[62:65]
	v_mfma_f32_16x16x32_bf16 v[58:61], v[158:161], v[210:213], v[58:61]
	v_mfma_f32_16x16x32_bf16 v[46:49], v[150:153], v[218:221], v[46:49]
	v_mfma_f32_16x16x32_bf16 v[42:45], v[158:161], v[218:221], v[42:45]
	v_mfma_f32_16x16x32_bf16 v[30:33], v[150:153], v[226:229], v[30:33]
	v_mfma_f32_16x16x32_bf16 v[26:29], v[158:161], v[226:229], v[26:29]
	v_mfma_f32_16x16x32_bf16 v[14:17], v[150:153], v[234:237], v[14:17]
	v_mfma_f32_16x16x32_bf16 v[10:13], v[158:161], v[234:237], v[10:13]
	v_mfma_f32_16x16x32_bf16 v[54:57], v[182:185], v[210:213], v[54:57]
	v_mfma_f32_16x16x32_bf16 v[50:53], v[202:205], v[210:213], v[50:53]
	v_mfma_f32_16x16x32_bf16 v[38:41], v[182:185], v[218:221], v[38:41]
	v_mfma_f32_16x16x32_bf16 v[34:37], v[202:205], v[218:221], v[34:37]
	v_mfma_f32_16x16x32_bf16 v[22:25], v[182:185], v[226:229], v[22:25]
	v_mfma_f32_16x16x32_bf16 v[18:21], v[202:205], v[226:229], v[18:21]
	v_mfma_f32_16x16x32_bf16 v[6:9], v[182:185], v[234:237], v[6:9]
	v_mfma_f32_16x16x32_bf16 v[2:5], v[202:205], v[234:237], v[2:5]
	s_barrier
	s_add_i32 s64, s64, 2
	s_add_u32 s62, s62, 0x100
	s_addc_u32 s63, s63, 0
	s_cmp_gt_u32 s64, 41
	s_mov_b64 s[12:13], s[48:49]
	s_cbranch_scc0 .LBB0_1220
	v_lshl_add_u32 v160, s61, 8, v146
	v_ashrrev_i32_e32 v161, 31, v160
	v_lshl_or_b32 v162, s8, 8, v148
	v_ashrrev_i32_e32 v163, 31, v162
	v_lshlrev_b64 v[160:161], 10, v[160:161]
	v_lshl_add_u64 v[160:161], v[160:161], 0, v[162:163]
	v_lshl_add_u64 v[160:161], v[160:161], 1, s[86:87]
	global_load_dwordx4 v[178:181], v[160:161], off
	global_load_dwordx4 v[182:185], v[160:161], off offset:256
	s_mov_b64 vcc, 0x8000
	v_lshl_add_u64 v[162:163], v[160:161], 0, vcc
	global_load_dwordx4 v[186:189], v[162:163], off
	global_load_dwordx4 v[202:205], v[162:163], off offset:256
	s_mov_b64 vcc, 0x10000
	v_lshl_add_u64 v[162:163], v[160:161], 0, vcc
	global_load_dwordx4 v[206:209], v[162:163], off
	global_load_dwordx4 v[210:213], v[162:163], off offset:256
	s_mov_b64 vcc, 0x18000
	v_lshl_add_u64 v[162:163], v[160:161], 0, vcc
	global_load_dwordx4 v[214:217], v[162:163], off
	global_load_dwordx4 v[218:221], v[162:163], off offset:256
	s_mov_b64 vcc, 0x40000
	v_lshl_add_u64 v[162:163], v[160:161], 0, vcc
	global_load_dwordx4 v[222:225], v[162:163], off
	global_load_dwordx4 v[226:229], v[162:163], off offset:256
	s_mov_b64 vcc, 0x48000
	v_lshl_add_u64 v[162:163], v[160:161], 0, vcc
	global_load_dwordx4 v[230:233], v[162:163], off
	global_load_dwordx4 v[234:237], v[162:163], off offset:256
	s_and_b64 vcc, exec, s[44:45]
	s_cbranch_vccz .LBB0_1223
	s_barrier
